# speedup vs baseline: 1.0102x; 1.0102x over previous
; __device__ __forceinline__ void transpose_tile(const float* __restrict__ W, int K, int N, u16* __restrict__ WT, int k0,
;                                                int n0) {
;   float* ts = (float*)g_shm;
;   const int tid = tid_();
;   float4 v[8];
; #pragma unroll
;   for (int i = 0; i < 8; ++i) {
;     int idx = tid + i * NT, r = idx >> 6, c4 = idx & 63;
;     v[i] = (n0 + c4 * 4 < N) ? *(const float4*)(W + (size_t)(k0 + r) * N + n0 + c4 * 4) : float4{0.f, 0.f, 0.f, 0.f};
;   }
;   __syncthreads();
; #pragma unroll
;   for (int i = 0; i < 8; ++i) {
;     int idx = tid + i * NT, r = idx >> 6, c4 = idx & 63;
;     float* d = ts + r * 257 + c4 * 4;
;     d[0] = v[i].x; d[1] = v[i].y; d[2] = v[i].z; d[3] = v[i].w;
;   }
;   __syncthreads();
;   if (n0 + (tid >> 1) < N) {
;     int n = tid >> 1, kh = tid & 1;
;     u16* dst = WT + (size_t)(n0 + n) * K + k0 + kh * 32;
; #pragma unroll
;     for (int q = 0; q < 4; ++q) {
;       unsigned pk[4];
; #pragma unroll
;       for (int i = 0; i < 4; ++i)
;         pk[i] = pack2(ts[(kh * 32 + q * 8 + 2 * i) * 257 + n], ts[(kh * 32 + q * 8 + 2 * i + 1) * 257 + n]);
;       *(i32x4*)(dst + q * 8) = i32x4{(int)pk[0], (int)pk[1], (int)pk[2], (int)pk[3]};
;     }
;   }
; }
; __device__ void transpose_matrix(const float* W, int K, int N, u16* WT) {
;   int tk = K / 64, tn = (N + 255) / 256, total = tk * tn;
;   for (int t = blockIdx.x; t < total; t += gridDim.x) {
;     int kt = t % tk, nt_ = t / tk;
;     transpose_tile(W, K, N, WT, kt * 64, nt_ * 256);
;   }
; }
; __device__ void phase0(const Params& p) {
;     ...
;   transpose_matrix(p.w_in, DM, NIN, (u16*)(p.ws + OFF_W1T));
.LBB0_13:
	s_or_b64 exec, exec, s[10:11]
	v_lshrrev_b32_e32 v45, 6, v214
	v_and_b32_e32 v46, 63, v214
	v_lshrrev_b32_e32 v44, 1, v214
	v_and_b32_e32 v47, 1, v214
	v_lshlrev_b32_e32 v43, 2, v46
	v_mul_u32_u24_e32 v41, 0x410, v45
	v_lshl_add_u32 v41, v46, 4, v41
	v_mul_u32_u24_e32 v42, 0x8200, v47
	v_lshl_add_u32 v42, v44, 2, v42
	v_mov_b32_e32 v96, 0
	global_load_dwordx2 v[98:99], v96, s[50:51] offset:160
	s_waitcnt vmcnt(0)
	v_readfirstlane_b32 s28, v98
	v_readfirstlane_b32 s29, v99
	v_mov_b32_e32 v96, 0
	global_load_dwordx2 v[98:99], v96, s[50:51] offset:16
	s_mov_b32 s12, 0x5040
	v_mul_lo_u32 v32, v45, s12
	v_add_lshl_u32 v32, v32, v43, 2
	s_mov_b32 s13, 0xa0800
	v_add_u32_e32 v33, s13, v32
	v_add_u32_e32 v34, s13, v33
	v_add_u32_e32 v35, s13, v34
	v_add_u32_e32 v36, s13, v35
	v_add_u32_e32 v37, s13, v36
	v_add_u32_e32 v38, s13, v37
	v_add_u32_e32 v39, s13, v38
	v_mul_u32_u24_e32 v40, 0x1000, v44
	v_lshl_add_u32 v40, v47, 6, v40
	s_waitcnt vmcnt(0)
	v_readfirstlane_b32 s8, v98
	v_readfirstlane_b32 s9, v99
	s_add_u32 s10, s28, 0x0
	s_addc_u32 s11, s29, 0
	s_mov_b32 s3, s2
	s_cmp_lt_u32 s3, 2592
	s_cbranch_scc0 .Lt20a_end
	s_and_b32 s14, s3, 31
	s_lshr_b32 s15, s3, 5
	s_lshl_b32 s14, s14, 6
	s_lshl_b32 s24, s15, 8
	s_mul_i32 s16, s14, s12
	s_add_u32 s16, s16, s24
	s_lshl_b32 s16, s16, 2
	s_add_u32 s18, s8, s16
	s_addc_u32 s19, s9, 0
	s_mul_i32 s16, s24, 0x800
	s_add_u32 s16, s16, s14
	s_lshl_b32 s16, s16, 1
	s_add_u32 s20, s10, s16
	s_addc_u32 s21, s11, 0
	v_add_u32_e32 v97, s24, v43
	v_cmp_gt_u32_e32 vcc, s12, v97
	s_and_saveexec_b64 s[22:23], vcc
	global_load_dwordx4 v[0:3], v32, s[18:19]
	global_load_dwordx4 v[4:7], v33, s[18:19]
	global_load_dwordx4 v[8:11], v34, s[18:19]
	global_load_dwordx4 v[12:15], v35, s[18:19]
	global_load_dwordx4 v[16:19], v36, s[18:19]
	global_load_dwordx4 v[20:23], v37, s[18:19]
	global_load_dwordx4 v[24:27], v38, s[18:19]
	global_load_dwordx4 v[28:31], v39, s[18:19]
	s_or_b64 exec, exec, s[22:23]
	s_add_u32 s17, s3, s33
	s_cmp_lt_u32 s17, 2592
	s_cbranch_scc0 .Lt20a_loop
	s_and_b32 s14, s17, 31
	s_lshr_b32 s15, s17, 5
	s_lshl_b32 s14, s14, 6
	s_lshl_b32 s25, s15, 8
	s_mul_i32 s16, s14, s12
	s_add_u32 s16, s16, s25
	s_lshl_b32 s16, s16, 2
	s_add_u32 s18, s8, s16
	s_addc_u32 s19, s9, 0
	s_mul_i32 s16, s25, 0x800
	s_add_u32 s16, s16, s14
	s_lshl_b32 s16, s16, 1
	s_add_u32 s26, s10, s16
	s_addc_u32 s27, s11, 0
	v_add_u32_e32 v97, s25, v43
	v_cmp_gt_u32_e32 vcc, s12, v97
	s_and_saveexec_b64 s[22:23], vcc
	global_load_dwordx4 v[100:103], v32, s[18:19]
	global_load_dwordx4 v[104:107], v33, s[18:19]
	global_load_dwordx4 v[108:111], v34, s[18:19]
	global_load_dwordx4 v[112:115], v35, s[18:19]
	global_load_dwordx4 v[116:119], v36, s[18:19]
	global_load_dwordx4 v[120:123], v37, s[18:19]
	global_load_dwordx4 v[124:127], v38, s[18:19]
	global_load_dwordx4 v[128:131], v39, s[18:19]
	s_or_b64 exec, exec, s[22:23]
.Lt20a_loop:
	s_add_u32 s17, s3, s33
	s_cmp_lt_u32 s17, 2592
	s_cbranch_scc1 .Lt20a_Aw8
	s_waitcnt vmcnt(0)
	s_branch .Lt20a_Ago
.Lt20a_Aw8:
	s_waitcnt vmcnt(8)
.Lt20a_Ago:
	s_barrier
	ds_write_b128 v41, v[0:3]
	ds_write_b128 v41, v[4:7] offset:8320
	ds_write_b128 v41, v[8:11] offset:16640
	ds_write_b128 v41, v[12:15] offset:24960
	ds_write_b128 v41, v[16:19] offset:33280
	ds_write_b128 v41, v[20:23] offset:41600
	ds_write_b128 v41, v[24:27] offset:49920
	ds_write_b128 v41, v[28:31] offset:58240
	s_waitcnt lgkmcnt(0)
	s_barrier
	v_add_u32_e32 v97, s24, v44
	v_cmp_gt_u32_e32 vcc, s12, v97
	s_and_saveexec_b64 s[22:23], vcc
	ds_read_b32 v48, v42
	ds_read_b32 v49, v42 offset:1040
	ds_read_b32 v50, v42 offset:2080
	ds_read_b32 v51, v42 offset:3120
	ds_read_b32 v52, v42 offset:4160
	ds_read_b32 v53, v42 offset:5200
	ds_read_b32 v54, v42 offset:6240
	ds_read_b32 v55, v42 offset:7280
	ds_read_b32 v56, v42 offset:8320
	ds_read_b32 v57, v42 offset:9360
	ds_read_b32 v58, v42 offset:10400
	ds_read_b32 v59, v42 offset:11440
	ds_read_b32 v60, v42 offset:12480
	ds_read_b32 v61, v42 offset:13520
	ds_read_b32 v62, v42 offset:14560
	ds_read_b32 v63, v42 offset:15600
	s_waitcnt lgkmcnt(8)
	v_cvt_pk_bf16_f32 v80, v48, v49
	v_cvt_pk_bf16_f32 v81, v50, v51
	v_cvt_pk_bf16_f32 v82, v52, v53
	v_cvt_pk_bf16_f32 v83, v54, v55
	global_store_dwordx4 v40, v[80:83], s[20:21]
	ds_read_b32 v64, v42 offset:16640
	ds_read_b32 v65, v42 offset:17680
	ds_read_b32 v66, v42 offset:18720
	ds_read_b32 v67, v42 offset:19760
	ds_read_b32 v68, v42 offset:20800
	ds_read_b32 v69, v42 offset:21840
	ds_read_b32 v70, v42 offset:22880
	ds_read_b32 v71, v42 offset:23920
	s_waitcnt lgkmcnt(8)
	v_cvt_pk_bf16_f32 v84, v56, v57
	v_cvt_pk_bf16_f32 v85, v58, v59
	v_cvt_pk_bf16_f32 v86, v60, v61
	v_cvt_pk_bf16_f32 v87, v62, v63
	global_store_dwordx4 v40, v[84:87], s[20:21] offset:16
	ds_read_b32 v72, v42 offset:24960
	ds_read_b32 v73, v42 offset:26000
	ds_read_b32 v74, v42 offset:27040
	ds_read_b32 v75, v42 offset:28080
	ds_read_b32 v76, v42 offset:29120
	ds_read_b32 v77, v42 offset:30160
	ds_read_b32 v78, v42 offset:31200
	ds_read_b32 v79, v42 offset:32240
	s_waitcnt lgkmcnt(8)
	v_cvt_pk_bf16_f32 v88, v64, v65
	v_cvt_pk_bf16_f32 v89, v66, v67
	v_cvt_pk_bf16_f32 v90, v68, v69
	v_cvt_pk_bf16_f32 v91, v70, v71
	global_store_dwordx4 v40, v[88:91], s[20:21] offset:32
	s_waitcnt lgkmcnt(0)
	v_cvt_pk_bf16_f32 v92, v72, v73
	v_cvt_pk_bf16_f32 v93, v74, v75
	v_cvt_pk_bf16_f32 v94, v76, v77
	v_cvt_pk_bf16_f32 v95, v78, v79
	global_store_dwordx4 v40, v[92:95], s[20:21] offset:48
	s_or_b64 exec, exec, s[22:23]
	s_add_u32 s17, s17, s33
	s_cmp_lt_u32 s17, 2592
	s_cbranch_scc0 .Lt20a_Anl
	s_and_b32 s14, s17, 31
	s_lshr_b32 s15, s17, 5
	s_lshl_b32 s14, s14, 6
	s_lshl_b32 s24, s15, 8
	s_mul_i32 s16, s14, s12
	s_add_u32 s16, s16, s24
	s_lshl_b32 s16, s16, 2
	s_add_u32 s18, s8, s16
	s_addc_u32 s19, s9, 0
	s_mul_i32 s16, s24, 0x800
	s_add_u32 s16, s16, s14
	s_lshl_b32 s16, s16, 1
	s_add_u32 s20, s10, s16
	s_addc_u32 s21, s11, 0
	v_add_u32_e32 v97, s24, v43
	v_cmp_gt_u32_e32 vcc, s12, v97
	s_and_saveexec_b64 s[22:23], vcc
	global_load_dwordx4 v[0:3], v32, s[18:19]
	global_load_dwordx4 v[4:7], v33, s[18:19]
	global_load_dwordx4 v[8:11], v34, s[18:19]
	global_load_dwordx4 v[12:15], v35, s[18:19]
	global_load_dwordx4 v[16:19], v36, s[18:19]
	global_load_dwordx4 v[20:23], v37, s[18:19]
	global_load_dwordx4 v[24:27], v38, s[18:19]
	global_load_dwordx4 v[28:31], v39, s[18:19]
	s_or_b64 exec, exec, s[22:23]
.Lt20a_Anl:
	s_add_u32 s3, s3, s33
	s_cmp_lt_u32 s3, 2592
	s_cbranch_scc0 .Lt20a_end
	s_add_u32 s17, s3, s33
	s_cmp_lt_u32 s17, 2592
	s_cbranch_scc1 .Lt20a_Bw8
	s_waitcnt vmcnt(0)
	s_branch .Lt20a_Bgo

; __device__ __forceinline__ void transpose_tile(const float* __restrict__ W, int K, int N, u16* __restrict__ WT, int k0,
;                                                int n0) {
;   float* ts = (float*)g_shm;
;   const int tid = tid_();
;   float4 v[8];
; #pragma unroll
;   for (int i = 0; i < 8; ++i) {
;     int idx = tid + i * NT, r = idx >> 6, c4 = idx & 63;
;     v[i] = (n0 + c4 * 4 < N) ? *(const float4*)(W + (size_t)(k0 + r) * N + n0 + c4 * 4) : float4{0.f, 0.f, 0.f, 0.f};
;   }
;   __syncthreads();
; #pragma unroll
;   for (int i = 0; i < 8; ++i) {
;     int idx = tid + i * NT, r = idx >> 6, c4 = idx & 63;
;     float* d = ts + r * 257 + c4 * 4;
;     d[0] = v[i].x; d[1] = v[i].y; d[2] = v[i].z; d[3] = v[i].w;
;   }
;   __syncthreads();
;   if (n0 + (tid >> 1) < N) {
;     int n = tid >> 1, kh = tid & 1;
;     u16* dst = WT + (size_t)(n0 + n) * K + k0 + kh * 32;
; #pragma unroll
;     for (int q = 0; q < 4; ++q) {
;       unsigned pk[4];
; #pragma unroll
;       for (int i = 0; i < 4; ++i)
;         pk[i] = pack2(ts[(kh * 32 + q * 8 + 2 * i) * 257 + n], ts[(kh * 32 + q * 8 + 2 * i + 1) * 257 + n]);
;       *(i32x4*)(dst + q * 8) = i32x4{(int)pk[0], (int)pk[1], (int)pk[2], (int)pk[3]};
;     }
;   }
; }
; __device__ void transpose_matrix(const float* W, int K, int N, u16* WT) {
;   int tk = K / 64, tn = (N + 255) / 256, total = tk * tn;
;   for (int t = blockIdx.x; t < total; t += gridDim.x) {
;     int kt = t % tk, nt_ = t / tk;
;     transpose_tile(W, K, N, WT, kt * 64, nt_ * 256);
;   }
; }
; __device__ void phase0(const Params& p) {
;     ...
;   transpose_matrix(p.w_sb_proj, 2048, 2048, (u16*)(p.ws + OFF_WSB));
.Lt20a_Bgo:
	s_barrier
	ds_write_b128 v41, v[100:103]
	ds_write_b128 v41, v[104:107] offset:8320
	ds_write_b128 v41, v[108:111] offset:16640
	ds_write_b128 v41, v[112:115] offset:24960
	ds_write_b128 v41, v[116:119] offset:33280
	ds_write_b128 v41, v[120:123] offset:41600
	ds_write_b128 v41, v[124:127] offset:49920
	ds_write_b128 v41, v[128:131] offset:58240
	s_waitcnt lgkmcnt(0)
	s_barrier
	v_add_u32_e32 v97, s25, v44
	v_cmp_gt_u32_e32 vcc, s12, v97
	s_and_saveexec_b64 s[22:23], vcc
	ds_read_b32 v48, v42
	ds_read_b32 v49, v42 offset:1040
	ds_read_b32 v50, v42 offset:2080
	ds_read_b32 v51, v42 offset:3120
	ds_read_b32 v52, v42 offset:4160
	ds_read_b32 v53, v42 offset:5200
	ds_read_b32 v54, v42 offset:6240
	ds_read_b32 v55, v42 offset:7280
	ds_read_b32 v56, v42 offset:8320
	ds_read_b32 v57, v42 offset:9360
	ds_read_b32 v58, v42 offset:10400
	ds_read_b32 v59, v42 offset:11440
	ds_read_b32 v60, v42 offset:12480
	ds_read_b32 v61, v42 offset:13520
	ds_read_b32 v62, v42 offset:14560
	ds_read_b32 v63, v42 offset:15600
	s_waitcnt lgkmcnt(8)
	v_cvt_pk_bf16_f32 v80, v48, v49
	v_cvt_pk_bf16_f32 v81, v50, v51
	v_cvt_pk_bf16_f32 v82, v52, v53
	v_cvt_pk_bf16_f32 v83, v54, v55
	global_store_dwordx4 v40, v[80:83], s[26:27]
	ds_read_b32 v64, v42 offset:16640
	ds_read_b32 v65, v42 offset:17680
	ds_read_b32 v66, v42 offset:18720
	ds_read_b32 v67, v42 offset:19760
	ds_read_b32 v68, v42 offset:20800
	ds_read_b32 v69, v42 offset:21840
	ds_read_b32 v70, v42 offset:22880
	ds_read_b32 v71, v42 offset:23920
	s_waitcnt lgkmcnt(8)
	v_cvt_pk_bf16_f32 v84, v56, v57
	v_cvt_pk_bf16_f32 v85, v58, v59
	v_cvt_pk_bf16_f32 v86, v60, v61
	v_cvt_pk_bf16_f32 v87, v62, v63
	global_store_dwordx4 v40, v[84:87], s[26:27] offset:16
	ds_read_b32 v72, v42 offset:24960
	ds_read_b32 v73, v42 offset:26000
	ds_read_b32 v74, v42 offset:27040
	ds_read_b32 v75, v42 offset:28080
	ds_read_b32 v76, v42 offset:29120
	ds_read_b32 v77, v42 offset:30160
	ds_read_b32 v78, v42 offset:31200
	ds_read_b32 v79, v42 offset:32240
	s_waitcnt lgkmcnt(8)
	v_cvt_pk_bf16_f32 v88, v64, v65
	v_cvt_pk_bf16_f32 v89, v66, v67
	v_cvt_pk_bf16_f32 v90, v68, v69
	v_cvt_pk_bf16_f32 v91, v70, v71
	global_store_dwordx4 v40, v[88:91], s[26:27] offset:32
	s_waitcnt lgkmcnt(0)
	v_cvt_pk_bf16_f32 v92, v72, v73
	v_cvt_pk_bf16_f32 v93, v74, v75
	v_cvt_pk_bf16_f32 v94, v76, v77
	v_cvt_pk_bf16_f32 v95, v78, v79
	global_store_dwordx4 v40, v[92:95], s[26:27] offset:48
	s_or_b64 exec, exec, s[22:23]
	s_add_u32 s17, s17, s33
	s_cmp_lt_u32 s17, 2592
	s_cbranch_scc0 .Lt20a_Bnl
	s_and_b32 s14, s17, 31
	s_lshr_b32 s15, s17, 5
	s_lshl_b32 s14, s14, 6
	s_lshl_b32 s25, s15, 8
	s_mul_i32 s16, s14, s12
	s_add_u32 s16, s16, s25
	s_lshl_b32 s16, s16, 2
	s_add_u32 s18, s8, s16
	s_addc_u32 s19, s9, 0
	s_mul_i32 s16, s25, 0x800
	s_add_u32 s16, s16, s14
	s_lshl_b32 s16, s16, 1
	s_add_u32 s26, s10, s16
	s_addc_u32 s27, s11, 0
	v_add_u32_e32 v97, s25, v43
	v_cmp_gt_u32_e32 vcc, s12, v97
	s_and_saveexec_b64 s[22:23], vcc
	global_load_dwordx4 v[100:103], v32, s[18:19]
	global_load_dwordx4 v[104:107], v33, s[18:19]
	global_load_dwordx4 v[108:111], v34, s[18:19]
	global_load_dwordx4 v[112:115], v35, s[18:19]
	global_load_dwordx4 v[116:119], v36, s[18:19]
	global_load_dwordx4 v[120:123], v37, s[18:19]
	global_load_dwordx4 v[124:127], v38, s[18:19]
	global_load_dwordx4 v[128:131], v39, s[18:19]
	s_or_b64 exec, exec, s[22:23]
.Lt20a_Bnl:
	s_add_u32 s3, s3, s33
	s_cmp_lt_u32 s3, 2592
	s_cbranch_scc1 .Lt20a_loop
.Lt20a_end:
	v_mov_b32_e32 v96, 0
	global_load_dwordx2 v[98:99], v96, s[50:51] offset:72
	s_mov_b32 s12, 0x800
	v_mul_lo_u32 v32, v45, s12
	v_add_lshl_u32 v32, v32, v43, 2
	s_mov_b32 s13, 0x10000
	v_add_u32_e32 v33, s13, v32
	v_add_u32_e32 v34, s13, v33
	v_add_u32_e32 v35, s13, v34
	v_add_u32_e32 v36, s13, v35
	v_add_u32_e32 v37, s13, v36
	v_add_u32_e32 v38, s13, v37
	v_add_u32_e32 v39, s13, v38
	v_mul_u32_u24_e32 v40, 0x1000, v44
	v_lshl_add_u32 v40, v47, 6, v40
	s_waitcnt vmcnt(0)
	v_readfirstlane_b32 s8, v98
	v_readfirstlane_b32 s9, v99
	s_add_u32 s10, s28, 0x5100000
	s_addc_u32 s11, s29, 0
	s_mov_b32 s3, s2
	s_cmp_lt_u32 s3, 256
	s_cbranch_scc0 .Lt20b_end
	s_and_b32 s14, s3, 31
	s_lshr_b32 s15, s3, 5
	s_lshl_b32 s14, s14, 6
	s_lshl_b32 s24, s15, 8
	s_mul_i32 s16, s14, s12
	s_add_u32 s16, s16, s24
	s_lshl_b32 s16, s16, 2
	s_add_u32 s18, s8, s16
	s_addc_u32 s19, s9, 0
	s_mul_i32 s16, s24, 0x800
	s_add_u32 s16, s16, s14
	s_lshl_b32 s16, s16, 1
	s_add_u32 s20, s10, s16
	s_addc_u32 s21, s11, 0
	global_load_dwordx4 v[0:3], v32, s[18:19]
	global_load_dwordx4 v[4:7], v33, s[18:19]
	global_load_dwordx4 v[8:11], v34, s[18:19]
	global_load_dwordx4 v[12:15], v35, s[18:19]
	global_load_dwordx4 v[16:19], v36, s[18:19]
	global_load_dwordx4 v[20:23], v37, s[18:19]
	global_load_dwordx4 v[24:27], v38, s[18:19]
	global_load_dwordx4 v[28:31], v39, s[18:19]
	s_add_u32 s17, s3, s33
	s_cmp_lt_u32 s17, 256
	s_cbranch_scc0 .Lt20b_loop
	s_and_b32 s14, s17, 31
	s_lshr_b32 s15, s17, 5
	s_lshl_b32 s14, s14, 6
	s_lshl_b32 s25, s15, 8
	s_mul_i32 s16, s14, s12
	s_add_u32 s16, s16, s25
	s_lshl_b32 s16, s16, 2
	s_add_u32 s18, s8, s16
	s_addc_u32 s19, s9, 0
	s_mul_i32 s16, s25, 0x800
	s_add_u32 s16, s16, s14
	s_lshl_b32 s16, s16, 1
	s_add_u32 s26, s10, s16
	s_addc_u32 s27, s11, 0
	global_load_dwordx4 v[100:103], v32, s[18:19]
	global_load_dwordx4 v[104:107], v33, s[18:19]
	global_load_dwordx4 v[108:111], v34, s[18:19]
	global_load_dwordx4 v[112:115], v35, s[18:19]
	global_load_dwordx4 v[116:119], v36, s[18:19]
	global_load_dwordx4 v[120:123], v37, s[18:19]
	global_load_dwordx4 v[124:127], v38, s[18:19]
	global_load_dwordx4 v[128:131], v39, s[18:19]
.Lt20b_loop:
	s_add_u32 s17, s3, s33
	s_cmp_lt_u32 s17, 256
	s_cbranch_scc1 .Lt20b_Aw8
	s_waitcnt vmcnt(0)
	s_branch .Lt20b_Ago

; __device__ __forceinline__ void transpose_tile(const float* __restrict__ W, int K, int N, u16* __restrict__ WT, int k0,
;                                                int n0) {
;   float* ts = (float*)g_shm;
;   const int tid = tid_();
;   float4 v[8];
; #pragma unroll
;   for (int i = 0; i < 8; ++i) {
;     int idx = tid + i * NT, r = idx >> 6, c4 = idx & 63;
;     v[i] = (n0 + c4 * 4 < N) ? *(const float4*)(W + (size_t)(k0 + r) * N + n0 + c4 * 4) : float4{0.f, 0.f, 0.f, 0.f};
;   }
;   __syncthreads();
; #pragma unroll
;   for (int i = 0; i < 8; ++i) {
;     int idx = tid + i * NT, r = idx >> 6, c4 = idx & 63;
;     float* d = ts + r * 257 + c4 * 4;
;     d[0] = v[i].x; d[1] = v[i].y; d[2] = v[i].z; d[3] = v[i].w;
;   }
;   __syncthreads();
;   if (n0 + (tid >> 1) < N) {
;     int n = tid >> 1, kh = tid & 1;
;     u16* dst = WT + (size_t)(n0 + n) * K + k0 + kh * 32;
; #pragma unroll
;     for (int q = 0; q < 4; ++q) {
;       unsigned pk[4];
; #pragma unroll
;       for (int i = 0; i < 4; ++i)
;         pk[i] = pack2(ts[(kh * 32 + q * 8 + 2 * i) * 257 + n], ts[(kh * 32 + q * 8 + 2 * i + 1) * 257 + n]);
;       *(i32x4*)(dst + q * 8) = i32x4{(int)pk[0], (int)pk[1], (int)pk[2], (int)pk[3]};
;     }
;   }
; }
; __device__ void transpose_matrix(const float* W, int K, int N, u16* WT) {
;   int tk = K / 64, tn = (N + 255) / 256, total = tk * tn;
;   for (int t = blockIdx.x; t < total; t += gridDim.x) {
;     int kt = t % tk, nt_ = t / tk;
;     transpose_tile(W, K, N, WT, kt * 64, nt_ * 256);
;   }
; }
; __device__ void phase0(const Params& p) {
;     ...
;   transpose_matrix(p.w_sb_proj, 2048, 2048, (u16*)(p.ws + OFF_WSB));
.Lt20b_Ago:
	s_barrier
	ds_write_b128 v41, v[0:3]
	ds_write_b128 v41, v[4:7] offset:8320
	ds_write_b128 v41, v[8:11] offset:16640
	ds_write_b128 v41, v[12:15] offset:24960
	ds_write_b128 v41, v[16:19] offset:33280
	ds_write_b128 v41, v[20:23] offset:41600
	ds_write_b128 v41, v[24:27] offset:49920
	ds_write_b128 v41, v[28:31] offset:58240
	s_waitcnt lgkmcnt(0)
	s_barrier
	ds_read_b32 v48, v42
	ds_read_b32 v49, v42 offset:1040
	ds_read_b32 v50, v42 offset:2080
	ds_read_b32 v51, v42 offset:3120
	ds_read_b32 v52, v42 offset:4160
	ds_read_b32 v53, v42 offset:5200
	ds_read_b32 v54, v42 offset:6240
	ds_read_b32 v55, v42 offset:7280
	ds_read_b32 v56, v42 offset:8320
	ds_read_b32 v57, v42 offset:9360
	ds_read_b32 v58, v42 offset:10400
	ds_read_b32 v59, v42 offset:11440
	ds_read_b32 v60, v42 offset:12480
	ds_read_b32 v61, v42 offset:13520
	ds_read_b32 v62, v42 offset:14560
	ds_read_b32 v63, v42 offset:15600
	s_waitcnt lgkmcnt(8)
	v_cvt_pk_bf16_f32 v80, v48, v49
	v_cvt_pk_bf16_f32 v81, v50, v51
	v_cvt_pk_bf16_f32 v82, v52, v53
	v_cvt_pk_bf16_f32 v83, v54, v55
	global_store_dwordx4 v40, v[80:83], s[20:21]
	ds_read_b32 v64, v42 offset:16640
	ds_read_b32 v65, v42 offset:17680
	ds_read_b32 v66, v42 offset:18720
	ds_read_b32 v67, v42 offset:19760
	ds_read_b32 v68, v42 offset:20800
	ds_read_b32 v69, v42 offset:21840
	ds_read_b32 v70, v42 offset:22880
	ds_read_b32 v71, v42 offset:23920
	s_waitcnt lgkmcnt(8)
	v_cvt_pk_bf16_f32 v84, v56, v57
	v_cvt_pk_bf16_f32 v85, v58, v59
	v_cvt_pk_bf16_f32 v86, v60, v61
	v_cvt_pk_bf16_f32 v87, v62, v63
	global_store_dwordx4 v40, v[84:87], s[20:21] offset:16
	ds_read_b32 v72, v42 offset:24960
	ds_read_b32 v73, v42 offset:26000
	ds_read_b32 v74, v42 offset:27040
	ds_read_b32 v75, v42 offset:28080
	ds_read_b32 v76, v42 offset:29120
	ds_read_b32 v77, v42 offset:30160
	ds_read_b32 v78, v42 offset:31200
	ds_read_b32 v79, v42 offset:32240
	s_waitcnt lgkmcnt(8)
	v_cvt_pk_bf16_f32 v88, v64, v65
	v_cvt_pk_bf16_f32 v89, v66, v67
	v_cvt_pk_bf16_f32 v90, v68, v69
	v_cvt_pk_bf16_f32 v91, v70, v71
	global_store_dwordx4 v40, v[88:91], s[20:21] offset:32
	s_waitcnt lgkmcnt(0)
	v_cvt_pk_bf16_f32 v92, v72, v73
	v_cvt_pk_bf16_f32 v93, v74, v75
	v_cvt_pk_bf16_f32 v94, v76, v77
	v_cvt_pk_bf16_f32 v95, v78, v79
	global_store_dwordx4 v40, v[92:95], s[20:21] offset:48
	s_add_u32 s17, s17, s33
	s_cmp_lt_u32 s17, 256
	s_cbranch_scc0 .Lt20b_Anl
	s_and_b32 s14, s17, 31
	s_lshr_b32 s15, s17, 5
	s_lshl_b32 s14, s14, 6
	s_lshl_b32 s24, s15, 8
	s_mul_i32 s16, s14, s12
	s_add_u32 s16, s16, s24
	s_lshl_b32 s16, s16, 2
	s_add_u32 s18, s8, s16
	s_addc_u32 s19, s9, 0
	s_mul_i32 s16, s24, 0x800
	s_add_u32 s16, s16, s14
	s_lshl_b32 s16, s16, 1
	s_add_u32 s20, s10, s16
	s_addc_u32 s21, s11, 0
	global_load_dwordx4 v[0:3], v32, s[18:19]
	global_load_dwordx4 v[4:7], v33, s[18:19]
	global_load_dwordx4 v[8:11], v34, s[18:19]
	global_load_dwordx4 v[12:15], v35, s[18:19]
	global_load_dwordx4 v[16:19], v36, s[18:19]
	global_load_dwordx4 v[20:23], v37, s[18:19]
	global_load_dwordx4 v[24:27], v38, s[18:19]
	global_load_dwordx4 v[28:31], v39, s[18:19]
.Lt20b_Anl:
	s_add_u32 s3, s3, s33
	s_cmp_lt_u32 s3, 256
	s_cbranch_scc0 .Lt20b_end
	s_add_u32 s17, s3, s33
	s_cmp_lt_u32 s17, 256
	s_cbranch_scc1 .Lt20b_Bw8
	s_waitcnt vmcnt(0)
	s_branch .Lt20b_Bgo

; __device__ __forceinline__ void transpose_tile(const float* __restrict__ W, int K, int N, u16* __restrict__ WT, int k0,
;                                                int n0) {
;   float* ts = (float*)g_shm;
;   const int tid = tid_();
;   float4 v[8];
; #pragma unroll
;   for (int i = 0; i < 8; ++i) {
;     int idx = tid + i * NT, r = idx >> 6, c4 = idx & 63;
;     v[i] = (n0 + c4 * 4 < N) ? *(const float4*)(W + (size_t)(k0 + r) * N + n0 + c4 * 4) : float4{0.f, 0.f, 0.f, 0.f};
;   }
;   __syncthreads();
; #pragma unroll
;   for (int i = 0; i < 8; ++i) {
;     int idx = tid + i * NT, r = idx >> 6, c4 = idx & 63;
;     float* d = ts + r * 257 + c4 * 4;
;     d[0] = v[i].x; d[1] = v[i].y; d[2] = v[i].z; d[3] = v[i].w;
;   }
;   __syncthreads();
;   if (n0 + (tid >> 1) < N) {
;     int n = tid >> 1, kh = tid & 1;
;     u16* dst = WT + (size_t)(n0 + n) * K + k0 + kh * 32;
; #pragma unroll
;     for (int q = 0; q < 4; ++q) {
;       unsigned pk[4];
; #pragma unroll
;       for (int i = 0; i < 4; ++i)
;         pk[i] = pack2(ts[(kh * 32 + q * 8 + 2 * i) * 257 + n], ts[(kh * 32 + q * 8 + 2 * i + 1) * 257 + n]);
;       *(i32x4*)(dst + q * 8) = i32x4{(int)pk[0], (int)pk[1], (int)pk[2], (int)pk[3]};
;     }
;   }
; }
; __device__ void transpose_matrix(const float* W, int K, int N, u16* WT) {
;   int tk = K / 64, tn = (N + 255) / 256, total = tk * tn;
;   for (int t = blockIdx.x; t < total; t += gridDim.x) {
;     int kt = t % tk, nt_ = t / tk;
;     transpose_tile(W, K, N, WT, kt * 64, nt_ * 256);
;   }
; }
; __device__ void phase0(const Params& p) {
;     ...
;   transpose_matrix(p.w_sb_proj, 2048, 2048, (u16*)(p.ws + OFF_WSB));
;   transpose_matrix(p.w_ssd_proj, 4096, 2048, (u16*)(p.ws + OFF_WSSD));
.Lt20b_Bgo:
	s_barrier
	ds_write_b128 v41, v[100:103]
	ds_write_b128 v41, v[104:107] offset:8320
	ds_write_b128 v41, v[108:111] offset:16640
	ds_write_b128 v41, v[112:115] offset:24960
	ds_write_b128 v41, v[116:119] offset:33280
	ds_write_b128 v41, v[120:123] offset:41600
	ds_write_b128 v41, v[124:127] offset:49920
	ds_write_b128 v41, v[128:131] offset:58240
	s_waitcnt lgkmcnt(0)
	s_barrier
	ds_read_b32 v48, v42
	ds_read_b32 v49, v42 offset:1040
	ds_read_b32 v50, v42 offset:2080
	ds_read_b32 v51, v42 offset:3120
	ds_read_b32 v52, v42 offset:4160
	ds_read_b32 v53, v42 offset:5200
	ds_read_b32 v54, v42 offset:6240
	ds_read_b32 v55, v42 offset:7280
	ds_read_b32 v56, v42 offset:8320
	ds_read_b32 v57, v42 offset:9360
	ds_read_b32 v58, v42 offset:10400
	ds_read_b32 v59, v42 offset:11440
	ds_read_b32 v60, v42 offset:12480
	ds_read_b32 v61, v42 offset:13520
	ds_read_b32 v62, v42 offset:14560
	ds_read_b32 v63, v42 offset:15600
	s_waitcnt lgkmcnt(8)
	v_cvt_pk_bf16_f32 v80, v48, v49
	v_cvt_pk_bf16_f32 v81, v50, v51
	v_cvt_pk_bf16_f32 v82, v52, v53
	v_cvt_pk_bf16_f32 v83, v54, v55
	global_store_dwordx4 v40, v[80:83], s[26:27]
	ds_read_b32 v64, v42 offset:16640
	ds_read_b32 v65, v42 offset:17680
	ds_read_b32 v66, v42 offset:18720
	ds_read_b32 v67, v42 offset:19760
	ds_read_b32 v68, v42 offset:20800
	ds_read_b32 v69, v42 offset:21840
	ds_read_b32 v70, v42 offset:22880
	ds_read_b32 v71, v42 offset:23920
	s_waitcnt lgkmcnt(8)
	v_cvt_pk_bf16_f32 v84, v56, v57
	v_cvt_pk_bf16_f32 v85, v58, v59
	v_cvt_pk_bf16_f32 v86, v60, v61
	v_cvt_pk_bf16_f32 v87, v62, v63
	global_store_dwordx4 v40, v[84:87], s[26:27] offset:16
	ds_read_b32 v72, v42 offset:24960
	ds_read_b32 v73, v42 offset:26000
	ds_read_b32 v74, v42 offset:27040
	ds_read_b32 v75, v42 offset:28080
	ds_read_b32 v76, v42 offset:29120
	ds_read_b32 v77, v42 offset:30160
	ds_read_b32 v78, v42 offset:31200
	ds_read_b32 v79, v42 offset:32240
	s_waitcnt lgkmcnt(8)
	v_cvt_pk_bf16_f32 v88, v64, v65
	v_cvt_pk_bf16_f32 v89, v66, v67
	v_cvt_pk_bf16_f32 v90, v68, v69
	v_cvt_pk_bf16_f32 v91, v70, v71
	global_store_dwordx4 v40, v[88:91], s[26:27] offset:32
	s_waitcnt lgkmcnt(0)
	v_cvt_pk_bf16_f32 v92, v72, v73
	v_cvt_pk_bf16_f32 v93, v74, v75
	v_cvt_pk_bf16_f32 v94, v76, v77
	v_cvt_pk_bf16_f32 v95, v78, v79
	global_store_dwordx4 v40, v[92:95], s[26:27] offset:48
	s_add_u32 s17, s17, s33
	s_cmp_lt_u32 s17, 256
	s_cbranch_scc0 .Lt20b_Bnl
	s_and_b32 s14, s17, 31
	s_lshr_b32 s15, s17, 5
	s_lshl_b32 s14, s14, 6
	s_lshl_b32 s25, s15, 8
	s_mul_i32 s16, s14, s12
	s_add_u32 s16, s16, s25
	s_lshl_b32 s16, s16, 2
	s_add_u32 s18, s8, s16
	s_addc_u32 s19, s9, 0
	s_mul_i32 s16, s25, 0x800
	s_add_u32 s16, s16, s14
	s_lshl_b32 s16, s16, 1
	s_add_u32 s26, s10, s16
	s_addc_u32 s27, s11, 0
	global_load_dwordx4 v[100:103], v32, s[18:19]
	global_load_dwordx4 v[104:107], v33, s[18:19]
	global_load_dwordx4 v[108:111], v34, s[18:19]
	global_load_dwordx4 v[112:115], v35, s[18:19]
	global_load_dwordx4 v[116:119], v36, s[18:19]
	global_load_dwordx4 v[120:123], v37, s[18:19]
	global_load_dwordx4 v[124:127], v38, s[18:19]
	global_load_dwordx4 v[128:131], v39, s[18:19]
.Lt20b_Bnl:
	s_add_u32 s3, s3, s33
	s_cmp_lt_u32 s3, 256
	s_cbranch_scc1 .Lt20b_loop
.Lt20b_end:
	v_mov_b32_e32 v96, 0
	global_load_dwordx2 v[98:99], v96, s[50:51] offset:80
	s_mov_b32 s12, 0x800
	v_mul_lo_u32 v32, v45, s12
	v_add_lshl_u32 v32, v32, v43, 2
	s_mov_b32 s13, 0x10000
	v_add_u32_e32 v33, s13, v32
	v_add_u32_e32 v34, s13, v33
	v_add_u32_e32 v35, s13, v34
	v_add_u32_e32 v36, s13, v35
	v_add_u32_e32 v37, s13, v36
	v_add_u32_e32 v38, s13, v37
	v_add_u32_e32 v39, s13, v38
	v_mul_u32_u24_e32 v40, 0x2000, v44
	v_lshl_add_u32 v40, v47, 6, v40
	s_waitcnt vmcnt(0)
	v_readfirstlane_b32 s8, v98
	v_readfirstlane_b32 s9, v99
	s_add_u32 s10, s28, 0x5900000
	s_addc_u32 s11, s29, 0
	s_mov_b32 s3, s2
	s_cmp_lt_u32 s3, 512
	s_cbranch_scc0 .Lt20c_end
	s_and_b32 s14, s3, 63
	s_lshr_b32 s15, s3, 6
	s_lshl_b32 s14, s14, 6
	s_lshl_b32 s24, s15, 8
	s_mul_i32 s16, s14, s12
	s_add_u32 s16, s16, s24
	s_lshl_b32 s16, s16, 2
	s_add_u32 s18, s8, s16
	s_addc_u32 s19, s9, 0
	s_mul_i32 s16, s24, 0x1000
	s_add_u32 s16, s16, s14
	s_lshl_b32 s16, s16, 1
	s_add_u32 s20, s10, s16
	s_addc_u32 s21, s11, 0
	global_load_dwordx4 v[0:3], v32, s[18:19]
	global_load_dwordx4 v[4:7], v33, s[18:19]
	global_load_dwordx4 v[8:11], v34, s[18:19]
	global_load_dwordx4 v[12:15], v35, s[18:19]
	global_load_dwordx4 v[16:19], v36, s[18:19]
	global_load_dwordx4 v[20:23], v37, s[18:19]
	global_load_dwordx4 v[24:27], v38, s[18:19]
	global_load_dwordx4 v[28:31], v39, s[18:19]
	s_add_u32 s17, s3, s33
	s_cmp_lt_u32 s17, 512
	s_cbranch_scc0 .Lt20c_loop
	s_and_b32 s14, s17, 63
	s_lshr_b32 s15, s17, 6
	s_lshl_b32 s14, s14, 6
	s_lshl_b32 s25, s15, 8
	s_mul_i32 s16, s14, s12
	s_add_u32 s16, s16, s25
	s_lshl_b32 s16, s16, 2
	s_add_u32 s18, s8, s16
	s_addc_u32 s19, s9, 0
	s_mul_i32 s16, s25, 0x1000
	s_add_u32 s16, s16, s14
	s_lshl_b32 s16, s16, 1
	s_add_u32 s26, s10, s16
	s_addc_u32 s27, s11, 0
	global_load_dwordx4 v[100:103], v32, s[18:19]
	global_load_dwordx4 v[104:107], v33, s[18:19]
	global_load_dwordx4 v[108:111], v34, s[18:19]
	global_load_dwordx4 v[112:115], v35, s[18:19]
	global_load_dwordx4 v[116:119], v36, s[18:19]
	global_load_dwordx4 v[120:123], v37, s[18:19]
	global_load_dwordx4 v[124:127], v38, s[18:19]
	global_load_dwordx4 v[128:131], v39, s[18:19]
.Lt20c_loop:
	s_add_u32 s17, s3, s33
	s_cmp_lt_u32 s17, 512
	s_cbranch_scc1 .Lt20c_Aw8
	s_waitcnt vmcnt(0)
	s_branch .Lt20c_Ago

; __device__ __forceinline__ void transpose_tile(const float* __restrict__ W, int K, int N, u16* __restrict__ WT, int k0,
;                                                int n0) {
;   float* ts = (float*)g_shm;
;   const int tid = tid_();
;   float4 v[8];
; #pragma unroll
;   for (int i = 0; i < 8; ++i) {
;     int idx = tid + i * NT, r = idx >> 6, c4 = idx & 63;
;     v[i] = (n0 + c4 * 4 < N) ? *(const float4*)(W + (size_t)(k0 + r) * N + n0 + c4 * 4) : float4{0.f, 0.f, 0.f, 0.f};
;   }
;   __syncthreads();
; #pragma unroll
;   for (int i = 0; i < 8; ++i) {
;     int idx = tid + i * NT, r = idx >> 6, c4 = idx & 63;
;     float* d = ts + r * 257 + c4 * 4;
;     d[0] = v[i].x; d[1] = v[i].y; d[2] = v[i].z; d[3] = v[i].w;
;   }
;   __syncthreads();
;   if (n0 + (tid >> 1) < N) {
;     int n = tid >> 1, kh = tid & 1;
;     u16* dst = WT + (size_t)(n0 + n) * K + k0 + kh * 32;
; #pragma unroll
;     for (int q = 0; q < 4; ++q) {
;       unsigned pk[4];
; #pragma unroll
;       for (int i = 0; i < 4; ++i)
;         pk[i] = pack2(ts[(kh * 32 + q * 8 + 2 * i) * 257 + n], ts[(kh * 32 + q * 8 + 2 * i + 1) * 257 + n]);
;       *(i32x4*)(dst + q * 8) = i32x4{(int)pk[0], (int)pk[1], (int)pk[2], (int)pk[3]};
;     }
;   }
; }
; __device__ void transpose_matrix(const float* W, int K, int N, u16* WT) {
;   int tk = K / 64, tn = (N + 255) / 256, total = tk * tn;
;   for (int t = blockIdx.x; t < total; t += gridDim.x) {
;     int kt = t % tk, nt_ = t / tk;
;     transpose_tile(W, K, N, WT, kt * 64, nt_ * 256);
;   }
; }
; __device__ void phase0(const Params& p) {
;     ...
;   transpose_matrix(p.w_ssd_proj, 4096, 2048, (u16*)(p.ws + OFF_WSSD));
.Lt20c_Ago:
	s_barrier
	ds_write_b128 v41, v[0:3]
	ds_write_b128 v41, v[4:7] offset:8320
	ds_write_b128 v41, v[8:11] offset:16640
	ds_write_b128 v41, v[12:15] offset:24960
	ds_write_b128 v41, v[16:19] offset:33280
	ds_write_b128 v41, v[20:23] offset:41600
	ds_write_b128 v41, v[24:27] offset:49920
	ds_write_b128 v41, v[28:31] offset:58240
	s_waitcnt lgkmcnt(0)
	s_barrier
	ds_read_b32 v48, v42
	ds_read_b32 v49, v42 offset:1040
	ds_read_b32 v50, v42 offset:2080
	ds_read_b32 v51, v42 offset:3120
	ds_read_b32 v52, v42 offset:4160
	ds_read_b32 v53, v42 offset:5200
	ds_read_b32 v54, v42 offset:6240
	ds_read_b32 v55, v42 offset:7280
	ds_read_b32 v56, v42 offset:8320
	ds_read_b32 v57, v42 offset:9360
	ds_read_b32 v58, v42 offset:10400
	ds_read_b32 v59, v42 offset:11440
	ds_read_b32 v60, v42 offset:12480
	ds_read_b32 v61, v42 offset:13520
	ds_read_b32 v62, v42 offset:14560
	ds_read_b32 v63, v42 offset:15600
	s_waitcnt lgkmcnt(8)
	v_cvt_pk_bf16_f32 v80, v48, v49
	v_cvt_pk_bf16_f32 v81, v50, v51
	v_cvt_pk_bf16_f32 v82, v52, v53
	v_cvt_pk_bf16_f32 v83, v54, v55
	global_store_dwordx4 v40, v[80:83], s[20:21]
	ds_read_b32 v64, v42 offset:16640
	ds_read_b32 v65, v42 offset:17680
	ds_read_b32 v66, v42 offset:18720
	ds_read_b32 v67, v42 offset:19760
	ds_read_b32 v68, v42 offset:20800
	ds_read_b32 v69, v42 offset:21840
	ds_read_b32 v70, v42 offset:22880
	ds_read_b32 v71, v42 offset:23920
	s_waitcnt lgkmcnt(8)
	v_cvt_pk_bf16_f32 v84, v56, v57
	v_cvt_pk_bf16_f32 v85, v58, v59
	v_cvt_pk_bf16_f32 v86, v60, v61
	v_cvt_pk_bf16_f32 v87, v62, v63
	global_store_dwordx4 v40, v[84:87], s[20:21] offset:16
	ds_read_b32 v72, v42 offset:24960
	ds_read_b32 v73, v42 offset:26000
	ds_read_b32 v74, v42 offset:27040
	ds_read_b32 v75, v42 offset:28080
	ds_read_b32 v76, v42 offset:29120
	ds_read_b32 v77, v42 offset:30160
	ds_read_b32 v78, v42 offset:31200
	ds_read_b32 v79, v42 offset:32240
	s_waitcnt lgkmcnt(8)
	v_cvt_pk_bf16_f32 v88, v64, v65
	v_cvt_pk_bf16_f32 v89, v66, v67
	v_cvt_pk_bf16_f32 v90, v68, v69
	v_cvt_pk_bf16_f32 v91, v70, v71
	global_store_dwordx4 v40, v[88:91], s[20:21] offset:32
	s_waitcnt lgkmcnt(0)
	v_cvt_pk_bf16_f32 v92, v72, v73
	v_cvt_pk_bf16_f32 v93, v74, v75
	v_cvt_pk_bf16_f32 v94, v76, v77
	v_cvt_pk_bf16_f32 v95, v78, v79
	global_store_dwordx4 v40, v[92:95], s[20:21] offset:48
	s_add_u32 s17, s17, s33
	s_cmp_lt_u32 s17, 512
	s_cbranch_scc0 .Lt20c_Anl
	s_and_b32 s14, s17, 63
	s_lshr_b32 s15, s17, 6
	s_lshl_b32 s14, s14, 6
	s_lshl_b32 s24, s15, 8
	s_mul_i32 s16, s14, s12
	s_add_u32 s16, s16, s24
	s_lshl_b32 s16, s16, 2
	s_add_u32 s18, s8, s16
	s_addc_u32 s19, s9, 0
	s_mul_i32 s16, s24, 0x1000
	s_add_u32 s16, s16, s14
	s_lshl_b32 s16, s16, 1
	s_add_u32 s20, s10, s16
	s_addc_u32 s21, s11, 0
	global_load_dwordx4 v[0:3], v32, s[18:19]
	global_load_dwordx4 v[4:7], v33, s[18:19]
	global_load_dwordx4 v[8:11], v34, s[18:19]
	global_load_dwordx4 v[12:15], v35, s[18:19]
	global_load_dwordx4 v[16:19], v36, s[18:19]
	global_load_dwordx4 v[20:23], v37, s[18:19]
	global_load_dwordx4 v[24:27], v38, s[18:19]
	global_load_dwordx4 v[28:31], v39, s[18:19]
.Lt20c_Anl:
	s_add_u32 s3, s3, s33
	s_cmp_lt_u32 s3, 512
	s_cbranch_scc0 .Lt20c_end
	s_add_u32 s17, s3, s33
	s_cmp_lt_u32 s17, 512
	s_cbranch_scc1 .Lt20c_Bw8
	s_waitcnt vmcnt(0)
	s_branch .Lt20c_Bgo

; __device__ __forceinline__ void transpose_tile(const float* __restrict__ W, int K, int N, u16* __restrict__ WT, int k0,
;                                                int n0) {
;   float* ts = (float*)g_shm;
;   const int tid = tid_();
;   float4 v[8];
; #pragma unroll
;   for (int i = 0; i < 8; ++i) {
;     int idx = tid + i * NT, r = idx >> 6, c4 = idx & 63;
;     v[i] = (n0 + c4 * 4 < N) ? *(const float4*)(W + (size_t)(k0 + r) * N + n0 + c4 * 4) : float4{0.f, 0.f, 0.f, 0.f};
;   }
;   __syncthreads();
; #pragma unroll
;   for (int i = 0; i < 8; ++i) {
;     int idx = tid + i * NT, r = idx >> 6, c4 = idx & 63;
;     float* d = ts + r * 257 + c4 * 4;
;     d[0] = v[i].x; d[1] = v[i].y; d[2] = v[i].z; d[3] = v[i].w;
;   }
;   __syncthreads();
;   if (n0 + (tid >> 1) < N) {
;     int n = tid >> 1, kh = tid & 1;
;     u16* dst = WT + (size_t)(n0 + n) * K + k0 + kh * 32;
; #pragma unroll
;     for (int q = 0; q < 4; ++q) {
;       unsigned pk[4];
; #pragma unroll
;       for (int i = 0; i < 4; ++i)
;         pk[i] = pack2(ts[(kh * 32 + q * 8 + 2 * i) * 257 + n], ts[(kh * 32 + q * 8 + 2 * i + 1) * 257 + n]);
;       *(i32x4*)(dst + q * 8) = i32x4{(int)pk[0], (int)pk[1], (int)pk[2], (int)pk[3]};
;     }
;   }
; }
; __device__ void transpose_matrix(const float* W, int K, int N, u16* WT) {
;   int tk = K / 64, tn = (N + 255) / 256, total = tk * tn;
;   for (int t = blockIdx.x; t < total; t += gridDim.x) {
;     int kt = t % tk, nt_ = t / tk;
;     transpose_tile(W, K, N, WT, kt * 64, nt_ * 256);
;   }
; }
; __device__ void phase0(const Params& p) {
;     ...
;   transpose_matrix(p.w_ssd_proj, 4096, 2048, (u16*)(p.ws + OFF_WSSD));
;   transpose_matrix(p.w_out, 2048, 2048, (u16*)(p.ws + OFF_WOUT));
.Lt20c_Bgo:
	s_barrier
	ds_write_b128 v41, v[100:103]
	ds_write_b128 v41, v[104:107] offset:8320
	ds_write_b128 v41, v[108:111] offset:16640
	ds_write_b128 v41, v[112:115] offset:24960
	ds_write_b128 v41, v[116:119] offset:33280
	ds_write_b128 v41, v[120:123] offset:41600
	ds_write_b128 v41, v[124:127] offset:49920
	ds_write_b128 v41, v[128:131] offset:58240
	s_waitcnt lgkmcnt(0)
	s_barrier
	ds_read_b32 v48, v42
	ds_read_b32 v49, v42 offset:1040
	ds_read_b32 v50, v42 offset:2080
	ds_read_b32 v51, v42 offset:3120
	ds_read_b32 v52, v42 offset:4160
	ds_read_b32 v53, v42 offset:5200
	ds_read_b32 v54, v42 offset:6240
	ds_read_b32 v55, v42 offset:7280
	ds_read_b32 v56, v42 offset:8320
	ds_read_b32 v57, v42 offset:9360
	ds_read_b32 v58, v42 offset:10400
	ds_read_b32 v59, v42 offset:11440
	ds_read_b32 v60, v42 offset:12480
	ds_read_b32 v61, v42 offset:13520
	ds_read_b32 v62, v42 offset:14560
	ds_read_b32 v63, v42 offset:15600
	s_waitcnt lgkmcnt(8)
	v_cvt_pk_bf16_f32 v80, v48, v49
	v_cvt_pk_bf16_f32 v81, v50, v51
	v_cvt_pk_bf16_f32 v82, v52, v53
	v_cvt_pk_bf16_f32 v83, v54, v55
	global_store_dwordx4 v40, v[80:83], s[26:27]
	ds_read_b32 v64, v42 offset:16640
	ds_read_b32 v65, v42 offset:17680
	ds_read_b32 v66, v42 offset:18720
	ds_read_b32 v67, v42 offset:19760
	ds_read_b32 v68, v42 offset:20800
	ds_read_b32 v69, v42 offset:21840
	ds_read_b32 v70, v42 offset:22880
	ds_read_b32 v71, v42 offset:23920
	s_waitcnt lgkmcnt(8)
	v_cvt_pk_bf16_f32 v84, v56, v57
	v_cvt_pk_bf16_f32 v85, v58, v59
	v_cvt_pk_bf16_f32 v86, v60, v61
	v_cvt_pk_bf16_f32 v87, v62, v63
	global_store_dwordx4 v40, v[84:87], s[26:27] offset:16
	ds_read_b32 v72, v42 offset:24960
	ds_read_b32 v73, v42 offset:26000
	ds_read_b32 v74, v42 offset:27040
	ds_read_b32 v75, v42 offset:28080
	ds_read_b32 v76, v42 offset:29120
	ds_read_b32 v77, v42 offset:30160
	ds_read_b32 v78, v42 offset:31200
	ds_read_b32 v79, v42 offset:32240
	s_waitcnt lgkmcnt(8)
	v_cvt_pk_bf16_f32 v88, v64, v65
	v_cvt_pk_bf16_f32 v89, v66, v67
	v_cvt_pk_bf16_f32 v90, v68, v69
	v_cvt_pk_bf16_f32 v91, v70, v71
	global_store_dwordx4 v40, v[88:91], s[26:27] offset:32
	s_waitcnt lgkmcnt(0)
	v_cvt_pk_bf16_f32 v92, v72, v73
	v_cvt_pk_bf16_f32 v93, v74, v75
	v_cvt_pk_bf16_f32 v94, v76, v77
	v_cvt_pk_bf16_f32 v95, v78, v79
	global_store_dwordx4 v40, v[92:95], s[26:27] offset:48
	s_add_u32 s17, s17, s33
	s_cmp_lt_u32 s17, 512
	s_cbranch_scc0 .Lt20c_Bnl
	s_and_b32 s14, s17, 63
	s_lshr_b32 s15, s17, 6
	s_lshl_b32 s14, s14, 6
	s_lshl_b32 s25, s15, 8
	s_mul_i32 s16, s14, s12
	s_add_u32 s16, s16, s25
	s_lshl_b32 s16, s16, 2
	s_add_u32 s18, s8, s16
	s_addc_u32 s19, s9, 0
	s_mul_i32 s16, s25, 0x1000
	s_add_u32 s16, s16, s14
	s_lshl_b32 s16, s16, 1
	s_add_u32 s26, s10, s16
	s_addc_u32 s27, s11, 0
	global_load_dwordx4 v[100:103], v32, s[18:19]
	global_load_dwordx4 v[104:107], v33, s[18:19]
	global_load_dwordx4 v[108:111], v34, s[18:19]
	global_load_dwordx4 v[112:115], v35, s[18:19]
	global_load_dwordx4 v[116:119], v36, s[18:19]
	global_load_dwordx4 v[120:123], v37, s[18:19]
	global_load_dwordx4 v[124:127], v38, s[18:19]
	global_load_dwordx4 v[128:131], v39, s[18:19]
.Lt20c_Bnl:
	s_add_u32 s3, s3, s33
	s_cmp_lt_u32 s3, 512
	s_cbranch_scc1 .Lt20c_loop
.Lt20c_end:
	v_mov_b32_e32 v96, 0
	global_load_dwordx2 v[98:99], v96, s[50:51] offset:88
	s_mov_b32 s12, 0x800
	v_mul_lo_u32 v32, v45, s12
	v_add_lshl_u32 v32, v32, v43, 2
	s_mov_b32 s13, 0x10000
	v_add_u32_e32 v33, s13, v32
	v_add_u32_e32 v34, s13, v33
	v_add_u32_e32 v35, s13, v34
	v_add_u32_e32 v36, s13, v35
	v_add_u32_e32 v37, s13, v36
	v_add_u32_e32 v38, s13, v37
	v_add_u32_e32 v39, s13, v38
	v_mul_u32_u24_e32 v40, 0x1000, v44
	v_lshl_add_u32 v40, v47, 6, v40
	s_waitcnt vmcnt(0)
	v_readfirstlane_b32 s8, v98
	v_readfirstlane_b32 s9, v99
	s_add_u32 s10, s28, 0x6900000
	s_addc_u32 s11, s29, 0
	s_mov_b32 s3, s2
	s_cmp_lt_u32 s3, 256
	s_cbranch_scc0 .Lt20d_end
	s_and_b32 s14, s3, 31
	s_lshr_b32 s15, s3, 5
	s_lshl_b32 s14, s14, 6
	s_lshl_b32 s24, s15, 8
	s_mul_i32 s16, s14, s12
	s_add_u32 s16, s16, s24
	s_lshl_b32 s16, s16, 2
	s_add_u32 s18, s8, s16
	s_addc_u32 s19, s9, 0
	s_mul_i32 s16, s24, 0x800
	s_add_u32 s16, s16, s14
	s_lshl_b32 s16, s16, 1
	s_add_u32 s20, s10, s16
	s_addc_u32 s21, s11, 0
	global_load_dwordx4 v[0:3], v32, s[18:19]
	global_load_dwordx4 v[4:7], v33, s[18:19]
	global_load_dwordx4 v[8:11], v34, s[18:19]
	global_load_dwordx4 v[12:15], v35, s[18:19]
	global_load_dwordx4 v[16:19], v36, s[18:19]
	global_load_dwordx4 v[20:23], v37, s[18:19]
	global_load_dwordx4 v[24:27], v38, s[18:19]
	global_load_dwordx4 v[28:31], v39, s[18:19]
	s_add_u32 s17, s3, s33
	s_cmp_lt_u32 s17, 256
	s_cbranch_scc0 .Lt20d_loop
	s_and_b32 s14, s17, 31
	s_lshr_b32 s15, s17, 5
	s_lshl_b32 s14, s14, 6
	s_lshl_b32 s25, s15, 8
	s_mul_i32 s16, s14, s12
	s_add_u32 s16, s16, s25
	s_lshl_b32 s16, s16, 2
	s_add_u32 s18, s8, s16
	s_addc_u32 s19, s9, 0
	s_mul_i32 s16, s25, 0x800
	s_add_u32 s16, s16, s14
	s_lshl_b32 s16, s16, 1
	s_add_u32 s26, s10, s16
	s_addc_u32 s27, s11, 0
	global_load_dwordx4 v[100:103], v32, s[18:19]
	global_load_dwordx4 v[104:107], v33, s[18:19]
	global_load_dwordx4 v[108:111], v34, s[18:19]
	global_load_dwordx4 v[112:115], v35, s[18:19]
	global_load_dwordx4 v[116:119], v36, s[18:19]
	global_load_dwordx4 v[120:123], v37, s[18:19]
	global_load_dwordx4 v[124:127], v38, s[18:19]
	global_load_dwordx4 v[128:131], v39, s[18:19]

; __device__ void transpose_matrix(const float* W, int K, int N, u16* WT) {
;   int tk = K / 64, tn = (N + 255) / 256, total = tk * tn;
;   for (int t = blockIdx.x; t < total; t += gridDim.x) {
;     int kt = t % tk, nt_ = t / tk;
;     transpose_tile(W, K, N, WT, kt * 64, nt_ * 256);
;   }
; }
; __device__ void phase0(const Params& p) {
;     ...
;   transpose_matrix(p.w_sb_proj, 2048, 2048, (u16*)(p.ws + OFF_WSB));
;   transpose_matrix(p.w_ssd_proj, 4096, 2048, (u16*)(p.ws + OFF_WSSD));
;   transpose_matrix(p.w_out, 2048, 2048, (u16*)(p.ws + OFF_WOUT));
.Lt20d_end:
	s_cmpk_lt_i32 s2, 0x200
	s_cselect_b64 s[10:11], -1, 0
	v_writelane_b32 v254, s10, 1
	s_nop 0
	v_writelane_b32 v254, s11, 2
	s_cmpk_lt_i32 s2, 0x100
	s_cselect_b64 s[46:47], 0, -1

; __device__ __forceinline__ float siluf_(float v) { return v * __builtin_amdgcn_rcpf(1.f + __expf(-v)); }
; __device__ void phase_bcconv(const Params& p) {
;   const int tid = tid_();
;   const u16* xbc = (const u16*)(p.ws + OFF_XBC);
;   u16* bc = (u16*)p.out;
;   const int NJ = 256, RB = 8;
;   const int total = NJ * (MTOK / RB);
;   for (int it = blockIdx.x * NT + tid; it < total; it += gridDim.x * NT) {
;     int j8 = it % NJ, tblk = it / NJ;
;     int t0 = tblk * RB, tin = t0 & (SEQ - 1);
;     float w[4][8], bs[8];
; #pragma unroll
;     for (int k = 0; k < 4; ++k) {
;       float4 a = *(const float4*)(p.ssd_conv_w + (size_t)k * 6144 + 4096 + j8 * 8);
;       float4 b = *(const float4*)(p.ssd_conv_w + (size_t)k * 6144 + 4096 + j8 * 8 + 4);
;       w[k][0] = a.x; w[k][1] = a.y; w[k][2] = a.z; w[k][3] = a.w; w[k][4] = b.x; w[k][5] = b.y; w[k][6] = b.z; w[k][7] = b.w;
;     }
;     {
;       float4 a = *(const float4*)(p.ssd_conv_b + 4096 + j8 * 8), b = *(const float4*)(p.ssd_conv_b + 4096 + j8 * 8 + 4);
;       bs[0] = a.x; bs[1] = a.y; bs[2] = a.z; bs[3] = a.w; bs[4] = b.x; bs[5] = b.y; bs[6] = b.z; bs[7] = b.w;
;     }
;     float win[3][8];
; #pragma unroll
;     for (int k = 0; k < 3; ++k) {
;       if (tin - 3 + k >= 0) {
;         i32x4 a = *(const i32x4*)(xbc + (size_t)(t0 - 3 + k) * 6144 + 4096 + j8 * 8);
; #pragma unroll
;         for (int e = 0; e < 4; ++e) {
;           win[k][2 * e] = __uint_as_float(((unsigned)a[e]) << 16);
;           win[k][2 * e + 1] = __uint_as_float(((unsigned)a[e]) & 0xffff0000u);
;         }
;       } else {
; #pragma unroll
;         for (int e = 0; e < 8; ++e) win[k][e] = 0.f;
;       }
;     }
; #pragma unroll
;     for (int rr = 0; rr < RB; ++rr) {
;       float cur[8];
;       i32x4 a = *(const i32x4*)(xbc + (size_t)(t0 + rr) * 6144 + 4096 + j8 * 8);
; #pragma unroll
;       for (int e = 0; e < 4; ++e) {
;         cur[2 * e] = __uint_as_float(((unsigned)a[e]) << 16);
;         cur[2 * e + 1] = __uint_as_float(((unsigned)a[e]) & 0xffff0000u);
;       }
;       float res[8];
; #pragma unroll
;       for (int e = 0; e < 8; ++e) {
;         float s_ = bs[e] + w[0][e] * win[0][e] + w[1][e] * win[1][e] + w[2][e] * win[2][e] + w[3][e] * cur[e];
;         res[e] = siluf_(s_);
;         win[0][e] = win[1][e]; win[1][e] = win[2][e]; win[2][e] = cur[e];
;       }
;       *(i32x4*)(bc + (size_t)(t0 + rr) * 2048 + j8 * 8) =
.LBB0_873:
	s_or_b64 exec, exec, s[0:1]
	v_mov_b32_e32 v0, 0
	s_waitcnt lgkmcnt(0)
	s_barrier
	global_load_dwordx4 v[2:5], v0, s[50:51] offset:24
	global_load_dwordx4 v[6:9], v0, s[50:51] offset:152
	v_mov_b32_e32 v0, v214
	v_readlane_b32 s0, v254, 0
	s_mov_b32 s6, 0x80000
	s_waitcnt vmcnt(0)
	v_readfirstlane_b32 s4, v3
	v_add_u32_e32 v74, s0, v0
	v_readfirstlane_b32 s16, v2
	v_readfirstlane_b32 s3, v5
	v_readfirstlane_b32 s5, v4
	v_readfirstlane_b32 s1, v7
	v_readfirstlane_b32 s0, v6
	v_readfirstlane_b32 s9, v9
	v_readfirstlane_b32 s8, v8
	v_cmp_gt_i32_e32 vcc, s6, v74
	s_and_saveexec_b64 s[6:7], vcc
	s_cbranch_execz .LBB0_882
	s_add_u32 s8, s8, 0x17580000
	s_addc_u32 s9, s9, 0
	s_lshl_b32 s24, s33, 9
	s_add_u32 s10, s16, 0x4000
	s_addc_u32 s11, s4, 0
	s_add_u32 s12, s16, 0xa000
	s_addc_u32 s13, s4, 0
	s_add_u32 s14, s16, 0x10000
	s_addc_u32 s15, s4, 0
	s_add_u32 s16, s16, 0x16000
	s_addc_u32 s17, s4, 0
	s_add_u32 s18, s5, 0x4000
	v_lshlrev_b32_e32 v0, 3, v0
	s_addc_u32 s19, s3, 0
	v_lshl_add_u32 v75, s2, 12, v0
	s_lshl_b32 s25, s33, 12
	s_mov_b64 s[20:21], 0
	s_movk_i32 s26, 0x3000
	s_movk_i32 s27, 0x2000
	s_mov_b32 s28, 0x7ffff
	v_mov_b64_e32 v[40:41], s[8:9]
	s_mov_b32 s26, 0x18000
	s_movk_i32 s27, 0x3000
	s_mov_b32 s28, 0x80000
	s_mov_b32 s29, 0x9000
	s_movk_i32 s30, 0x1000
	v_mov_b32_e32 v235, v74
.Lbc_loop:
	v_lshrrev_b32_e32 v228, 8, v235
	v_and_b32_e32 v229, 0xff, v235
	v_mul_u32_u24_e32 v231, s26, v228
	v_lshlrev_b32_e32 v230, 5, v229
	v_lshlrev_b32_e32 v232, 15, v228
	v_lshl_add_u32 v231, v229, 4, v231
	v_lshl_add_u32 v232, v229, 4, v232
	v_add_u32_e32 v231, 0x2000, v231
	v_and_b32_e32 v233, 0x3ff, v228
	v_cmp_ne_u32_e32 vcc, 0, v233
	global_load_dwordx4 v[0:3], v230, s[10:11]
	global_load_dwordx4 v[4:7], v230, s[10:11] offset:16
	global_load_dwordx4 v[8:11], v230, s[12:13]
	global_load_dwordx4 v[12:15], v230, s[12:13] offset:16
	global_load_dwordx4 v[16:19], v230, s[14:15]
	global_load_dwordx4 v[20:23], v230, s[14:15] offset:16
	global_load_dwordx4 v[24:27], v230, s[16:17]
	global_load_dwordx4 v[28:31], v230, s[16:17] offset:16
	global_load_dwordx4 v[32:35], v230, s[18:19]
	global_load_dwordx4 v[36:39], v230, s[18:19] offset:16
	v_subrev_u32_e32 v234, s29, v231
	v_cndmask_b32_e32 v234, v231, v234, vcc
	global_load_dwordx4 v[64:67], v234, s[8:9]
	v_add_u32_e32 v234, s27, v234
	global_load_dwordx4 v[68:71], v234, s[8:9]
	v_add_u32_e32 v234, s27, v234
	global_load_dwordx4 v[72:75], v234, s[8:9]
	v_mov_b32_e32 v234, v231
	global_load_dwordx4 v[76:79], v234, s[8:9]
	v_add_u32_e32 v234, s27, v234
	global_load_dwordx4 v[80:83], v234, s[8:9]
	v_add_u32_e32 v234, s27, v234
	global_load_dwordx4 v[84:87], v234, s[8:9]
	v_add_u32_e32 v234, s27, v234
	global_load_dwordx4 v[88:91], v234, s[8:9]
	v_add_u32_e32 v234, s27, v234
	global_load_dwordx4 v[92:95], v234, s[8:9]
	v_add_u32_e32 v234, s27, v234
	global_load_dwordx4 v[96:99], v234, s[8:9]
	v_add_u32_e32 v234, s27, v234
	global_load_dwordx4 v[100:103], v234, s[8:9]
	v_add_u32_e32 v234, s27, v234
	global_load_dwordx4 v[104:107], v234, s[8:9]
	s_waitcnt vmcnt(7)
	v_cndmask_b32_e32 v64, 0, v64, vcc
	v_lshlrev_b32_e32 v144, 16, v64
	v_and_b32_e32 v145, 0xffff0000, v64
	v_cndmask_b32_e32 v65, 0, v65, vcc
	v_lshlrev_b32_e32 v146, 16, v65
	v_and_b32_e32 v147, 0xffff0000, v65
	v_cndmask_b32_e32 v66, 0, v66, vcc
	v_lshlrev_b32_e32 v148, 16, v66
	v_and_b32_e32 v149, 0xffff0000, v66
	v_cndmask_b32_e32 v67, 0, v67, vcc
	v_lshlrev_b32_e32 v150, 16, v67
	v_and_b32_e32 v151, 0xffff0000, v67
	v_cndmask_b32_e32 v68, 0, v68, vcc
	v_lshlrev_b32_e32 v152, 16, v68
	v_and_b32_e32 v153, 0xffff0000, v68
	v_cndmask_b32_e32 v69, 0, v69, vcc
	v_lshlrev_b32_e32 v154, 16, v69
	v_and_b32_e32 v155, 0xffff0000, v69
	v_cndmask_b32_e32 v70, 0, v70, vcc
	v_lshlrev_b32_e32 v156, 16, v70
	v_and_b32_e32 v157, 0xffff0000, v70
	v_cndmask_b32_e32 v71, 0, v71, vcc
	v_lshlrev_b32_e32 v158, 16, v71
	v_and_b32_e32 v159, 0xffff0000, v71
	v_cndmask_b32_e32 v72, 0, v72, vcc
	v_lshlrev_b32_e32 v160, 16, v72
	v_and_b32_e32 v161, 0xffff0000, v72
	v_cndmask_b32_e32 v73, 0, v73, vcc
	v_lshlrev_b32_e32 v162, 16, v73
	v_and_b32_e32 v163, 0xffff0000, v73
	v_cndmask_b32_e32 v74, 0, v74, vcc
	v_lshlrev_b32_e32 v164, 16, v74
	v_and_b32_e32 v165, 0xffff0000, v74
	v_cndmask_b32_e32 v75, 0, v75, vcc
	v_lshlrev_b32_e32 v166, 16, v75
	v_and_b32_e32 v167, 0xffff0000, v75
	v_lshlrev_b32_e32 v168, 16, v76
	v_and_b32_e32 v169, 0xffff0000, v76
	v_lshlrev_b32_e32 v170, 16, v77
	v_and_b32_e32 v171, 0xffff0000, v77
	v_lshlrev_b32_e32 v172, 16, v78
	v_and_b32_e32 v173, 0xffff0000, v78
	v_lshlrev_b32_e32 v174, 16, v79
	v_and_b32_e32 v175, 0xffff0000, v79
	v_pk_fma_f32 v[192:193], v[0:1], v[144:145], v[32:33]
	v_pk_fma_f32 v[192:193], v[8:9], v[152:153], v[192:193]
	v_pk_fma_f32 v[192:193], v[16:17], v[160:161], v[192:193]
	v_pk_fma_f32 v[192:193], v[24:25], v[168:169], v[192:193]
	v_pk_fma_f32 v[194:195], v[2:3], v[146:147], v[34:35]
	v_pk_fma_f32 v[194:195], v[10:11], v[154:155], v[194:195]
	v_pk_fma_f32 v[194:195], v[18:19], v[162:163], v[194:195]
	v_pk_fma_f32 v[194:195], v[26:27], v[170:171], v[194:195]
	v_pk_fma_f32 v[196:197], v[4:5], v[148:149], v[36:37]
	v_pk_fma_f32 v[196:197], v[12:13], v[156:157], v[196:197]
	v_pk_fma_f32 v[196:197], v[20:21], v[164:165], v[196:197]
	v_pk_fma_f32 v[196:197], v[28:29], v[172:173], v[196:197]
	v_pk_fma_f32 v[198:199], v[6:7], v[150:151], v[38:39]
	v_pk_fma_f32 v[198:199], v[14:15], v[158:159], v[198:199]
	v_pk_fma_f32 v[198:199], v[22:23], v[166:167], v[198:199]
	v_pk_fma_f32 v[198:199], v[30:31], v[174:175], v[198:199]
	v_mul_f32_e32 v216, 0xbfb8aa3b, v192
	v_mul_f32_e32 v217, 0xbfb8aa3b, v193
	v_mul_f32_e32 v218, 0xbfb8aa3b, v194
	v_mul_f32_e32 v219, 0xbfb8aa3b, v195
	v_mul_f32_e32 v220, 0xbfb8aa3b, v196
	v_mul_f32_e32 v221, 0xbfb8aa3b, v197
	v_mul_f32_e32 v222, 0xbfb8aa3b, v198
	v_mul_f32_e32 v223, 0xbfb8aa3b, v199
	v_exp_f32_e32 v216, v216
	v_exp_f32_e32 v217, v217
	v_exp_f32_e32 v218, v218
	v_exp_f32_e32 v219, v219
	v_exp_f32_e32 v220, v220
	v_exp_f32_e32 v221, v221
	v_exp_f32_e32 v222, v222
	v_exp_f32_e32 v223, v223
	v_add_f32_e32 v216, 1.0, v216
	v_add_f32_e32 v217, 1.0, v217
	v_add_f32_e32 v218, 1.0, v218
	v_add_f32_e32 v219, 1.0, v219
	v_add_f32_e32 v220, 1.0, v220
	v_add_f32_e32 v221, 1.0, v221
	v_add_f32_e32 v222, 1.0, v222
	v_add_f32_e32 v223, 1.0, v223
	v_rcp_f32_e32 v216, v216
	v_rcp_f32_e32 v217, v217
	v_rcp_f32_e32 v218, v218
	v_rcp_f32_e32 v219, v219
	v_rcp_f32_e32 v220, v220
	v_rcp_f32_e32 v221, v221
	v_rcp_f32_e32 v222, v222
	v_rcp_f32_e32 v223, v223
	s_nop 0
	v_pk_mul_f32 v[192:193], v[192:193], v[216:217]
	v_pk_mul_f32 v[194:195], v[194:195], v[218:219]
	v_pk_mul_f32 v[196:197], v[196:197], v[220:221]
	v_pk_mul_f32 v[198:199], v[198:199], v[222:223]
	v_cvt_pk_bf16_f32 v224, v192, v193
	v_cvt_pk_bf16_f32 v225, v194, v195
	v_cvt_pk_bf16_f32 v226, v196, v197
	v_cvt_pk_bf16_f32 v227, v198, v199
	global_store_dwordx4 v232, v[224:227], s[0:1]
	v_add_u32_e32 v232, s30, v232
	s_waitcnt vmcnt(7)
; __device__ __forceinline__ float siluf_(float v) { return v * __builtin_amdgcn_rcpf(1.f + __expf(-v)); }
; __device__ void phase_bcconv(const Params& p) {
;     ...
;     for (int rr = 0; rr < RB; ++rr) {
;       float cur[8];
;       i32x4 a = *(const i32x4*)(xbc + (size_t)(t0 + rr) * 6144 + 4096 + j8 * 8);
; #pragma unroll
;       for (int e = 0; e < 4; ++e) {
;         cur[2 * e] = __uint_as_float(((unsigned)a[e]) << 16);
;         cur[2 * e + 1] = __uint_as_float(((unsigned)a[e]) & 0xffff0000u);
;       }
;       float res[8];
; #pragma unroll
;       for (int e = 0; e < 8; ++e) {
;         float s_ = bs[e] + w[0][e] * win[0][e] + w[1][e] * win[1][e] + w[2][e] * win[2][e] + w[3][e] * cur[e];
;         res[e] = siluf_(s_);
;         win[0][e] = win[1][e]; win[1][e] = win[2][e]; win[2][e] = cur[e];
;       }
;       *(i32x4*)(bc + (size_t)(t0 + rr) * 2048 + j8 * 8) =
;           i32x4{(int)pack2(res[0], res[1]), (int)pack2(res[2], res[3]), (int)pack2(res[4], res[5]), (int)pack2(res[6], res[7])};
;     }
	v_lshlrev_b32_e32 v144, 16, v80
	v_and_b32_e32 v145, 0xffff0000, v80
	v_lshlrev_b32_e32 v146, 16, v81
	v_and_b32_e32 v147, 0xffff0000, v81
	v_lshlrev_b32_e32 v148, 16, v82
	v_and_b32_e32 v149, 0xffff0000, v82
	v_lshlrev_b32_e32 v150, 16, v83
	v_and_b32_e32 v151, 0xffff0000, v83
	v_pk_fma_f32 v[192:193], v[0:1], v[152:153], v[32:33]
	v_pk_fma_f32 v[192:193], v[8:9], v[160:161], v[192:193]
	v_pk_fma_f32 v[192:193], v[16:17], v[168:169], v[192:193]
	v_pk_fma_f32 v[192:193], v[24:25], v[144:145], v[192:193]
	v_pk_fma_f32 v[194:195], v[2:3], v[154:155], v[34:35]
	v_pk_fma_f32 v[194:195], v[10:11], v[162:163], v[194:195]
	v_pk_fma_f32 v[194:195], v[18:19], v[170:171], v[194:195]
	v_pk_fma_f32 v[194:195], v[26:27], v[146:147], v[194:195]
	v_pk_fma_f32 v[196:197], v[4:5], v[156:157], v[36:37]
	v_pk_fma_f32 v[196:197], v[12:13], v[164:165], v[196:197]
	v_pk_fma_f32 v[196:197], v[20:21], v[172:173], v[196:197]
	v_pk_fma_f32 v[196:197], v[28:29], v[148:149], v[196:197]
	v_pk_fma_f32 v[198:199], v[6:7], v[158:159], v[38:39]
	v_pk_fma_f32 v[198:199], v[14:15], v[166:167], v[198:199]
	v_pk_fma_f32 v[198:199], v[22:23], v[174:175], v[198:199]
	v_pk_fma_f32 v[198:199], v[30:31], v[150:151], v[198:199]
	v_mul_f32_e32 v216, 0xbfb8aa3b, v192
	v_mul_f32_e32 v217, 0xbfb8aa3b, v193
	v_mul_f32_e32 v218, 0xbfb8aa3b, v194
	v_mul_f32_e32 v219, 0xbfb8aa3b, v195
	v_mul_f32_e32 v220, 0xbfb8aa3b, v196
	v_mul_f32_e32 v221, 0xbfb8aa3b, v197
	v_mul_f32_e32 v222, 0xbfb8aa3b, v198
	v_mul_f32_e32 v223, 0xbfb8aa3b, v199
	v_exp_f32_e32 v216, v216
	v_exp_f32_e32 v217, v217
	v_exp_f32_e32 v218, v218
	v_exp_f32_e32 v219, v219
	v_exp_f32_e32 v220, v220
	v_exp_f32_e32 v221, v221
	v_exp_f32_e32 v222, v222
	v_exp_f32_e32 v223, v223
	v_add_f32_e32 v216, 1.0, v216
	v_add_f32_e32 v217, 1.0, v217
	v_add_f32_e32 v218, 1.0, v218
	v_add_f32_e32 v219, 1.0, v219
	v_add_f32_e32 v220, 1.0, v220
	v_add_f32_e32 v221, 1.0, v221
	v_add_f32_e32 v222, 1.0, v222
	v_add_f32_e32 v223, 1.0, v223
	v_rcp_f32_e32 v216, v216
	v_rcp_f32_e32 v217, v217
	v_rcp_f32_e32 v218, v218
	v_rcp_f32_e32 v219, v219
	v_rcp_f32_e32 v220, v220
	v_rcp_f32_e32 v221, v221
	v_rcp_f32_e32 v222, v222
	v_rcp_f32_e32 v223, v223
	s_nop 0
	v_pk_mul_f32 v[192:193], v[192:193], v[216:217]
	v_pk_mul_f32 v[194:195], v[194:195], v[218:219]
	v_pk_mul_f32 v[196:197], v[196:197], v[220:221]
	v_pk_mul_f32 v[198:199], v[198:199], v[222:223]
	v_cvt_pk_bf16_f32 v224, v192, v193
	v_cvt_pk_bf16_f32 v225, v194, v195
	v_cvt_pk_bf16_f32 v226, v196, v197
	v_cvt_pk_bf16_f32 v227, v198, v199
	global_store_dwordx4 v232, v[224:227], s[0:1]
	v_add_u32_e32 v232, s30, v232
	s_waitcnt vmcnt(7)
	v_lshlrev_b32_e32 v152, 16, v84
	v_and_b32_e32 v153, 0xffff0000, v84
	v_lshlrev_b32_e32 v154, 16, v85
	v_and_b32_e32 v155, 0xffff0000, v85
	v_lshlrev_b32_e32 v156, 16, v86
	v_and_b32_e32 v157, 0xffff0000, v86
	v_lshlrev_b32_e32 v158, 16, v87
	v_and_b32_e32 v159, 0xffff0000, v87
	v_pk_fma_f32 v[192:193], v[0:1], v[160:161], v[32:33]
	v_pk_fma_f32 v[192:193], v[8:9], v[168:169], v[192:193]
	v_pk_fma_f32 v[192:193], v[16:17], v[144:145], v[192:193]
	v_pk_fma_f32 v[192:193], v[24:25], v[152:153], v[192:193]
	v_pk_fma_f32 v[194:195], v[2:3], v[162:163], v[34:35]
	v_pk_fma_f32 v[194:195], v[10:11], v[170:171], v[194:195]
	v_pk_fma_f32 v[194:195], v[18:19], v[146:147], v[194:195]
	v_pk_fma_f32 v[194:195], v[26:27], v[154:155], v[194:195]
	v_pk_fma_f32 v[196:197], v[4:5], v[164:165], v[36:37]
	v_pk_fma_f32 v[196:197], v[12:13], v[172:173], v[196:197]
	v_pk_fma_f32 v[196:197], v[20:21], v[148:149], v[196:197]
	v_pk_fma_f32 v[196:197], v[28:29], v[156:157], v[196:197]
	v_pk_fma_f32 v[198:199], v[6:7], v[166:167], v[38:39]
	v_pk_fma_f32 v[198:199], v[14:15], v[174:175], v[198:199]
	v_pk_fma_f32 v[198:199], v[22:23], v[150:151], v[198:199]
	v_pk_fma_f32 v[198:199], v[30:31], v[158:159], v[198:199]
	v_mul_f32_e32 v216, 0xbfb8aa3b, v192
	v_mul_f32_e32 v217, 0xbfb8aa3b, v193
	v_mul_f32_e32 v218, 0xbfb8aa3b, v194
	v_mul_f32_e32 v219, 0xbfb8aa3b, v195
	v_mul_f32_e32 v220, 0xbfb8aa3b, v196
	v_mul_f32_e32 v221, 0xbfb8aa3b, v197
	v_mul_f32_e32 v222, 0xbfb8aa3b, v198
	v_mul_f32_e32 v223, 0xbfb8aa3b, v199
	v_exp_f32_e32 v216, v216
	v_exp_f32_e32 v217, v217
	v_exp_f32_e32 v218, v218
	v_exp_f32_e32 v219, v219
	v_exp_f32_e32 v220, v220
	v_exp_f32_e32 v221, v221
	v_exp_f32_e32 v222, v222
	v_exp_f32_e32 v223, v223
	v_add_f32_e32 v216, 1.0, v216
	v_add_f32_e32 v217, 1.0, v217
	v_add_f32_e32 v218, 1.0, v218
	v_add_f32_e32 v219, 1.0, v219
	v_add_f32_e32 v220, 1.0, v220
	v_add_f32_e32 v221, 1.0, v221
	v_add_f32_e32 v222, 1.0, v222
	v_add_f32_e32 v223, 1.0, v223
	v_rcp_f32_e32 v216, v216
	v_rcp_f32_e32 v217, v217
	v_rcp_f32_e32 v218, v218
	v_rcp_f32_e32 v219, v219
	v_rcp_f32_e32 v220, v220
	v_rcp_f32_e32 v221, v221
	v_rcp_f32_e32 v222, v222
	v_rcp_f32_e32 v223, v223
	s_nop 0
	v_pk_mul_f32 v[192:193], v[192:193], v[216:217]
	v_pk_mul_f32 v[194:195], v[194:195], v[218:219]
	v_pk_mul_f32 v[196:197], v[196:197], v[220:221]
	v_pk_mul_f32 v[198:199], v[198:199], v[222:223]
	v_cvt_pk_bf16_f32 v224, v192, v193
	v_cvt_pk_bf16_f32 v225, v194, v195
	v_cvt_pk_bf16_f32 v226, v196, v197
	v_cvt_pk_bf16_f32 v227, v198, v199
	global_store_dwordx4 v232, v[224:227], s[0:1]
	v_add_u32_e32 v232, s30, v232
	s_waitcnt vmcnt(7)
; __device__ __forceinline__ float siluf_(float v) { return v * __builtin_amdgcn_rcpf(1.f + __expf(-v)); }
; __device__ void phase_bcconv(const Params& p) {
;     ...
;     for (int rr = 0; rr < RB; ++rr) {
;       float cur[8];
;       i32x4 a = *(const i32x4*)(xbc + (size_t)(t0 + rr) * 6144 + 4096 + j8 * 8);
; #pragma unroll
;       for (int e = 0; e < 4; ++e) {
;         cur[2 * e] = __uint_as_float(((unsigned)a[e]) << 16);
;         cur[2 * e + 1] = __uint_as_float(((unsigned)a[e]) & 0xffff0000u);
;       }
;       float res[8];
; #pragma unroll
;       for (int e = 0; e < 8; ++e) {
;         float s_ = bs[e] + w[0][e] * win[0][e] + w[1][e] * win[1][e] + w[2][e] * win[2][e] + w[3][e] * cur[e];
;         res[e] = siluf_(s_);
;         win[0][e] = win[1][e]; win[1][e] = win[2][e]; win[2][e] = cur[e];
;       }
;       *(i32x4*)(bc + (size_t)(t0 + rr) * 2048 + j8 * 8) =
;           i32x4{(int)pack2(res[0], res[1]), (int)pack2(res[2], res[3]), (int)pack2(res[4], res[5]), (int)pack2(res[6], res[7])};
;     }
	v_lshlrev_b32_e32 v160, 16, v88
	v_and_b32_e32 v161, 0xffff0000, v88
	v_lshlrev_b32_e32 v162, 16, v89
	v_and_b32_e32 v163, 0xffff0000, v89
	v_lshlrev_b32_e32 v164, 16, v90
	v_and_b32_e32 v165, 0xffff0000, v90
	v_lshlrev_b32_e32 v166, 16, v91
	v_and_b32_e32 v167, 0xffff0000, v91
	v_pk_fma_f32 v[192:193], v[0:1], v[168:169], v[32:33]
	v_pk_fma_f32 v[192:193], v[8:9], v[144:145], v[192:193]
	v_pk_fma_f32 v[192:193], v[16:17], v[152:153], v[192:193]
	v_pk_fma_f32 v[192:193], v[24:25], v[160:161], v[192:193]
	v_pk_fma_f32 v[194:195], v[2:3], v[170:171], v[34:35]
	v_pk_fma_f32 v[194:195], v[10:11], v[146:147], v[194:195]
	v_pk_fma_f32 v[194:195], v[18:19], v[154:155], v[194:195]
	v_pk_fma_f32 v[194:195], v[26:27], v[162:163], v[194:195]
	v_pk_fma_f32 v[196:197], v[4:5], v[172:173], v[36:37]
	v_pk_fma_f32 v[196:197], v[12:13], v[148:149], v[196:197]
	v_pk_fma_f32 v[196:197], v[20:21], v[156:157], v[196:197]
	v_pk_fma_f32 v[196:197], v[28:29], v[164:165], v[196:197]
	v_pk_fma_f32 v[198:199], v[6:7], v[174:175], v[38:39]
	v_pk_fma_f32 v[198:199], v[14:15], v[150:151], v[198:199]
	v_pk_fma_f32 v[198:199], v[22:23], v[158:159], v[198:199]
	v_pk_fma_f32 v[198:199], v[30:31], v[166:167], v[198:199]
	v_mul_f32_e32 v216, 0xbfb8aa3b, v192
	v_mul_f32_e32 v217, 0xbfb8aa3b, v193
	v_mul_f32_e32 v218, 0xbfb8aa3b, v194
	v_mul_f32_e32 v219, 0xbfb8aa3b, v195
	v_mul_f32_e32 v220, 0xbfb8aa3b, v196
	v_mul_f32_e32 v221, 0xbfb8aa3b, v197
	v_mul_f32_e32 v222, 0xbfb8aa3b, v198
	v_mul_f32_e32 v223, 0xbfb8aa3b, v199
	v_exp_f32_e32 v216, v216
	v_exp_f32_e32 v217, v217
	v_exp_f32_e32 v218, v218
	v_exp_f32_e32 v219, v219
	v_exp_f32_e32 v220, v220
	v_exp_f32_e32 v221, v221
	v_exp_f32_e32 v222, v222
	v_exp_f32_e32 v223, v223
	v_add_f32_e32 v216, 1.0, v216
	v_add_f32_e32 v217, 1.0, v217
	v_add_f32_e32 v218, 1.0, v218
	v_add_f32_e32 v219, 1.0, v219
	v_add_f32_e32 v220, 1.0, v220
	v_add_f32_e32 v221, 1.0, v221
	v_add_f32_e32 v222, 1.0, v222
	v_add_f32_e32 v223, 1.0, v223
	v_rcp_f32_e32 v216, v216
	v_rcp_f32_e32 v217, v217
	v_rcp_f32_e32 v218, v218
	v_rcp_f32_e32 v219, v219
	v_rcp_f32_e32 v220, v220
	v_rcp_f32_e32 v221, v221
	v_rcp_f32_e32 v222, v222
	v_rcp_f32_e32 v223, v223
	s_nop 0
	v_pk_mul_f32 v[192:193], v[192:193], v[216:217]
	v_pk_mul_f32 v[194:195], v[194:195], v[218:219]
	v_pk_mul_f32 v[196:197], v[196:197], v[220:221]
	v_pk_mul_f32 v[198:199], v[198:199], v[222:223]
	v_cvt_pk_bf16_f32 v224, v192, v193
	v_cvt_pk_bf16_f32 v225, v194, v195
	v_cvt_pk_bf16_f32 v226, v196, v197
	v_cvt_pk_bf16_f32 v227, v198, v199
	global_store_dwordx4 v232, v[224:227], s[0:1]
	v_add_u32_e32 v232, s30, v232
	s_waitcnt vmcnt(7)
	v_lshlrev_b32_e32 v168, 16, v92
	v_and_b32_e32 v169, 0xffff0000, v92
	v_lshlrev_b32_e32 v170, 16, v93
	v_and_b32_e32 v171, 0xffff0000, v93
	v_lshlrev_b32_e32 v172, 16, v94
	v_and_b32_e32 v173, 0xffff0000, v94
	v_lshlrev_b32_e32 v174, 16, v95
	v_and_b32_e32 v175, 0xffff0000, v95
	v_pk_fma_f32 v[192:193], v[0:1], v[144:145], v[32:33]
	v_pk_fma_f32 v[192:193], v[8:9], v[152:153], v[192:193]
	v_pk_fma_f32 v[192:193], v[16:17], v[160:161], v[192:193]
	v_pk_fma_f32 v[192:193], v[24:25], v[168:169], v[192:193]
	v_pk_fma_f32 v[194:195], v[2:3], v[146:147], v[34:35]
	v_pk_fma_f32 v[194:195], v[10:11], v[154:155], v[194:195]
	v_pk_fma_f32 v[194:195], v[18:19], v[162:163], v[194:195]
	v_pk_fma_f32 v[194:195], v[26:27], v[170:171], v[194:195]
	v_pk_fma_f32 v[196:197], v[4:5], v[148:149], v[36:37]
	v_pk_fma_f32 v[196:197], v[12:13], v[156:157], v[196:197]
	v_pk_fma_f32 v[196:197], v[20:21], v[164:165], v[196:197]
	v_pk_fma_f32 v[196:197], v[28:29], v[172:173], v[196:197]
	v_pk_fma_f32 v[198:199], v[6:7], v[150:151], v[38:39]
	v_pk_fma_f32 v[198:199], v[14:15], v[158:159], v[198:199]
	v_pk_fma_f32 v[198:199], v[22:23], v[166:167], v[198:199]
	v_pk_fma_f32 v[198:199], v[30:31], v[174:175], v[198:199]
	v_mul_f32_e32 v216, 0xbfb8aa3b, v192
	v_mul_f32_e32 v217, 0xbfb8aa3b, v193
	v_mul_f32_e32 v218, 0xbfb8aa3b, v194
	v_mul_f32_e32 v219, 0xbfb8aa3b, v195
	v_mul_f32_e32 v220, 0xbfb8aa3b, v196
	v_mul_f32_e32 v221, 0xbfb8aa3b, v197
	v_mul_f32_e32 v222, 0xbfb8aa3b, v198
	v_mul_f32_e32 v223, 0xbfb8aa3b, v199
	v_exp_f32_e32 v216, v216
	v_exp_f32_e32 v217, v217
	v_exp_f32_e32 v218, v218
	v_exp_f32_e32 v219, v219
	v_exp_f32_e32 v220, v220
	v_exp_f32_e32 v221, v221
	v_exp_f32_e32 v222, v222
	v_exp_f32_e32 v223, v223
	v_add_f32_e32 v216, 1.0, v216
	v_add_f32_e32 v217, 1.0, v217
	v_add_f32_e32 v218, 1.0, v218
	v_add_f32_e32 v219, 1.0, v219
	v_add_f32_e32 v220, 1.0, v220
	v_add_f32_e32 v221, 1.0, v221
	v_add_f32_e32 v222, 1.0, v222
	v_add_f32_e32 v223, 1.0, v223
	v_rcp_f32_e32 v216, v216
	v_rcp_f32_e32 v217, v217
	v_rcp_f32_e32 v218, v218
	v_rcp_f32_e32 v219, v219
	v_rcp_f32_e32 v220, v220
	v_rcp_f32_e32 v221, v221
	v_rcp_f32_e32 v222, v222
	v_rcp_f32_e32 v223, v223
	s_nop 0
	v_pk_mul_f32 v[192:193], v[192:193], v[216:217]
	v_pk_mul_f32 v[194:195], v[194:195], v[218:219]
	v_pk_mul_f32 v[196:197], v[196:197], v[220:221]
	v_pk_mul_f32 v[198:199], v[198:199], v[222:223]
	v_cvt_pk_bf16_f32 v224, v192, v193
	v_cvt_pk_bf16_f32 v225, v194, v195
	v_cvt_pk_bf16_f32 v226, v196, v197
	v_cvt_pk_bf16_f32 v227, v198, v199
	global_store_dwordx4 v232, v[224:227], s[0:1]
	v_add_u32_e32 v232, s30, v232
	s_waitcnt vmcnt(7)
; __device__ __forceinline__ float siluf_(float v) { return v * __builtin_amdgcn_rcpf(1.f + __expf(-v)); }
; __device__ void phase_bcconv(const Params& p) {
;     ...
;     for (int rr = 0; rr < RB; ++rr) {
;       float cur[8];
;       i32x4 a = *(const i32x4*)(xbc + (size_t)(t0 + rr) * 6144 + 4096 + j8 * 8);
; #pragma unroll
;       for (int e = 0; e < 4; ++e) {
;         cur[2 * e] = __uint_as_float(((unsigned)a[e]) << 16);
;         cur[2 * e + 1] = __uint_as_float(((unsigned)a[e]) & 0xffff0000u);
;       }
;       float res[8];
; #pragma unroll
;       for (int e = 0; e < 8; ++e) {
;         float s_ = bs[e] + w[0][e] * win[0][e] + w[1][e] * win[1][e] + w[2][e] * win[2][e] + w[3][e] * cur[e];
;         res[e] = siluf_(s_);
;         win[0][e] = win[1][e]; win[1][e] = win[2][e]; win[2][e] = cur[e];
;       }
;       *(i32x4*)(bc + (size_t)(t0 + rr) * 2048 + j8 * 8) =
;           i32x4{(int)pack2(res[0], res[1]), (int)pack2(res[2], res[3]), (int)pack2(res[4], res[5]), (int)pack2(res[6], res[7])};
;     }
	v_lshlrev_b32_e32 v144, 16, v96
	v_and_b32_e32 v145, 0xffff0000, v96
	v_lshlrev_b32_e32 v146, 16, v97
	v_and_b32_e32 v147, 0xffff0000, v97
	v_lshlrev_b32_e32 v148, 16, v98
	v_and_b32_e32 v149, 0xffff0000, v98
	v_lshlrev_b32_e32 v150, 16, v99
	v_and_b32_e32 v151, 0xffff0000, v99
	v_pk_fma_f32 v[192:193], v[0:1], v[152:153], v[32:33]
	v_pk_fma_f32 v[192:193], v[8:9], v[160:161], v[192:193]
	v_pk_fma_f32 v[192:193], v[16:17], v[168:169], v[192:193]
	v_pk_fma_f32 v[192:193], v[24:25], v[144:145], v[192:193]
	v_pk_fma_f32 v[194:195], v[2:3], v[154:155], v[34:35]
	v_pk_fma_f32 v[194:195], v[10:11], v[162:163], v[194:195]
	v_pk_fma_f32 v[194:195], v[18:19], v[170:171], v[194:195]
	v_pk_fma_f32 v[194:195], v[26:27], v[146:147], v[194:195]
	v_pk_fma_f32 v[196:197], v[4:5], v[156:157], v[36:37]
	v_pk_fma_f32 v[196:197], v[12:13], v[164:165], v[196:197]
	v_pk_fma_f32 v[196:197], v[20:21], v[172:173], v[196:197]
	v_pk_fma_f32 v[196:197], v[28:29], v[148:149], v[196:197]
	v_pk_fma_f32 v[198:199], v[6:7], v[158:159], v[38:39]
	v_pk_fma_f32 v[198:199], v[14:15], v[166:167], v[198:199]
	v_pk_fma_f32 v[198:199], v[22:23], v[174:175], v[198:199]
	v_pk_fma_f32 v[198:199], v[30:31], v[150:151], v[198:199]
	v_mul_f32_e32 v216, 0xbfb8aa3b, v192
	v_mul_f32_e32 v217, 0xbfb8aa3b, v193
	v_mul_f32_e32 v218, 0xbfb8aa3b, v194
	v_mul_f32_e32 v219, 0xbfb8aa3b, v195
	v_mul_f32_e32 v220, 0xbfb8aa3b, v196
	v_mul_f32_e32 v221, 0xbfb8aa3b, v197
	v_mul_f32_e32 v222, 0xbfb8aa3b, v198
	v_mul_f32_e32 v223, 0xbfb8aa3b, v199
	v_exp_f32_e32 v216, v216
	v_exp_f32_e32 v217, v217
	v_exp_f32_e32 v218, v218
	v_exp_f32_e32 v219, v219
	v_exp_f32_e32 v220, v220
	v_exp_f32_e32 v221, v221
	v_exp_f32_e32 v222, v222
	v_exp_f32_e32 v223, v223
	v_add_f32_e32 v216, 1.0, v216
	v_add_f32_e32 v217, 1.0, v217
	v_add_f32_e32 v218, 1.0, v218
	v_add_f32_e32 v219, 1.0, v219
	v_add_f32_e32 v220, 1.0, v220
	v_add_f32_e32 v221, 1.0, v221
	v_add_f32_e32 v222, 1.0, v222
	v_add_f32_e32 v223, 1.0, v223
	v_rcp_f32_e32 v216, v216
	v_rcp_f32_e32 v217, v217
	v_rcp_f32_e32 v218, v218
	v_rcp_f32_e32 v219, v219
	v_rcp_f32_e32 v220, v220
	v_rcp_f32_e32 v221, v221
	v_rcp_f32_e32 v222, v222
	v_rcp_f32_e32 v223, v223
	s_nop 0
	v_pk_mul_f32 v[192:193], v[192:193], v[216:217]
	v_pk_mul_f32 v[194:195], v[194:195], v[218:219]
	v_pk_mul_f32 v[196:197], v[196:197], v[220:221]
	v_pk_mul_f32 v[198:199], v[198:199], v[222:223]
	v_cvt_pk_bf16_f32 v224, v192, v193
	v_cvt_pk_bf16_f32 v225, v194, v195
	v_cvt_pk_bf16_f32 v226, v196, v197
	v_cvt_pk_bf16_f32 v227, v198, v199
	global_store_dwordx4 v232, v[224:227], s[0:1]
	v_add_u32_e32 v232, s30, v232
	s_waitcnt vmcnt(7)
	v_lshlrev_b32_e32 v152, 16, v100
	v_and_b32_e32 v153, 0xffff0000, v100
	v_lshlrev_b32_e32 v154, 16, v101
	v_and_b32_e32 v155, 0xffff0000, v101
	v_lshlrev_b32_e32 v156, 16, v102
	v_and_b32_e32 v157, 0xffff0000, v102
	v_lshlrev_b32_e32 v158, 16, v103
	v_and_b32_e32 v159, 0xffff0000, v103
	v_pk_fma_f32 v[192:193], v[0:1], v[160:161], v[32:33]
	v_pk_fma_f32 v[192:193], v[8:9], v[168:169], v[192:193]
	v_pk_fma_f32 v[192:193], v[16:17], v[144:145], v[192:193]
	v_pk_fma_f32 v[192:193], v[24:25], v[152:153], v[192:193]
	v_pk_fma_f32 v[194:195], v[2:3], v[162:163], v[34:35]
	v_pk_fma_f32 v[194:195], v[10:11], v[170:171], v[194:195]
	v_pk_fma_f32 v[194:195], v[18:19], v[146:147], v[194:195]
	v_pk_fma_f32 v[194:195], v[26:27], v[154:155], v[194:195]
	v_pk_fma_f32 v[196:197], v[4:5], v[164:165], v[36:37]
	v_pk_fma_f32 v[196:197], v[12:13], v[172:173], v[196:197]
	v_pk_fma_f32 v[196:197], v[20:21], v[148:149], v[196:197]
	v_pk_fma_f32 v[196:197], v[28:29], v[156:157], v[196:197]
	v_pk_fma_f32 v[198:199], v[6:7], v[166:167], v[38:39]
	v_pk_fma_f32 v[198:199], v[14:15], v[174:175], v[198:199]
	v_pk_fma_f32 v[198:199], v[22:23], v[150:151], v[198:199]
	v_pk_fma_f32 v[198:199], v[30:31], v[158:159], v[198:199]
	v_mul_f32_e32 v216, 0xbfb8aa3b, v192
	v_mul_f32_e32 v217, 0xbfb8aa3b, v193
	v_mul_f32_e32 v218, 0xbfb8aa3b, v194
	v_mul_f32_e32 v219, 0xbfb8aa3b, v195
	v_mul_f32_e32 v220, 0xbfb8aa3b, v196
	v_mul_f32_e32 v221, 0xbfb8aa3b, v197
	v_mul_f32_e32 v222, 0xbfb8aa3b, v198
	v_mul_f32_e32 v223, 0xbfb8aa3b, v199
	v_exp_f32_e32 v216, v216
	v_exp_f32_e32 v217, v217
	v_exp_f32_e32 v218, v218
	v_exp_f32_e32 v219, v219
	v_exp_f32_e32 v220, v220
	v_exp_f32_e32 v221, v221
	v_exp_f32_e32 v222, v222
	v_exp_f32_e32 v223, v223
	v_add_f32_e32 v216, 1.0, v216
	v_add_f32_e32 v217, 1.0, v217
	v_add_f32_e32 v218, 1.0, v218
	v_add_f32_e32 v219, 1.0, v219
	v_add_f32_e32 v220, 1.0, v220
	v_add_f32_e32 v221, 1.0, v221
	v_add_f32_e32 v222, 1.0, v222
	v_add_f32_e32 v223, 1.0, v223
	v_rcp_f32_e32 v216, v216
	v_rcp_f32_e32 v217, v217
	v_rcp_f32_e32 v218, v218
	v_rcp_f32_e32 v219, v219
	v_rcp_f32_e32 v220, v220
	v_rcp_f32_e32 v221, v221
	v_rcp_f32_e32 v222, v222
	v_rcp_f32_e32 v223, v223
	s_nop 0
	v_pk_mul_f32 v[192:193], v[192:193], v[216:217]
	v_pk_mul_f32 v[194:195], v[194:195], v[218:219]
	v_pk_mul_f32 v[196:197], v[196:197], v[220:221]
	v_pk_mul_f32 v[198:199], v[198:199], v[222:223]
	v_cvt_pk_bf16_f32 v224, v192, v193
	v_cvt_pk_bf16_f32 v225, v194, v195
	v_cvt_pk_bf16_f32 v226, v196, v197
	v_cvt_pk_bf16_f32 v227, v198, v199
	global_store_dwordx4 v232, v[224:227], s[0:1]
	v_add_u32_e32 v232, s30, v232
	s_waitcnt vmcnt(7)
; __device__ __forceinline__ float siluf_(float v) { return v * __builtin_amdgcn_rcpf(1.f + __expf(-v)); }
; __device__ void phase_bcconv(const Params& p) {
;     ...
;   for (int it = blockIdx.x * NT + tid; it < total; it += gridDim.x * NT) {
;     ...
;     for (int rr = 0; rr < RB; ++rr) {
;       float cur[8];
;       i32x4 a = *(const i32x4*)(xbc + (size_t)(t0 + rr) * 6144 + 4096 + j8 * 8);
; #pragma unroll
;       for (int e = 0; e < 4; ++e) {
;         cur[2 * e] = __uint_as_float(((unsigned)a[e]) << 16);
;         cur[2 * e + 1] = __uint_as_float(((unsigned)a[e]) & 0xffff0000u);
;       }
;       float res[8];
; #pragma unroll
;       for (int e = 0; e < 8; ++e) {
;         float s_ = bs[e] + w[0][e] * win[0][e] + w[1][e] * win[1][e] + w[2][e] * win[2][e] + w[3][e] * cur[e];
;         res[e] = siluf_(s_);
;         win[0][e] = win[1][e]; win[1][e] = win[2][e]; win[2][e] = cur[e];
;       }
;       *(i32x4*)(bc + (size_t)(t0 + rr) * 2048 + j8 * 8) =
;           i32x4{(int)pack2(res[0], res[1]), (int)pack2(res[2], res[3]), (int)pack2(res[4], res[5]), (int)pack2(res[6], res[7])};
;     }
	v_lshlrev_b32_e32 v160, 16, v104
	v_and_b32_e32 v161, 0xffff0000, v104
	v_lshlrev_b32_e32 v162, 16, v105
	v_and_b32_e32 v163, 0xffff0000, v105
	v_lshlrev_b32_e32 v164, 16, v106
	v_and_b32_e32 v165, 0xffff0000, v106
	v_lshlrev_b32_e32 v166, 16, v107
	v_and_b32_e32 v167, 0xffff0000, v107
	v_pk_fma_f32 v[192:193], v[0:1], v[168:169], v[32:33]
	v_pk_fma_f32 v[192:193], v[8:9], v[144:145], v[192:193]
	v_pk_fma_f32 v[192:193], v[16:17], v[152:153], v[192:193]
	v_pk_fma_f32 v[192:193], v[24:25], v[160:161], v[192:193]
	v_pk_fma_f32 v[194:195], v[2:3], v[170:171], v[34:35]
	v_pk_fma_f32 v[194:195], v[10:11], v[146:147], v[194:195]
	v_pk_fma_f32 v[194:195], v[18:19], v[154:155], v[194:195]
	v_pk_fma_f32 v[194:195], v[26:27], v[162:163], v[194:195]
	v_pk_fma_f32 v[196:197], v[4:5], v[172:173], v[36:37]
	v_pk_fma_f32 v[196:197], v[12:13], v[148:149], v[196:197]
	v_pk_fma_f32 v[196:197], v[20:21], v[156:157], v[196:197]
	v_pk_fma_f32 v[196:197], v[28:29], v[164:165], v[196:197]
	v_pk_fma_f32 v[198:199], v[6:7], v[174:175], v[38:39]
	v_pk_fma_f32 v[198:199], v[14:15], v[150:151], v[198:199]
	v_pk_fma_f32 v[198:199], v[22:23], v[158:159], v[198:199]
	v_pk_fma_f32 v[198:199], v[30:31], v[166:167], v[198:199]
	v_mul_f32_e32 v216, 0xbfb8aa3b, v192
	v_mul_f32_e32 v217, 0xbfb8aa3b, v193
	v_mul_f32_e32 v218, 0xbfb8aa3b, v194
	v_mul_f32_e32 v219, 0xbfb8aa3b, v195
	v_mul_f32_e32 v220, 0xbfb8aa3b, v196
	v_mul_f32_e32 v221, 0xbfb8aa3b, v197
	v_mul_f32_e32 v222, 0xbfb8aa3b, v198
	v_mul_f32_e32 v223, 0xbfb8aa3b, v199
	v_exp_f32_e32 v216, v216
	v_exp_f32_e32 v217, v217
	v_exp_f32_e32 v218, v218
	v_exp_f32_e32 v219, v219
	v_exp_f32_e32 v220, v220
	v_exp_f32_e32 v221, v221
	v_exp_f32_e32 v222, v222
	v_exp_f32_e32 v223, v223
	v_add_f32_e32 v216, 1.0, v216
	v_add_f32_e32 v217, 1.0, v217
	v_add_f32_e32 v218, 1.0, v218
	v_add_f32_e32 v219, 1.0, v219
	v_add_f32_e32 v220, 1.0, v220
	v_add_f32_e32 v221, 1.0, v221
	v_add_f32_e32 v222, 1.0, v222
	v_add_f32_e32 v223, 1.0, v223
	v_rcp_f32_e32 v216, v216
	v_rcp_f32_e32 v217, v217
	v_rcp_f32_e32 v218, v218
	v_rcp_f32_e32 v219, v219
	v_rcp_f32_e32 v220, v220
	v_rcp_f32_e32 v221, v221
	v_rcp_f32_e32 v222, v222
	v_rcp_f32_e32 v223, v223
	s_nop 0
	v_pk_mul_f32 v[192:193], v[192:193], v[216:217]
	v_pk_mul_f32 v[194:195], v[194:195], v[218:219]
	v_pk_mul_f32 v[196:197], v[196:197], v[220:221]
	v_pk_mul_f32 v[198:199], v[198:199], v[222:223]
	v_cvt_pk_bf16_f32 v224, v192, v193
	v_cvt_pk_bf16_f32 v225, v194, v195
	v_cvt_pk_bf16_f32 v226, v196, v197
	v_cvt_pk_bf16_f32 v227, v198, v199
	global_store_dwordx4 v232, v[224:227], s[0:1]
	v_add_u32_e32 v235, s24, v235
	v_cmp_gt_i32_e32 vcc, s28, v235
	s_and_b64 exec, exec, vcc
	s_cbranch_execnz .Lbc_loop

; __device__ __forceinline__ void transpose_tile(const float* __restrict__ W, int K, int N, u16* __restrict__ WT, int k0,
;                                                int n0) {
;     ...
;   float4 v[8];
; #pragma unroll
;   for (int i = 0; i < 8; ++i) {
;     int idx = tid + i * NT, r = idx >> 6, c4 = idx & 63;
;     v[i] = (n0 + c4 * 4 < N) ? *(const float4*)(W + (size_t)(k0 + r) * N + n0 + c4 * 4) : float4{0.f, 0.f, 0.f, 0.f};
;   }
; __device__ void transpose_matrix(const float* W, int K, int N, u16* WT) {
;   int tk = K / 64, tn = (N + 255) / 256, total = tk * tn;
;   for (int t = blockIdx.x; t < total; t += gridDim.x) {
;     int kt = t % tk, nt_ = t / tk;
;     transpose_tile(W, K, N, WT, kt * 64, nt_ * 256);
.LBB0_1183:
	s_or_b64 exec, exec, s[6:7]
	v_lshrrev_b32_e32 v45, 6, v214
	v_and_b32_e32 v46, 63, v214
	v_lshrrev_b32_e32 v44, 1, v214
	v_and_b32_e32 v47, 1, v214
	v_lshlrev_b32_e32 v43, 2, v46
	v_mul_u32_u24_e32 v41, 0x410, v45
	v_lshl_add_u32 v41, v46, 4, v41
	v_mul_u32_u24_e32 v42, 0x8200, v47
	v_lshl_add_u32 v42, v44, 2, v42
	v_mov_b32_e32 v96, 0
	global_load_dwordx2 v[98:99], v96, s[50:51] offset:160
	s_waitcnt vmcnt(0)
	v_readfirstlane_b32 s28, v98
	v_readfirstlane_b32 s29, v99
	v_mov_b32_e32 v96, 0
	global_load_dwordx2 v[98:99], v96, s[50:51] offset:112
	s_mov_b32 s12, 0x2c00
	v_mul_lo_u32 v32, v45, s12
	v_add_lshl_u32 v32, v32, v43, 2
	s_mov_b32 s13, 0x58000
	v_add_u32_e32 v33, s13, v32
	v_add_u32_e32 v34, s13, v33
	v_add_u32_e32 v35, s13, v34
	v_add_u32_e32 v36, s13, v35
	v_add_u32_e32 v37, s13, v36
	v_add_u32_e32 v38, s13, v37
	v_add_u32_e32 v39, s13, v38
	v_mul_u32_u24_e32 v40, 0x1000, v44
	v_lshl_add_u32 v40, v47, 6, v40
	s_waitcnt vmcnt(0)
	v_readfirstlane_b32 s8, v98
	v_readfirstlane_b32 s9, v99
	s_add_u32 s10, s28, 0x1600000
	s_addc_u32 s11, s29, 0
	s_mov_b32 s3, s2
	s_cmp_lt_u32 s3, 1408
	s_cbranch_scc0 .Lt25a_end
	s_and_b32 s14, s3, 31
	s_lshr_b32 s15, s3, 5
	s_lshl_b32 s14, s14, 6
	s_lshl_b32 s24, s15, 8
	s_mul_i32 s16, s14, s12
	s_add_u32 s16, s16, s24
	s_lshl_b32 s16, s16, 2
	s_add_u32 s18, s8, s16
	s_addc_u32 s19, s9, 0
	s_mul_i32 s16, s24, 0x800
	s_add_u32 s16, s16, s14
	s_lshl_b32 s16, s16, 1
	s_add_u32 s20, s10, s16
	s_addc_u32 s21, s11, 0
	global_load_dwordx4 v[0:3], v32, s[18:19]
	global_load_dwordx4 v[4:7], v33, s[18:19]
	global_load_dwordx4 v[8:11], v34, s[18:19]
	global_load_dwordx4 v[12:15], v35, s[18:19]
	global_load_dwordx4 v[16:19], v36, s[18:19]
	global_load_dwordx4 v[20:23], v37, s[18:19]
	global_load_dwordx4 v[24:27], v38, s[18:19]
	global_load_dwordx4 v[28:31], v39, s[18:19]
	s_add_u32 s17, s3, s33
	s_cmp_lt_u32 s17, 1408
	s_cbranch_scc0 .Lt25a_loop
	s_and_b32 s14, s17, 31
	s_lshr_b32 s15, s17, 5
	s_lshl_b32 s14, s14, 6
	s_lshl_b32 s25, s15, 8
	s_mul_i32 s16, s14, s12
	s_add_u32 s16, s16, s25
	s_lshl_b32 s16, s16, 2
	s_add_u32 s18, s8, s16
	s_addc_u32 s19, s9, 0
	s_mul_i32 s16, s25, 0x800
	s_add_u32 s16, s16, s14
	s_lshl_b32 s16, s16, 1
	s_add_u32 s26, s10, s16
	s_addc_u32 s27, s11, 0
	global_load_dwordx4 v[100:103], v32, s[18:19]
	global_load_dwordx4 v[104:107], v33, s[18:19]
	global_load_dwordx4 v[108:111], v34, s[18:19]
	global_load_dwordx4 v[112:115], v35, s[18:19]
	global_load_dwordx4 v[116:119], v36, s[18:19]
	global_load_dwordx4 v[120:123], v37, s[18:19]
	global_load_dwordx4 v[124:127], v38, s[18:19]
	global_load_dwordx4 v[128:131], v39, s[18:19]
.Lt25a_loop:
	s_add_u32 s17, s3, s33
	s_cmp_lt_u32 s17, 1408
	s_cbranch_scc1 .Lt25a_Aw8
	s_waitcnt vmcnt(0)
	s_branch .Lt25a_Ago

; __device__ __forceinline__ void transpose_tile(const float* __restrict__ W, int K, int N, u16* __restrict__ WT, int k0,
;                                                int n0) {
;   float* ts = (float*)g_shm;
;   const int tid = tid_();
;   float4 v[8];
; #pragma unroll
;   for (int i = 0; i < 8; ++i) {
;     int idx = tid + i * NT, r = idx >> 6, c4 = idx & 63;
;     v[i] = (n0 + c4 * 4 < N) ? *(const float4*)(W + (size_t)(k0 + r) * N + n0 + c4 * 4) : float4{0.f, 0.f, 0.f, 0.f};
;   }
;   __syncthreads();
; #pragma unroll
;   for (int i = 0; i < 8; ++i) {
;     int idx = tid + i * NT, r = idx >> 6, c4 = idx & 63;
;     float* d = ts + r * 257 + c4 * 4;
;     d[0] = v[i].x; d[1] = v[i].y; d[2] = v[i].z; d[3] = v[i].w;
;   }
;   __syncthreads();
;   if (n0 + (tid >> 1) < N) {
;     int n = tid >> 1, kh = tid & 1;
;     u16* dst = WT + (size_t)(n0 + n) * K + k0 + kh * 32;
; #pragma unroll
;     for (int q = 0; q < 4; ++q) {
;       unsigned pk[4];
; #pragma unroll
;       for (int i = 0; i < 4; ++i)
;         pk[i] = pack2(ts[(kh * 32 + q * 8 + 2 * i) * 257 + n], ts[(kh * 32 + q * 8 + 2 * i + 1) * 257 + n]);
;       *(i32x4*)(dst + q * 8) = i32x4{(int)pk[0], (int)pk[1], (int)pk[2], (int)pk[3]};
;     }
;   }
.Lt25a_Ago:
	s_barrier
	ds_write_b128 v41, v[0:3]
	ds_write_b128 v41, v[4:7] offset:8320
	ds_write_b128 v41, v[8:11] offset:16640
	ds_write_b128 v41, v[12:15] offset:24960
	ds_write_b128 v41, v[16:19] offset:33280
	ds_write_b128 v41, v[20:23] offset:41600
	ds_write_b128 v41, v[24:27] offset:49920
	ds_write_b128 v41, v[28:31] offset:58240
	s_waitcnt lgkmcnt(0)
	s_barrier
	ds_read_b32 v48, v42
	ds_read_b32 v49, v42 offset:1040
	ds_read_b32 v50, v42 offset:2080
	ds_read_b32 v51, v42 offset:3120
	ds_read_b32 v52, v42 offset:4160
	ds_read_b32 v53, v42 offset:5200
	ds_read_b32 v54, v42 offset:6240
	ds_read_b32 v55, v42 offset:7280
	ds_read_b32 v56, v42 offset:8320
	ds_read_b32 v57, v42 offset:9360
	ds_read_b32 v58, v42 offset:10400
	ds_read_b32 v59, v42 offset:11440
	ds_read_b32 v60, v42 offset:12480
	ds_read_b32 v61, v42 offset:13520
	ds_read_b32 v62, v42 offset:14560
	ds_read_b32 v63, v42 offset:15600
	s_waitcnt lgkmcnt(8)
	v_cvt_pk_bf16_f32 v80, v48, v49
	v_cvt_pk_bf16_f32 v81, v50, v51
	v_cvt_pk_bf16_f32 v82, v52, v53
	v_cvt_pk_bf16_f32 v83, v54, v55
	global_store_dwordx4 v40, v[80:83], s[20:21]
	ds_read_b32 v64, v42 offset:16640
	ds_read_b32 v65, v42 offset:17680
	ds_read_b32 v66, v42 offset:18720
	ds_read_b32 v67, v42 offset:19760
	ds_read_b32 v68, v42 offset:20800
	ds_read_b32 v69, v42 offset:21840
	ds_read_b32 v70, v42 offset:22880
	ds_read_b32 v71, v42 offset:23920
	s_waitcnt lgkmcnt(8)
	v_cvt_pk_bf16_f32 v84, v56, v57
	v_cvt_pk_bf16_f32 v85, v58, v59
	v_cvt_pk_bf16_f32 v86, v60, v61
	v_cvt_pk_bf16_f32 v87, v62, v63
	global_store_dwordx4 v40, v[84:87], s[20:21] offset:16
	ds_read_b32 v72, v42 offset:24960
	ds_read_b32 v73, v42 offset:26000
	ds_read_b32 v74, v42 offset:27040
	ds_read_b32 v75, v42 offset:28080
	ds_read_b32 v76, v42 offset:29120
	ds_read_b32 v77, v42 offset:30160
	ds_read_b32 v78, v42 offset:31200
	ds_read_b32 v79, v42 offset:32240
	s_waitcnt lgkmcnt(8)
	v_cvt_pk_bf16_f32 v88, v64, v65
	v_cvt_pk_bf16_f32 v89, v66, v67
	v_cvt_pk_bf16_f32 v90, v68, v69
	v_cvt_pk_bf16_f32 v91, v70, v71
	global_store_dwordx4 v40, v[88:91], s[20:21] offset:32
	s_waitcnt lgkmcnt(0)
	v_cvt_pk_bf16_f32 v92, v72, v73
	v_cvt_pk_bf16_f32 v93, v74, v75
	v_cvt_pk_bf16_f32 v94, v76, v77
	v_cvt_pk_bf16_f32 v95, v78, v79
	global_store_dwordx4 v40, v[92:95], s[20:21] offset:48
	s_add_u32 s17, s17, s33
	s_cmp_lt_u32 s17, 1408
	s_cbranch_scc0 .Lt25a_Anl
	s_and_b32 s14, s17, 31
	s_lshr_b32 s15, s17, 5
	s_lshl_b32 s14, s14, 6
	s_lshl_b32 s24, s15, 8
	s_mul_i32 s16, s14, s12
	s_add_u32 s16, s16, s24
	s_lshl_b32 s16, s16, 2
	s_add_u32 s18, s8, s16
	s_addc_u32 s19, s9, 0
	s_mul_i32 s16, s24, 0x800
	s_add_u32 s16, s16, s14
	s_lshl_b32 s16, s16, 1
	s_add_u32 s20, s10, s16
	s_addc_u32 s21, s11, 0
	global_load_dwordx4 v[0:3], v32, s[18:19]
	global_load_dwordx4 v[4:7], v33, s[18:19]
	global_load_dwordx4 v[8:11], v34, s[18:19]
	global_load_dwordx4 v[12:15], v35, s[18:19]
	global_load_dwordx4 v[16:19], v36, s[18:19]
	global_load_dwordx4 v[20:23], v37, s[18:19]
	global_load_dwordx4 v[24:27], v38, s[18:19]
	global_load_dwordx4 v[28:31], v39, s[18:19]
.Lt25a_Anl:
	s_add_u32 s3, s3, s33
	s_cmp_lt_u32 s3, 1408
	s_cbranch_scc0 .Lt25a_end
	s_add_u32 s17, s3, s33
	s_cmp_lt_u32 s17, 1408
	s_cbranch_scc1 .Lt25a_Bw8
	s_waitcnt vmcnt(0)
	s_branch .Lt25a_Bgo

; __device__ __forceinline__ void transpose_tile(const float* __restrict__ W, int K, int N, u16* __restrict__ WT, int k0,
;                                                int n0) {
;     ...
;   __syncthreads();
; #pragma unroll
;   for (int i = 0; i < 8; ++i) {
;     int idx = tid + i * NT, r = idx >> 6, c4 = idx & 63;
;     float* d = ts + r * 257 + c4 * 4;
;     d[0] = v[i].x; d[1] = v[i].y; d[2] = v[i].z; d[3] = v[i].w;
;   }
;   __syncthreads();
;   if (n0 + (tid >> 1) < N) {
;     int n = tid >> 1, kh = tid & 1;
;     u16* dst = WT + (size_t)(n0 + n) * K + k0 + kh * 32;
; #pragma unroll
;     for (int q = 0; q < 4; ++q) {
;       unsigned pk[4];
; #pragma unroll
;       for (int i = 0; i < 4; ++i)
;         pk[i] = pack2(ts[(kh * 32 + q * 8 + 2 * i) * 257 + n], ts[(kh * 32 + q * 8 + 2 * i + 1) * 257 + n]);
;       *(i32x4*)(dst + q * 8) = i32x4{(int)pk[0], (int)pk[1], (int)pk[2], (int)pk[3]};
;     }
;   }
; __device__ void phase2c(const Params& p) {
;     ...
;   transpose_matrix(p.w_down, DFF, 2048, (u16*)(p.ws + OFF_WDOWN));
.Lt25a_Bgo:
	s_barrier
	ds_write_b128 v41, v[100:103]
	ds_write_b128 v41, v[104:107] offset:8320
	ds_write_b128 v41, v[108:111] offset:16640
	ds_write_b128 v41, v[112:115] offset:24960
	ds_write_b128 v41, v[116:119] offset:33280
	ds_write_b128 v41, v[120:123] offset:41600
	ds_write_b128 v41, v[124:127] offset:49920
	ds_write_b128 v41, v[128:131] offset:58240
	s_waitcnt lgkmcnt(0)
	s_barrier
	ds_read_b32 v48, v42
	ds_read_b32 v49, v42 offset:1040
	ds_read_b32 v50, v42 offset:2080
	ds_read_b32 v51, v42 offset:3120
	ds_read_b32 v52, v42 offset:4160
	ds_read_b32 v53, v42 offset:5200
	ds_read_b32 v54, v42 offset:6240
	ds_read_b32 v55, v42 offset:7280
	ds_read_b32 v56, v42 offset:8320
	ds_read_b32 v57, v42 offset:9360
	ds_read_b32 v58, v42 offset:10400
	ds_read_b32 v59, v42 offset:11440
	ds_read_b32 v60, v42 offset:12480
	ds_read_b32 v61, v42 offset:13520
	ds_read_b32 v62, v42 offset:14560
	ds_read_b32 v63, v42 offset:15600
	s_waitcnt lgkmcnt(8)
	v_cvt_pk_bf16_f32 v80, v48, v49
	v_cvt_pk_bf16_f32 v81, v50, v51
	v_cvt_pk_bf16_f32 v82, v52, v53
	v_cvt_pk_bf16_f32 v83, v54, v55
	global_store_dwordx4 v40, v[80:83], s[26:27]
	ds_read_b32 v64, v42 offset:16640
	ds_read_b32 v65, v42 offset:17680
	ds_read_b32 v66, v42 offset:18720
	ds_read_b32 v67, v42 offset:19760
	ds_read_b32 v68, v42 offset:20800
	ds_read_b32 v69, v42 offset:21840
	ds_read_b32 v70, v42 offset:22880
	ds_read_b32 v71, v42 offset:23920
	s_waitcnt lgkmcnt(8)
	v_cvt_pk_bf16_f32 v84, v56, v57
	v_cvt_pk_bf16_f32 v85, v58, v59
	v_cvt_pk_bf16_f32 v86, v60, v61
	v_cvt_pk_bf16_f32 v87, v62, v63
	global_store_dwordx4 v40, v[84:87], s[26:27] offset:16
	ds_read_b32 v72, v42 offset:24960
	ds_read_b32 v73, v42 offset:26000
	ds_read_b32 v74, v42 offset:27040
	ds_read_b32 v75, v42 offset:28080
	ds_read_b32 v76, v42 offset:29120
	ds_read_b32 v77, v42 offset:30160
	ds_read_b32 v78, v42 offset:31200
	ds_read_b32 v79, v42 offset:32240
	s_waitcnt lgkmcnt(8)
	v_cvt_pk_bf16_f32 v88, v64, v65
	v_cvt_pk_bf16_f32 v89, v66, v67
	v_cvt_pk_bf16_f32 v90, v68, v69
	v_cvt_pk_bf16_f32 v91, v70, v71
	global_store_dwordx4 v40, v[88:91], s[26:27] offset:32
	s_waitcnt lgkmcnt(0)
	v_cvt_pk_bf16_f32 v92, v72, v73
	v_cvt_pk_bf16_f32 v93, v74, v75
	v_cvt_pk_bf16_f32 v94, v76, v77
	v_cvt_pk_bf16_f32 v95, v78, v79
	global_store_dwordx4 v40, v[92:95], s[26:27] offset:48
	s_add_u32 s17, s17, s33
	s_cmp_lt_u32 s17, 1408
	s_cbranch_scc0 .Lt25a_Bnl
	s_and_b32 s14, s17, 31
	s_lshr_b32 s15, s17, 5
	s_lshl_b32 s14, s14, 6
	s_lshl_b32 s25, s15, 8
	s_mul_i32 s16, s14, s12
	s_add_u32 s16, s16, s25
	s_lshl_b32 s16, s16, 2
	s_add_u32 s18, s8, s16
	s_addc_u32 s19, s9, 0
	s_mul_i32 s16, s25, 0x800
	s_add_u32 s16, s16, s14
	s_lshl_b32 s16, s16, 1
	s_add_u32 s26, s10, s16
	s_addc_u32 s27, s11, 0
	global_load_dwordx4 v[100:103], v32, s[18:19]
	global_load_dwordx4 v[104:107], v33, s[18:19]
	global_load_dwordx4 v[108:111], v34, s[18:19]
	global_load_dwordx4 v[112:115], v35, s[18:19]
	global_load_dwordx4 v[116:119], v36, s[18:19]
	global_load_dwordx4 v[120:123], v37, s[18:19]
	global_load_dwordx4 v[124:127], v38, s[18:19]
	global_load_dwordx4 v[128:131], v39, s[18:19]
.Lt25a_Bnl:
	s_add_u32 s3, s3, s33
	s_cmp_lt_u32 s3, 1408
	s_cbranch_scc1 .Lt25a_loop
.Lt25a_end:
	v_mov_b32_e32 v96, 0
	global_load_dwordx2 v[98:99], v96, s[50:51] offset:136
	s_mov_b32 s12, 0x800
	v_mul_lo_u32 v32, v45, s12
	v_add_lshl_u32 v32, v32, v43, 2
	s_mov_b32 s13, 0x10000
	v_add_u32_e32 v33, s13, v32
	v_add_u32_e32 v34, s13, v33
	v_add_u32_e32 v35, s13, v34
	v_add_u32_e32 v36, s13, v35
	v_add_u32_e32 v37, s13, v36
	v_add_u32_e32 v38, s13, v37
	v_add_u32_e32 v39, s13, v38
	v_mul_u32_u24_e32 v40, 0x2c00, v44
	v_lshl_add_u32 v40, v47, 6, v40
	s_waitcnt vmcnt(0)
	v_readfirstlane_b32 s8, v98
	v_readfirstlane_b32 s9, v99
	s_add_u32 s10, s28, 0x0
	s_addc_u32 s11, s29, 0
	s_mov_b32 s3, s2
	s_cmp_lt_u32 s3, 704
	s_cbranch_scc0 .Lt25b_end
	s_mul_hi_u32 s15, s3, 0x2e8ba2f
	s_mul_i32 s14, s15, 88
	s_sub_u32 s14, s3, s14
	s_lshl_b32 s14, s14, 6
	s_lshl_b32 s24, s15, 8
	s_mul_i32 s16, s14, s12
	s_add_u32 s16, s16, s24
	s_lshl_b32 s16, s16, 2
	s_add_u32 s18, s8, s16
	s_addc_u32 s19, s9, 0
	s_mul_i32 s16, s24, 0x1600
	s_add_u32 s16, s16, s14
	s_lshl_b32 s16, s16, 1
	s_add_u32 s20, s10, s16
	s_addc_u32 s21, s11, 0
	global_load_dwordx4 v[0:3], v32, s[18:19]
	global_load_dwordx4 v[4:7], v33, s[18:19]
	global_load_dwordx4 v[8:11], v34, s[18:19]
	global_load_dwordx4 v[12:15], v35, s[18:19]
	global_load_dwordx4 v[16:19], v36, s[18:19]
	global_load_dwordx4 v[20:23], v37, s[18:19]
	global_load_dwordx4 v[24:27], v38, s[18:19]
	global_load_dwordx4 v[28:31], v39, s[18:19]
	s_add_u32 s17, s3, s33
	s_cmp_lt_u32 s17, 704
	s_cbranch_scc0 .Lt25b_loop
	s_mul_hi_u32 s15, s17, 0x2e8ba2f
	s_mul_i32 s14, s15, 88
	s_sub_u32 s14, s17, s14
	s_lshl_b32 s14, s14, 6
	s_lshl_b32 s25, s15, 8
	s_mul_i32 s16, s14, s12
	s_add_u32 s16, s16, s25
	s_lshl_b32 s16, s16, 2
	s_add_u32 s18, s8, s16
	s_addc_u32 s19, s9, 0
	s_mul_i32 s16, s25, 0x1600
	s_add_u32 s16, s16, s14
	s_lshl_b32 s16, s16, 1
	s_add_u32 s26, s10, s16
	s_addc_u32 s27, s11, 0
	global_load_dwordx4 v[100:103], v32, s[18:19]
	global_load_dwordx4 v[104:107], v33, s[18:19]
	global_load_dwordx4 v[108:111], v34, s[18:19]
	global_load_dwordx4 v[112:115], v35, s[18:19]
	global_load_dwordx4 v[116:119], v36, s[18:19]
	global_load_dwordx4 v[120:123], v37, s[18:19]
	global_load_dwordx4 v[124:127], v38, s[18:19]
	global_load_dwordx4 v[128:131], v39, s[18:19]
.Lt25b_loop:
	s_add_u32 s17, s3, s33
	s_cmp_lt_u32 s17, 704
	s_cbranch_scc1 .Lt25b_Aw8
	s_waitcnt vmcnt(0)
	s_branch .Lt25b_Ago

; __device__ __forceinline__ void transpose_tile(const float* __restrict__ W, int K, int N, u16* __restrict__ WT, int k0,
;                                                int n0) {
;   float* ts = (float*)g_shm;
;   const int tid = tid_();
;   float4 v[8];
; #pragma unroll
;   for (int i = 0; i < 8; ++i) {
;     int idx = tid + i * NT, r = idx >> 6, c4 = idx & 63;
;     v[i] = (n0 + c4 * 4 < N) ? *(const float4*)(W + (size_t)(k0 + r) * N + n0 + c4 * 4) : float4{0.f, 0.f, 0.f, 0.f};
;   }
;   __syncthreads();
; #pragma unroll
;   for (int i = 0; i < 8; ++i) {
;     int idx = tid + i * NT, r = idx >> 6, c4 = idx & 63;
;     float* d = ts + r * 257 + c4 * 4;
;     d[0] = v[i].x; d[1] = v[i].y; d[2] = v[i].z; d[3] = v[i].w;
;   }
;   __syncthreads();
;   if (n0 + (tid >> 1) < N) {
;     int n = tid >> 1, kh = tid & 1;
;     u16* dst = WT + (size_t)(n0 + n) * K + k0 + kh * 32;
; #pragma unroll
;     for (int q = 0; q < 4; ++q) {
;       unsigned pk[4];
; #pragma unroll
;       for (int i = 0; i < 4; ++i)
;         pk[i] = pack2(ts[(kh * 32 + q * 8 + 2 * i) * 257 + n], ts[(kh * 32 + q * 8 + 2 * i + 1) * 257 + n]);
;       *(i32x4*)(dst + q * 8) = i32x4{(int)pk[0], (int)pk[1], (int)pk[2], (int)pk[3]};
;     }
;   }
.Lt25b_Ago:
	s_barrier
	ds_write_b128 v41, v[0:3]
	ds_write_b128 v41, v[4:7] offset:8320
	ds_write_b128 v41, v[8:11] offset:16640
	ds_write_b128 v41, v[12:15] offset:24960
	ds_write_b128 v41, v[16:19] offset:33280
	ds_write_b128 v41, v[20:23] offset:41600
	ds_write_b128 v41, v[24:27] offset:49920
	ds_write_b128 v41, v[28:31] offset:58240
	s_waitcnt lgkmcnt(0)
	s_barrier
	ds_read_b32 v48, v42
	ds_read_b32 v49, v42 offset:1040
	ds_read_b32 v50, v42 offset:2080
	ds_read_b32 v51, v42 offset:3120
	ds_read_b32 v52, v42 offset:4160
	ds_read_b32 v53, v42 offset:5200
	ds_read_b32 v54, v42 offset:6240
	ds_read_b32 v55, v42 offset:7280
	ds_read_b32 v56, v42 offset:8320
	ds_read_b32 v57, v42 offset:9360
	ds_read_b32 v58, v42 offset:10400
	ds_read_b32 v59, v42 offset:11440
	ds_read_b32 v60, v42 offset:12480
	ds_read_b32 v61, v42 offset:13520
	ds_read_b32 v62, v42 offset:14560
	ds_read_b32 v63, v42 offset:15600
	s_waitcnt lgkmcnt(8)
	v_cvt_pk_bf16_f32 v80, v48, v49
	v_cvt_pk_bf16_f32 v81, v50, v51
	v_cvt_pk_bf16_f32 v82, v52, v53
	v_cvt_pk_bf16_f32 v83, v54, v55
	global_store_dwordx4 v40, v[80:83], s[20:21]
	ds_read_b32 v64, v42 offset:16640
	ds_read_b32 v65, v42 offset:17680
	ds_read_b32 v66, v42 offset:18720
	ds_read_b32 v67, v42 offset:19760
	ds_read_b32 v68, v42 offset:20800
	ds_read_b32 v69, v42 offset:21840
	ds_read_b32 v70, v42 offset:22880
	ds_read_b32 v71, v42 offset:23920
	s_waitcnt lgkmcnt(8)
	v_cvt_pk_bf16_f32 v84, v56, v57
	v_cvt_pk_bf16_f32 v85, v58, v59
	v_cvt_pk_bf16_f32 v86, v60, v61
	v_cvt_pk_bf16_f32 v87, v62, v63
	global_store_dwordx4 v40, v[84:87], s[20:21] offset:16
	ds_read_b32 v72, v42 offset:24960
	ds_read_b32 v73, v42 offset:26000
	ds_read_b32 v74, v42 offset:27040
	ds_read_b32 v75, v42 offset:28080
	ds_read_b32 v76, v42 offset:29120
	ds_read_b32 v77, v42 offset:30160
	ds_read_b32 v78, v42 offset:31200
	ds_read_b32 v79, v42 offset:32240
	s_waitcnt lgkmcnt(8)
	v_cvt_pk_bf16_f32 v88, v64, v65
	v_cvt_pk_bf16_f32 v89, v66, v67
	v_cvt_pk_bf16_f32 v90, v68, v69
	v_cvt_pk_bf16_f32 v91, v70, v71
	global_store_dwordx4 v40, v[88:91], s[20:21] offset:32
	s_waitcnt lgkmcnt(0)
	v_cvt_pk_bf16_f32 v92, v72, v73
	v_cvt_pk_bf16_f32 v93, v74, v75
	v_cvt_pk_bf16_f32 v94, v76, v77
	v_cvt_pk_bf16_f32 v95, v78, v79
	global_store_dwordx4 v40, v[92:95], s[20:21] offset:48
	s_add_u32 s17, s17, s33
	s_cmp_lt_u32 s17, 704
	s_cbranch_scc0 .Lt25b_Anl
	s_mul_hi_u32 s15, s17, 0x2e8ba2f
	s_mul_i32 s14, s15, 88
	s_sub_u32 s14, s17, s14
	s_lshl_b32 s14, s14, 6
	s_lshl_b32 s24, s15, 8
	s_mul_i32 s16, s14, s12
	s_add_u32 s16, s16, s24
	s_lshl_b32 s16, s16, 2
	s_add_u32 s18, s8, s16
	s_addc_u32 s19, s9, 0
	s_mul_i32 s16, s24, 0x1600
	s_add_u32 s16, s16, s14
	s_lshl_b32 s16, s16, 1
	s_add_u32 s20, s10, s16
	s_addc_u32 s21, s11, 0
	global_load_dwordx4 v[0:3], v32, s[18:19]
	global_load_dwordx4 v[4:7], v33, s[18:19]
	global_load_dwordx4 v[8:11], v34, s[18:19]
	global_load_dwordx4 v[12:15], v35, s[18:19]
	global_load_dwordx4 v[16:19], v36, s[18:19]
	global_load_dwordx4 v[20:23], v37, s[18:19]
	global_load_dwordx4 v[24:27], v38, s[18:19]
	global_load_dwordx4 v[28:31], v39, s[18:19]
.Lt25b_Anl:
	s_add_u32 s3, s3, s33
	s_cmp_lt_u32 s3, 704
	s_cbranch_scc0 .Lt25b_end
	s_add_u32 s17, s3, s33
	s_cmp_lt_u32 s17, 704
	s_cbranch_scc1 .Lt25b_Bw8
	s_waitcnt vmcnt(0)
	s_branch .Lt25b_Bgo

; __device__ __forceinline__ unsigned xb_ld(unsigned* p) { return __hip_atomic_load(p, __ATOMIC_RELAXED, __HIP_MEMORY_SCOPE_AGENT); }
; __device__ __forceinline__ unsigned xb_xcc_id() { return (unsigned)__builtin_amdgcn_s_getreg((3 << 11) | 20) & 0xFu; }
; __device__ __forceinline__ void transpose_tile(const float* __restrict__ W, int K, int N, u16* __restrict__ WT, int k0,
;                                                int n0) {
;     ...
;   __syncthreads();
; #pragma unroll
;   for (int i = 0; i < 8; ++i) {
;     int idx = tid + i * NT, r = idx >> 6, c4 = idx & 63;
;     float* d = ts + r * 257 + c4 * 4;
;     d[0] = v[i].x; d[1] = v[i].y; d[2] = v[i].z; d[3] = v[i].w;
;   }
;   __syncthreads();
;   if (n0 + (tid >> 1) < N) {
;     int n = tid >> 1, kh = tid & 1;
;     u16* dst = WT + (size_t)(n0 + n) * K + k0 + kh * 32;
; #pragma unroll
;     for (int q = 0; q < 4; ++q) {
;       unsigned pk[4];
; #pragma unroll
;       for (int i = 0; i < 4; ++i)
;         pk[i] = pack2(ts[(kh * 32 + q * 8 + 2 * i) * 257 + n], ts[(kh * 32 + q * 8 + 2 * i + 1) * 257 + n]);
;       *(i32x4*)(dst + q * 8) = i32x4{(int)pk[0], (int)pk[1], (int)pk[2], (int)pk[3]};
;     }
;   }
; __device__ __forceinline__ void flat_barrier(unsigned* bar) {
;   asm volatile("s_waitcnt vmcnt(0)" ::: "memory");
;   __syncthreads();
;   if (threadIdx.x == 0) {
;     const unsigned bx = xb_xcc_id();
;     unsigned nloc, nx, tot, tries = 0;
;     do {
;       nx = 0; tot = 0;
;       for (unsigned j = 0; j < 16; ++j) { const unsigned cj = xb_ld(&bar[XB_XCNT(j)]); nx += (cj > 0u); tot += cj; }
;       nloc = xb_ld(&bar[XB_XCNT(bx)]);
.Lt25b_Bgo:
	s_barrier
	ds_write_b128 v41, v[100:103]
	ds_write_b128 v41, v[104:107] offset:8320
	ds_write_b128 v41, v[108:111] offset:16640
	ds_write_b128 v41, v[112:115] offset:24960
	ds_write_b128 v41, v[116:119] offset:33280
	ds_write_b128 v41, v[120:123] offset:41600
	ds_write_b128 v41, v[124:127] offset:49920
	ds_write_b128 v41, v[128:131] offset:58240
	s_waitcnt lgkmcnt(0)
	s_barrier
	ds_read_b32 v48, v42
	ds_read_b32 v49, v42 offset:1040
	ds_read_b32 v50, v42 offset:2080
	ds_read_b32 v51, v42 offset:3120
	ds_read_b32 v52, v42 offset:4160
	ds_read_b32 v53, v42 offset:5200
	ds_read_b32 v54, v42 offset:6240
	ds_read_b32 v55, v42 offset:7280
	ds_read_b32 v56, v42 offset:8320
	ds_read_b32 v57, v42 offset:9360
	ds_read_b32 v58, v42 offset:10400
	ds_read_b32 v59, v42 offset:11440
	ds_read_b32 v60, v42 offset:12480
	ds_read_b32 v61, v42 offset:13520
	ds_read_b32 v62, v42 offset:14560
	ds_read_b32 v63, v42 offset:15600
	s_waitcnt lgkmcnt(8)
	v_cvt_pk_bf16_f32 v80, v48, v49
	v_cvt_pk_bf16_f32 v81, v50, v51
	v_cvt_pk_bf16_f32 v82, v52, v53
	v_cvt_pk_bf16_f32 v83, v54, v55
	global_store_dwordx4 v40, v[80:83], s[26:27]
	ds_read_b32 v64, v42 offset:16640
	ds_read_b32 v65, v42 offset:17680
	ds_read_b32 v66, v42 offset:18720
	ds_read_b32 v67, v42 offset:19760
	ds_read_b32 v68, v42 offset:20800
	ds_read_b32 v69, v42 offset:21840
	ds_read_b32 v70, v42 offset:22880
	ds_read_b32 v71, v42 offset:23920
	s_waitcnt lgkmcnt(8)
	v_cvt_pk_bf16_f32 v84, v56, v57
	v_cvt_pk_bf16_f32 v85, v58, v59
	v_cvt_pk_bf16_f32 v86, v60, v61
	v_cvt_pk_bf16_f32 v87, v62, v63
	global_store_dwordx4 v40, v[84:87], s[26:27] offset:16
	ds_read_b32 v72, v42 offset:24960
	ds_read_b32 v73, v42 offset:26000
	ds_read_b32 v74, v42 offset:27040
	ds_read_b32 v75, v42 offset:28080
	ds_read_b32 v76, v42 offset:29120
	ds_read_b32 v77, v42 offset:30160
	ds_read_b32 v78, v42 offset:31200
	ds_read_b32 v79, v42 offset:32240
	s_waitcnt lgkmcnt(8)
	v_cvt_pk_bf16_f32 v88, v64, v65
	v_cvt_pk_bf16_f32 v89, v66, v67
	v_cvt_pk_bf16_f32 v90, v68, v69
	v_cvt_pk_bf16_f32 v91, v70, v71
	global_store_dwordx4 v40, v[88:91], s[26:27] offset:32
	s_waitcnt lgkmcnt(0)
	v_cvt_pk_bf16_f32 v92, v72, v73
	v_cvt_pk_bf16_f32 v93, v74, v75
	v_cvt_pk_bf16_f32 v94, v76, v77
	v_cvt_pk_bf16_f32 v95, v78, v79
	global_store_dwordx4 v40, v[92:95], s[26:27] offset:48
	s_add_u32 s17, s17, s33
	s_cmp_lt_u32 s17, 704
	s_cbranch_scc0 .Lt25b_Bnl
	s_mul_hi_u32 s15, s17, 0x2e8ba2f
	s_mul_i32 s14, s15, 88
	s_sub_u32 s14, s17, s14
	s_lshl_b32 s14, s14, 6
	s_lshl_b32 s25, s15, 8
	s_mul_i32 s16, s14, s12
	s_add_u32 s16, s16, s25
	s_lshl_b32 s16, s16, 2
	s_add_u32 s18, s8, s16
	s_addc_u32 s19, s9, 0
	s_mul_i32 s16, s25, 0x1600
	s_add_u32 s16, s16, s14
	s_lshl_b32 s16, s16, 1
	s_add_u32 s26, s10, s16
	s_addc_u32 s27, s11, 0
	global_load_dwordx4 v[100:103], v32, s[18:19]
	global_load_dwordx4 v[104:107], v33, s[18:19]
	global_load_dwordx4 v[108:111], v34, s[18:19]
	global_load_dwordx4 v[112:115], v35, s[18:19]
	global_load_dwordx4 v[116:119], v36, s[18:19]
	global_load_dwordx4 v[120:123], v37, s[18:19]
	global_load_dwordx4 v[124:127], v38, s[18:19]
	global_load_dwordx4 v[128:131], v39, s[18:19]
.Lt25b_Bnl:
	s_add_u32 s3, s3, s33
	s_cmp_lt_u32 s3, 704
	s_cbranch_scc1 .Lt25b_loop
.Lt25b_end:
.LBB0_1225:
	v_mov_b32_e32 v0, 0
	global_load_dwordx2 v[4:5], v0, s[50:51] offset:160
	s_waitcnt vmcnt(0)
	s_barrier
	s_and_saveexec_b64 s[0:1], s[44:45]
	s_cbranch_execz .LBB0_1257
	s_getreg_b32 s3, hwreg(HW_REG_XCC_ID, 0, 4)
	s_lshl_b32 s3, s3, 8
	s_and_b32 s4, s3, 0xf00
	s_mov_b32 s5, 0
	s_waitcnt vmcnt(0)
	v_lshl_add_u64 v[0:1], v[4:5], 0, s[4:5]
	s_mov_b64 s[6:7], 0x25210000
	v_lshl_add_u64 v[0:1], v[0:1], 0, s[6:7]
	s_mov_b64 s[6:7], 0x25210400
	v_lshl_add_u64 v[2:3], v[4:5], 0, s[6:7]
	s_mov_b64 s[6:7], 0x25210500
	v_lshl_add_u64 v[6:7], v[4:5], 0, s[6:7]
	s_mov_b64 s[6:7], 0x25210600
	v_lshl_add_u64 v[8:9], v[4:5], 0, s[6:7]
	s_mov_b64 s[6:7], 0x25210700
	v_lshl_add_u64 v[10:11], v[4:5], 0, s[6:7]
	s_mov_b64 s[6:7], 0x25210800
	v_lshl_add_u64 v[12:13], v[4:5], 0, s[6:7]
	s_mov_b64 s[6:7], 0x25210900
	v_lshl_add_u64 v[14:15], v[4:5], 0, s[6:7]
	s_mov_b64 s[6:7], 0x25210a00
	v_lshl_add_u64 v[16:17], v[4:5], 0, s[6:7]
	s_mov_b64 s[6:7], 0x25210b00
	v_lshl_add_u64 v[18:19], v[4:5], 0, s[6:7]
	s_mov_b64 s[6:7], 0x25210c00
	v_lshl_add_u64 v[20:21], v[4:5], 0, s[6:7]
	s_mov_b64 s[6:7], 0x25210d00
	v_lshl_add_u64 v[22:23], v[4:5], 0, s[6:7]
	s_mov_b64 s[6:7], 0x25210e00
	v_lshl_add_u64 v[24:25], v[4:5], 0, s[6:7]
	s_mov_b64 s[6:7], 0x25210f00
	v_lshl_add_u64 v[28:29], v[4:5], 0, s[6:7]
	s_mov_b64 s[6:7], 0x25211000
	v_lshl_add_u64 v[30:31], v[4:5], 0, s[6:7]
	s_mov_b64 s[6:7], 0x25211100
	v_lshl_add_u64 v[32:33], v[4:5], 0, s[6:7]
	s_mov_b64 s[6:7], 0x25211200
	v_lshl_add_u64 v[34:35], v[4:5], 0, s[6:7]
	s_mov_b64 s[6:7], 0x25211300
	v_lshl_add_u64 v[36:37], v[4:5], 0, s[6:7]
	s_mov_b64 s[6:7], 0

; __device__ void phase7(const Params& p) {
;     ...
;   for (int it = blockIdx.x * NT + tid; it < total; it += gridDim.x * NT) {
;     int j8 = it % NJ, tblk = it / NJ;
;     int t0 = tblk * RB;
;     int tin = t0 & (SEQ - 1);
;     float wg[3][8], wv[3][8], bg[8], bv[8];
; #pragma unroll
;     for (int k = 0; k < 3; ++k)
; #pragma unroll
;       for (int e = 0; e < 8; ++e) {
;         wg[k][e] = p.ffn_conv_w[(size_t)k * 2 * DFF + j8 * 8 + e];
;         wv[k][e] = p.ffn_conv_w[(size_t)k * 2 * DFF + DFF + j8 * 8 + e];
;       }
; #pragma unroll
;     for (int e = 0; e < 8; ++e) {
;       bg[e] = p.ffn_conv_b[j8 * 8 + e];
;       bv[e] = p.ffn_conv_b[DFF + j8 * 8 + e];
;     }
;     float pg[2][8], pvv[2][8];
; #pragma unroll
;     for (int k = 0; k < 2; ++k) {
;       int tt = tin - 2 + k;
;       if (tt >= 0) {
;         i32x4 a = *(const i32x4*)(U + (size_t)(t0 - 2 + k) * (2 * DFF) + j8 * 8);
;         i32x4 bq = *(const i32x4*)(U + (size_t)(t0 - 2 + k) * (2 * DFF) + DFF + j8 * 8);
; #pragma unroll
;         for (int e = 0; e < 4; ++e) {
;           pg[k][2 * e] = __uint_as_float(((unsigned)a[e]) << 16);
;           pg[k][2 * e + 1] = __uint_as_float(((unsigned)a[e]) & 0xffff0000u);
;           pvv[k][2 * e] = __uint_as_float(((unsigned)bq[e]) << 16);
;           pvv[k][2 * e + 1] = __uint_as_float(((unsigned)bq[e]) & 0xffff0000u);
;         }
;       } else {
; #pragma unroll
;         for (int e = 0; e < 8; ++e) { pg[k][e] = 0.f; pvv[k][e] = 0.f; }
;       }
;     }
; #pragma unroll
;     for (int rr = 0; rr < RB; ++rr) {
;       float cgv[8], cvv[8];
;       i32x4 a = *(const i32x4*)(U + (size_t)(t0 + rr) * (2 * DFF) + j8 * 8);
;       i32x4 bq = *(const i32x4*)(U + (size_t)(t0 + rr) * (2 * DFF) + DFF + j8 * 8);
.LBB0_1462:
	s_or_b64 exec, exec, s[4:5]
	v_mov_b32_e32 v0, 0
	s_waitcnt lgkmcnt(0)
	s_barrier
	global_load_dwordx4 v[2:5], v0, s[50:51] offset:120
	global_load_dwordx2 v[6:7], v0, s[50:51] offset:160
	v_mov_b32_e32 v0, v214
	v_readlane_b32 s3, v254, 0
	s_mov_b32 s5, 0x160000
	s_waitcnt vmcnt(0)
	v_readfirstlane_b32 s7, v3
	v_add_u32_e32 v130, s3, v0
	v_readfirstlane_b32 s6, v2
	v_readfirstlane_b32 s9, v5
	v_readfirstlane_b32 s8, v4
	v_readfirstlane_b32 s3, v7
	v_readfirstlane_b32 s4, v6
	v_cmp_gt_i32_e32 vcc, s5, v130
	s_and_saveexec_b64 s[10:11], vcc
	s_cbranch_execz .LBB0_1469
	s_add_u32 s12, s4, 0x4200000
	s_addc_u32 s13, s3, 0
	s_add_u32 s14, s4, 0x1a200000
	s_addc_u32 s15, s3, 0
	s_lshl_b32 s3, s33, 9
	s_add_u32 s18, s6, 0x5800
	s_addc_u32 s19, s7, 0
	s_add_u32 s20, s6, 0xb000
	s_addc_u32 s21, s7, 0
	s_add_u32 s22, s6, 0x10800
	s_addc_u32 s23, s7, 0
	s_add_u32 s24, s6, 0x16000
	s_addc_u32 s25, s7, 0
	s_add_u32 s26, s6, 0x1b800
	v_lshlrev_b32_e32 v0, 3, v0
	s_mov_b64 s[16:17], 0x5800
	s_addc_u32 s27, s7, 0
	v_lshl_add_u32 v131, s2, 12, v0
	s_lshl_b32 s34, s33, 12
	s_mov_b64 s[28:29], 0
	s_mov_b32 s35, 0x2e8ba2e9
	s_movk_i32 s36, 0x5800
	s_movk_i32 s37, 0x2000
	s_movk_i32 s38, 0x2c00
	s_mov_b32 s39, 0x15ffff
	v_mov_b64_e32 v[84:85], s[12:13]
	s_add_u32 s30, s8, 0x5800
	s_addc_u32 s31, s9, 0
	s_add_u32 s36, s12, 0x2c00
	s_addc_u32 s37, s13, 0
	s_mov_b32 s39, 0x2c000
	s_mov_b32 s40, 0x16000
	s_movk_i32 s41, 0x5800
	s_mov_b32 s42, 0xb000
	s_movk_i32 s43, 0x2c0
	v_mov_b32_e32 v235, v130
.Lp7_loop:
	v_lshrrev_b32_e32 v233, 6, v235
	v_mul_hi_u32 v228, v233, s35
	v_lshrrev_b32_e32 v228, 1, v228
	v_mul_u32_u24_e32 v233, s43, v228
	v_mul_u32_u24_e32 v231, s39, v228
	v_sub_u32_e32 v229, v235, v233
	v_mul_u32_u24_e32 v232, s40, v228
	v_lshlrev_b32_e32 v230, 5, v229
	v_lshl_add_u32 v231, v229, 4, v231
	v_lshl_add_u32 v232, v229, 4, v232
	v_and_b32_e32 v233, 0x3ff, v228
	v_cmp_ne_u32_e32 vcc, 0, v233
	global_load_dwordx4 v[0:3], v230, s[6:7]
	global_load_dwordx4 v[4:7], v230, s[6:7] offset:16
	global_load_dwordx4 v[8:11], v230, s[20:21]
	global_load_dwordx4 v[12:15], v230, s[20:21] offset:16
	global_load_dwordx4 v[16:19], v230, s[24:25]
	global_load_dwordx4 v[20:23], v230, s[24:25] offset:16
	global_load_dwordx4 v[24:27], v230, s[8:9]
	global_load_dwordx4 v[28:31], v230, s[8:9] offset:16
	global_load_dwordx4 v[32:35], v230, s[18:19]
	global_load_dwordx4 v[36:39], v230, s[18:19] offset:16
	global_load_dwordx4 v[40:43], v230, s[22:23]
	global_load_dwordx4 v[44:47], v230, s[22:23] offset:16
	global_load_dwordx4 v[48:51], v230, s[26:27]
	global_load_dwordx4 v[52:55], v230, s[26:27] offset:16
	global_load_dwordx4 v[56:59], v230, s[30:31]
	global_load_dwordx4 v[60:63], v230, s[30:31] offset:16
	v_subrev_u32_e32 v234, s42, v231
	v_cndmask_b32_e32 v234, v231, v234, vcc
	global_load_dwordx4 v[64:67], v234, s[12:13]
	global_load_dwordx4 v[68:71], v234, s[36:37]
	v_add_u32_e32 v234, s41, v234
	global_load_dwordx4 v[72:75], v234, s[12:13]
	global_load_dwordx4 v[76:79], v234, s[36:37]
	v_mov_b32_e32 v234, v231
	global_load_dwordx4 v[80:83], v234, s[12:13]
	global_load_dwordx4 v[84:87], v234, s[36:37]
	v_add_u32_e32 v234, s41, v234
	global_load_dwordx4 v[88:91], v234, s[12:13]
	global_load_dwordx4 v[92:95], v234, s[36:37]
	v_add_u32_e32 v234, s41, v234
	global_load_dwordx4 v[96:99], v234, s[12:13]
	global_load_dwordx4 v[100:103], v234, s[36:37]
	v_add_u32_e32 v234, s41, v234
	global_load_dwordx4 v[104:107], v234, s[12:13]
	global_load_dwordx4 v[108:111], v234, s[36:37]
	v_add_u32_e32 v234, s41, v234
	global_load_dwordx4 v[112:115], v234, s[12:13]
	global_load_dwordx4 v[116:119], v234, s[36:37]
	v_add_u32_e32 v234, s41, v234
	global_load_dwordx4 v[120:123], v234, s[12:13]
	global_load_dwordx4 v[124:127], v234, s[36:37]
	v_add_u32_e32 v234, s41, v234
	global_load_dwordx4 v[128:131], v234, s[12:13]
	global_load_dwordx4 v[132:135], v234, s[36:37]
	v_add_u32_e32 v234, s41, v234
	global_load_dwordx4 v[136:139], v234, s[12:13]
	global_load_dwordx4 v[140:143], v234, s[36:37]
	s_waitcnt vmcnt(14)
	v_cndmask_b32_e32 v64, 0, v64, vcc
	v_lshlrev_b32_e32 v144, 16, v64
	v_and_b32_e32 v145, 0xffff0000, v64
	v_cndmask_b32_e32 v65, 0, v65, vcc
	v_lshlrev_b32_e32 v146, 16, v65
	v_and_b32_e32 v147, 0xffff0000, v65
	v_cndmask_b32_e32 v66, 0, v66, vcc
	v_lshlrev_b32_e32 v148, 16, v66
	v_and_b32_e32 v149, 0xffff0000, v66
	v_cndmask_b32_e32 v67, 0, v67, vcc
	v_lshlrev_b32_e32 v150, 16, v67
	v_and_b32_e32 v151, 0xffff0000, v67
	v_cndmask_b32_e32 v68, 0, v68, vcc
	v_lshlrev_b32_e32 v152, 16, v68
	v_and_b32_e32 v153, 0xffff0000, v68
	v_cndmask_b32_e32 v69, 0, v69, vcc
	v_lshlrev_b32_e32 v154, 16, v69
	v_and_b32_e32 v155, 0xffff0000, v69
	v_cndmask_b32_e32 v70, 0, v70, vcc
	v_lshlrev_b32_e32 v156, 16, v70
	v_and_b32_e32 v157, 0xffff0000, v70
	v_cndmask_b32_e32 v71, 0, v71, vcc
	v_lshlrev_b32_e32 v158, 16, v71
	v_and_b32_e32 v159, 0xffff0000, v71
	v_cndmask_b32_e32 v72, 0, v72, vcc
	v_lshlrev_b32_e32 v160, 16, v72
	v_and_b32_e32 v161, 0xffff0000, v72
	v_cndmask_b32_e32 v73, 0, v73, vcc
	v_lshlrev_b32_e32 v162, 16, v73
	v_and_b32_e32 v163, 0xffff0000, v73
	v_cndmask_b32_e32 v74, 0, v74, vcc
	v_lshlrev_b32_e32 v164, 16, v74
	v_and_b32_e32 v165, 0xffff0000, v74
	v_cndmask_b32_e32 v75, 0, v75, vcc
	v_lshlrev_b32_e32 v166, 16, v75
	v_and_b32_e32 v167, 0xffff0000, v75
	v_cndmask_b32_e32 v76, 0, v76, vcc
	v_lshlrev_b32_e32 v168, 16, v76
	v_and_b32_e32 v169, 0xffff0000, v76
	v_cndmask_b32_e32 v77, 0, v77, vcc
	v_lshlrev_b32_e32 v170, 16, v77
	v_and_b32_e32 v171, 0xffff0000, v77
	v_cndmask_b32_e32 v78, 0, v78, vcc
	v_lshlrev_b32_e32 v172, 16, v78
	v_and_b32_e32 v173, 0xffff0000, v78
; __device__ void phase7(const Params& p) {
;     ...
;     for (int rr = 0; rr < RB; ++rr) {
;       float cgv[8], cvv[8];
;       i32x4 a = *(const i32x4*)(U + (size_t)(t0 + rr) * (2 * DFF) + j8 * 8);
;       i32x4 bq = *(const i32x4*)(U + (size_t)(t0 + rr) * (2 * DFF) + DFF + j8 * 8);
; #pragma unroll
;       for (int e = 0; e < 4; ++e) {
;         cgv[2 * e] = __uint_as_float(((unsigned)a[e]) << 16);
;         cgv[2 * e + 1] = __uint_as_float(((unsigned)a[e]) & 0xffff0000u);
;         cvv[2 * e] = __uint_as_float(((unsigned)bq[e]) << 16);
;         cvv[2 * e + 1] = __uint_as_float(((unsigned)bq[e]) & 0xffff0000u);
;       }
;       unsigned pk[4];
;       float res[8];
; #pragma unroll
;       for (int e = 0; e < 8; ++e) {
;         float gg = bg[e] + wg[0][e] * pg[0][e] + wg[1][e] * pg[1][e] + wg[2][e] * cgv[e];
;         float vv = bv[e] + wv[0][e] * pvv[0][e] + wv[1][e] * pvv[1][e] + wv[2][e] * cvv[e];
;         res[e] = gelu_tanh(gg) * vv;
;         pg[0][e] = pg[1][e]; pg[1][e] = cgv[e];
;         pvv[0][e] = pvv[1][e]; pvv[1][e] = cvv[e];
;       }
; #pragma unroll
;       for (int e = 0; e < 4; ++e) pk[e] = pack2(res[2 * e], res[2 * e + 1]);
;       *(i32x4*)(act + (size_t)(t0 + rr) * DFF + j8 * 8) = i32x4{(int)pk[0], (int)pk[1], (int)pk[2], (int)pk[3]};
	v_cndmask_b32_e32 v79, 0, v79, vcc
	v_lshlrev_b32_e32 v174, 16, v79
	v_and_b32_e32 v175, 0xffff0000, v79
	v_lshlrev_b32_e32 v176, 16, v80
	v_and_b32_e32 v177, 0xffff0000, v80
	v_lshlrev_b32_e32 v178, 16, v81
	v_and_b32_e32 v179, 0xffff0000, v81
	v_lshlrev_b32_e32 v180, 16, v82
	v_and_b32_e32 v181, 0xffff0000, v82
	v_lshlrev_b32_e32 v182, 16, v83
	v_and_b32_e32 v183, 0xffff0000, v83
	v_lshlrev_b32_e32 v184, 16, v84
	v_and_b32_e32 v185, 0xffff0000, v84
	v_lshlrev_b32_e32 v186, 16, v85
	v_and_b32_e32 v187, 0xffff0000, v85
	v_lshlrev_b32_e32 v188, 16, v86
	v_and_b32_e32 v189, 0xffff0000, v86
	v_lshlrev_b32_e32 v190, 16, v87
	v_and_b32_e32 v191, 0xffff0000, v87
	v_pk_fma_f32 v[192:193], v[0:1], v[144:145], v[24:25]
	v_pk_fma_f32 v[192:193], v[8:9], v[160:161], v[192:193]
	v_pk_fma_f32 v[192:193], v[16:17], v[176:177], v[192:193]
	v_pk_fma_f32 v[194:195], v[2:3], v[146:147], v[26:27]
	v_pk_fma_f32 v[194:195], v[10:11], v[162:163], v[194:195]
	v_pk_fma_f32 v[194:195], v[18:19], v[178:179], v[194:195]
	v_pk_fma_f32 v[196:197], v[4:5], v[148:149], v[28:29]
	v_pk_fma_f32 v[196:197], v[12:13], v[164:165], v[196:197]
	v_pk_fma_f32 v[196:197], v[20:21], v[180:181], v[196:197]
	v_pk_fma_f32 v[198:199], v[6:7], v[150:151], v[30:31]
	v_pk_fma_f32 v[198:199], v[14:15], v[166:167], v[198:199]
	v_pk_fma_f32 v[198:199], v[22:23], v[182:183], v[198:199]
	v_pk_fma_f32 v[200:201], v[32:33], v[152:153], v[56:57]
	v_pk_fma_f32 v[200:201], v[40:41], v[168:169], v[200:201]
	v_pk_fma_f32 v[200:201], v[48:49], v[184:185], v[200:201]
	v_pk_fma_f32 v[202:203], v[34:35], v[154:155], v[58:59]
	v_pk_fma_f32 v[202:203], v[42:43], v[170:171], v[202:203]
	v_pk_fma_f32 v[202:203], v[50:51], v[186:187], v[202:203]
	v_pk_fma_f32 v[204:205], v[36:37], v[156:157], v[60:61]
	v_pk_fma_f32 v[204:205], v[44:45], v[172:173], v[204:205]
	v_pk_fma_f32 v[204:205], v[52:53], v[188:189], v[204:205]
	v_pk_fma_f32 v[206:207], v[38:39], v[158:159], v[62:63]
	v_pk_fma_f32 v[206:207], v[46:47], v[174:175], v[206:207]
	v_pk_fma_f32 v[206:207], v[54:55], v[190:191], v[206:207]
	v_mul_f32_e32 v216, 0x3d372713, v192
	v_mul_f32_e32 v217, 0x3d372713, v193
	v_mul_f32_e32 v218, 0x3d372713, v194
	v_mul_f32_e32 v219, 0x3d372713, v195
	v_mul_f32_e32 v220, 0x3d372713, v196
	v_mul_f32_e32 v221, 0x3d372713, v197
	v_mul_f32_e32 v222, 0x3d372713, v198
	v_mul_f32_e32 v223, 0x3d372713, v199
	v_mul_f32_e32 v216, v192, v216
	v_mul_f32_e32 v217, v193, v217
	v_mul_f32_e32 v218, v194, v218
	v_mul_f32_e32 v219, v195, v219
	v_mul_f32_e32 v220, v196, v220
	v_mul_f32_e32 v221, v197, v221
	v_mul_f32_e32 v222, v198, v222
	v_mul_f32_e32 v223, v199, v223
	v_fma_f32 v216, v192, v216, v192
	v_fma_f32 v217, v193, v217, v193
	v_fma_f32 v218, v194, v218, v194
	v_fma_f32 v219, v195, v219, v195
	v_fma_f32 v220, v196, v220, v196
	v_fma_f32 v221, v197, v221, v197
	v_fma_f32 v222, v198, v222, v198
	v_fma_f32 v223, v199, v223, v199
	v_mul_f32_e32 v216, 0x3f4c422a, v216
	v_mul_f32_e32 v217, 0x3f4c422a, v217
	v_mul_f32_e32 v218, 0x3f4c422a, v218
	v_mul_f32_e32 v219, 0x3f4c422a, v219
	v_mul_f32_e32 v220, 0x3f4c422a, v220
	v_mul_f32_e32 v221, 0x3f4c422a, v221
	v_mul_f32_e32 v222, 0x3f4c422a, v222
	v_mul_f32_e32 v223, 0x3f4c422a, v223
	v_mul_f32_e32 v216, -2.0, v216
	v_mul_f32_e32 v217, -2.0, v217
	v_mul_f32_e32 v218, -2.0, v218
	v_mul_f32_e32 v219, -2.0, v219
	v_mul_f32_e32 v220, -2.0, v220
	v_mul_f32_e32 v221, -2.0, v221
	v_mul_f32_e32 v222, -2.0, v222
	v_mul_f32_e32 v223, -2.0, v223
	v_mul_f32_e32 v216, 0x3fb8aa3b, v216
	v_mul_f32_e32 v217, 0x3fb8aa3b, v217
	v_mul_f32_e32 v218, 0x3fb8aa3b, v218
	v_mul_f32_e32 v219, 0x3fb8aa3b, v219
	v_mul_f32_e32 v220, 0x3fb8aa3b, v220
	v_mul_f32_e32 v221, 0x3fb8aa3b, v221
	v_mul_f32_e32 v222, 0x3fb8aa3b, v222
	v_mul_f32_e32 v223, 0x3fb8aa3b, v223
	v_exp_f32_e32 v216, v216
	v_exp_f32_e32 v217, v217
	v_exp_f32_e32 v218, v218
	v_exp_f32_e32 v219, v219
	v_exp_f32_e32 v220, v220
	v_exp_f32_e32 v221, v221
	v_exp_f32_e32 v222, v222
	v_exp_f32_e32 v223, v223
	v_add_f32_e32 v216, 1.0, v216
	v_add_f32_e32 v217, 1.0, v217
	v_add_f32_e32 v218, 1.0, v218
	v_add_f32_e32 v219, 1.0, v219
	v_add_f32_e32 v220, 1.0, v220
	v_add_f32_e32 v221, 1.0, v221
	v_add_f32_e32 v222, 1.0, v222
	v_add_f32_e32 v223, 1.0, v223
	v_rcp_f32_e32 v216, v216
	v_rcp_f32_e32 v217, v217
	v_rcp_f32_e32 v218, v218
	v_rcp_f32_e32 v219, v219
	v_rcp_f32_e32 v220, v220
	v_rcp_f32_e32 v221, v221
	v_rcp_f32_e32 v222, v222
	v_rcp_f32_e32 v223, v223
	s_nop 0
	v_pk_mul_f32 v[192:193], v[192:193], v[216:217]
	v_pk_mul_f32 v[194:195], v[194:195], v[218:219]
	v_pk_mul_f32 v[196:197], v[196:197], v[220:221]
	v_pk_mul_f32 v[198:199], v[198:199], v[222:223]
	v_pk_mul_f32 v[192:193], v[200:201], v[192:193]
	v_pk_mul_f32 v[194:195], v[202:203], v[194:195]
	v_pk_mul_f32 v[196:197], v[204:205], v[196:197]
	v_pk_mul_f32 v[198:199], v[206:207], v[198:199]
	v_cvt_pk_bf16_f32 v224, v192, v193
	v_cvt_pk_bf16_f32 v225, v194, v195
	v_cvt_pk_bf16_f32 v226, v196, v197
	v_cvt_pk_bf16_f32 v227, v198, v199
	global_store_dwordx4 v232, v[224:227], s[14:15]
	v_add_u32_e32 v232, s38, v232
	s_waitcnt vmcnt(13)
; __device__ void phase7(const Params& p) {
;     ...
;     for (int rr = 0; rr < RB; ++rr) {
;       float cgv[8], cvv[8];
;       i32x4 a = *(const i32x4*)(U + (size_t)(t0 + rr) * (2 * DFF) + j8 * 8);
;       i32x4 bq = *(const i32x4*)(U + (size_t)(t0 + rr) * (2 * DFF) + DFF + j8 * 8);
; #pragma unroll
;       for (int e = 0; e < 4; ++e) {
;         cgv[2 * e] = __uint_as_float(((unsigned)a[e]) << 16);
;         cgv[2 * e + 1] = __uint_as_float(((unsigned)a[e]) & 0xffff0000u);
;         cvv[2 * e] = __uint_as_float(((unsigned)bq[e]) << 16);
;         cvv[2 * e + 1] = __uint_as_float(((unsigned)bq[e]) & 0xffff0000u);
;       }
;       unsigned pk[4];
;       float res[8];
; #pragma unroll
;       for (int e = 0; e < 8; ++e) {
;         float gg = bg[e] + wg[0][e] * pg[0][e] + wg[1][e] * pg[1][e] + wg[2][e] * cgv[e];
;         float vv = bv[e] + wv[0][e] * pvv[0][e] + wv[1][e] * pvv[1][e] + wv[2][e] * cvv[e];
;         res[e] = gelu_tanh(gg) * vv;
;         pg[0][e] = pg[1][e]; pg[1][e] = cgv[e];
;         pvv[0][e] = pvv[1][e]; pvv[1][e] = cvv[e];
;       }
; #pragma unroll
;       for (int e = 0; e < 4; ++e) pk[e] = pack2(res[2 * e], res[2 * e + 1]);
;       *(i32x4*)(act + (size_t)(t0 + rr) * DFF + j8 * 8) = i32x4{(int)pk[0], (int)pk[1], (int)pk[2], (int)pk[3]};
	v_lshlrev_b32_e32 v144, 16, v88
	v_and_b32_e32 v145, 0xffff0000, v88
	v_lshlrev_b32_e32 v146, 16, v89
	v_and_b32_e32 v147, 0xffff0000, v89
	v_lshlrev_b32_e32 v148, 16, v90
	v_and_b32_e32 v149, 0xffff0000, v90
	v_lshlrev_b32_e32 v150, 16, v91
	v_and_b32_e32 v151, 0xffff0000, v91
	v_lshlrev_b32_e32 v152, 16, v92
	v_and_b32_e32 v153, 0xffff0000, v92
	v_lshlrev_b32_e32 v154, 16, v93
	v_and_b32_e32 v155, 0xffff0000, v93
	v_lshlrev_b32_e32 v156, 16, v94
	v_and_b32_e32 v157, 0xffff0000, v94
	v_lshlrev_b32_e32 v158, 16, v95
	v_and_b32_e32 v159, 0xffff0000, v95
	v_pk_fma_f32 v[192:193], v[0:1], v[160:161], v[24:25]
	v_pk_fma_f32 v[192:193], v[8:9], v[176:177], v[192:193]
	v_pk_fma_f32 v[192:193], v[16:17], v[144:145], v[192:193]
	v_pk_fma_f32 v[194:195], v[2:3], v[162:163], v[26:27]
	v_pk_fma_f32 v[194:195], v[10:11], v[178:179], v[194:195]
	v_pk_fma_f32 v[194:195], v[18:19], v[146:147], v[194:195]
	v_pk_fma_f32 v[196:197], v[4:5], v[164:165], v[28:29]
	v_pk_fma_f32 v[196:197], v[12:13], v[180:181], v[196:197]
	v_pk_fma_f32 v[196:197], v[20:21], v[148:149], v[196:197]
	v_pk_fma_f32 v[198:199], v[6:7], v[166:167], v[30:31]
	v_pk_fma_f32 v[198:199], v[14:15], v[182:183], v[198:199]
	v_pk_fma_f32 v[198:199], v[22:23], v[150:151], v[198:199]
	v_pk_fma_f32 v[200:201], v[32:33], v[168:169], v[56:57]
	v_pk_fma_f32 v[200:201], v[40:41], v[184:185], v[200:201]
	v_pk_fma_f32 v[200:201], v[48:49], v[152:153], v[200:201]
	v_pk_fma_f32 v[202:203], v[34:35], v[170:171], v[58:59]
	v_pk_fma_f32 v[202:203], v[42:43], v[186:187], v[202:203]
	v_pk_fma_f32 v[202:203], v[50:51], v[154:155], v[202:203]
	v_pk_fma_f32 v[204:205], v[36:37], v[172:173], v[60:61]
	v_pk_fma_f32 v[204:205], v[44:45], v[188:189], v[204:205]
	v_pk_fma_f32 v[204:205], v[52:53], v[156:157], v[204:205]
	v_pk_fma_f32 v[206:207], v[38:39], v[174:175], v[62:63]
	v_pk_fma_f32 v[206:207], v[46:47], v[190:191], v[206:207]
	v_pk_fma_f32 v[206:207], v[54:55], v[158:159], v[206:207]
	v_mul_f32_e32 v216, 0x3d372713, v192
	v_mul_f32_e32 v217, 0x3d372713, v193
	v_mul_f32_e32 v218, 0x3d372713, v194
	v_mul_f32_e32 v219, 0x3d372713, v195
	v_mul_f32_e32 v220, 0x3d372713, v196
	v_mul_f32_e32 v221, 0x3d372713, v197
	v_mul_f32_e32 v222, 0x3d372713, v198
	v_mul_f32_e32 v223, 0x3d372713, v199
	v_mul_f32_e32 v216, v192, v216
	v_mul_f32_e32 v217, v193, v217
	v_mul_f32_e32 v218, v194, v218
	v_mul_f32_e32 v219, v195, v219
	v_mul_f32_e32 v220, v196, v220
	v_mul_f32_e32 v221, v197, v221
	v_mul_f32_e32 v222, v198, v222
	v_mul_f32_e32 v223, v199, v223
	v_fma_f32 v216, v192, v216, v192
	v_fma_f32 v217, v193, v217, v193
	v_fma_f32 v218, v194, v218, v194
	v_fma_f32 v219, v195, v219, v195
	v_fma_f32 v220, v196, v220, v196
	v_fma_f32 v221, v197, v221, v197
	v_fma_f32 v222, v198, v222, v198
	v_fma_f32 v223, v199, v223, v199
	v_mul_f32_e32 v216, 0x3f4c422a, v216
	v_mul_f32_e32 v217, 0x3f4c422a, v217
	v_mul_f32_e32 v218, 0x3f4c422a, v218
	v_mul_f32_e32 v219, 0x3f4c422a, v219
	v_mul_f32_e32 v220, 0x3f4c422a, v220
	v_mul_f32_e32 v221, 0x3f4c422a, v221
	v_mul_f32_e32 v222, 0x3f4c422a, v222
	v_mul_f32_e32 v223, 0x3f4c422a, v223
	v_mul_f32_e32 v216, -2.0, v216
	v_mul_f32_e32 v217, -2.0, v217
	v_mul_f32_e32 v218, -2.0, v218
	v_mul_f32_e32 v219, -2.0, v219
	v_mul_f32_e32 v220, -2.0, v220
	v_mul_f32_e32 v221, -2.0, v221
	v_mul_f32_e32 v222, -2.0, v222
	v_mul_f32_e32 v223, -2.0, v223
	v_mul_f32_e32 v216, 0x3fb8aa3b, v216
	v_mul_f32_e32 v217, 0x3fb8aa3b, v217
	v_mul_f32_e32 v218, 0x3fb8aa3b, v218
	v_mul_f32_e32 v219, 0x3fb8aa3b, v219
	v_mul_f32_e32 v220, 0x3fb8aa3b, v220
	v_mul_f32_e32 v221, 0x3fb8aa3b, v221
	v_mul_f32_e32 v222, 0x3fb8aa3b, v222
	v_mul_f32_e32 v223, 0x3fb8aa3b, v223
	v_exp_f32_e32 v216, v216
	v_exp_f32_e32 v217, v217
	v_exp_f32_e32 v218, v218
	v_exp_f32_e32 v219, v219
	v_exp_f32_e32 v220, v220
	v_exp_f32_e32 v221, v221
	v_exp_f32_e32 v222, v222
	v_exp_f32_e32 v223, v223
	v_add_f32_e32 v216, 1.0, v216
	v_add_f32_e32 v217, 1.0, v217
	v_add_f32_e32 v218, 1.0, v218
	v_add_f32_e32 v219, 1.0, v219
	v_add_f32_e32 v220, 1.0, v220
	v_add_f32_e32 v221, 1.0, v221
	v_add_f32_e32 v222, 1.0, v222
	v_add_f32_e32 v223, 1.0, v223
	v_rcp_f32_e32 v216, v216
	v_rcp_f32_e32 v217, v217
	v_rcp_f32_e32 v218, v218
	v_rcp_f32_e32 v219, v219
	v_rcp_f32_e32 v220, v220
	v_rcp_f32_e32 v221, v221
	v_rcp_f32_e32 v222, v222
	v_rcp_f32_e32 v223, v223
	s_nop 0
	v_pk_mul_f32 v[192:193], v[192:193], v[216:217]
	v_pk_mul_f32 v[194:195], v[194:195], v[218:219]
	v_pk_mul_f32 v[196:197], v[196:197], v[220:221]
	v_pk_mul_f32 v[198:199], v[198:199], v[222:223]
	v_pk_mul_f32 v[192:193], v[200:201], v[192:193]
	v_pk_mul_f32 v[194:195], v[202:203], v[194:195]
	v_pk_mul_f32 v[196:197], v[204:205], v[196:197]
	v_pk_mul_f32 v[198:199], v[206:207], v[198:199]
	v_cvt_pk_bf16_f32 v224, v192, v193
	v_cvt_pk_bf16_f32 v225, v194, v195
	v_cvt_pk_bf16_f32 v226, v196, v197
	v_cvt_pk_bf16_f32 v227, v198, v199
	global_store_dwordx4 v232, v[224:227], s[14:15]
	v_add_u32_e32 v232, s38, v232
	s_waitcnt vmcnt(12)
; __device__ void phase7(const Params& p) {
;     ...
;     for (int rr = 0; rr < RB; ++rr) {
;       float cgv[8], cvv[8];
;       i32x4 a = *(const i32x4*)(U + (size_t)(t0 + rr) * (2 * DFF) + j8 * 8);
;       i32x4 bq = *(const i32x4*)(U + (size_t)(t0 + rr) * (2 * DFF) + DFF + j8 * 8);
; #pragma unroll
;       for (int e = 0; e < 4; ++e) {
;         cgv[2 * e] = __uint_as_float(((unsigned)a[e]) << 16);
;         cgv[2 * e + 1] = __uint_as_float(((unsigned)a[e]) & 0xffff0000u);
;         cvv[2 * e] = __uint_as_float(((unsigned)bq[e]) << 16);
;         cvv[2 * e + 1] = __uint_as_float(((unsigned)bq[e]) & 0xffff0000u);
;       }
;       unsigned pk[4];
;       float res[8];
; #pragma unroll
;       for (int e = 0; e < 8; ++e) {
;         float gg = bg[e] + wg[0][e] * pg[0][e] + wg[1][e] * pg[1][e] + wg[2][e] * cgv[e];
;         float vv = bv[e] + wv[0][e] * pvv[0][e] + wv[1][e] * pvv[1][e] + wv[2][e] * cvv[e];
;         res[e] = gelu_tanh(gg) * vv;
;         pg[0][e] = pg[1][e]; pg[1][e] = cgv[e];
;         pvv[0][e] = pvv[1][e]; pvv[1][e] = cvv[e];
;       }
; #pragma unroll
;       for (int e = 0; e < 4; ++e) pk[e] = pack2(res[2 * e], res[2 * e + 1]);
;       *(i32x4*)(act + (size_t)(t0 + rr) * DFF + j8 * 8) = i32x4{(int)pk[0], (int)pk[1], (int)pk[2], (int)pk[3]};
	v_lshlrev_b32_e32 v160, 16, v96
	v_and_b32_e32 v161, 0xffff0000, v96
	v_lshlrev_b32_e32 v162, 16, v97
	v_and_b32_e32 v163, 0xffff0000, v97
	v_lshlrev_b32_e32 v164, 16, v98
	v_and_b32_e32 v165, 0xffff0000, v98
	v_lshlrev_b32_e32 v166, 16, v99
	v_and_b32_e32 v167, 0xffff0000, v99
	v_lshlrev_b32_e32 v168, 16, v100
	v_and_b32_e32 v169, 0xffff0000, v100
	v_lshlrev_b32_e32 v170, 16, v101
	v_and_b32_e32 v171, 0xffff0000, v101
	v_lshlrev_b32_e32 v172, 16, v102
	v_and_b32_e32 v173, 0xffff0000, v102
	v_lshlrev_b32_e32 v174, 16, v103
	v_and_b32_e32 v175, 0xffff0000, v103
	v_pk_fma_f32 v[192:193], v[0:1], v[176:177], v[24:25]
	v_pk_fma_f32 v[192:193], v[8:9], v[144:145], v[192:193]
	v_pk_fma_f32 v[192:193], v[16:17], v[160:161], v[192:193]
	v_pk_fma_f32 v[194:195], v[2:3], v[178:179], v[26:27]
	v_pk_fma_f32 v[194:195], v[10:11], v[146:147], v[194:195]
	v_pk_fma_f32 v[194:195], v[18:19], v[162:163], v[194:195]
	v_pk_fma_f32 v[196:197], v[4:5], v[180:181], v[28:29]
	v_pk_fma_f32 v[196:197], v[12:13], v[148:149], v[196:197]
	v_pk_fma_f32 v[196:197], v[20:21], v[164:165], v[196:197]
	v_pk_fma_f32 v[198:199], v[6:7], v[182:183], v[30:31]
	v_pk_fma_f32 v[198:199], v[14:15], v[150:151], v[198:199]
	v_pk_fma_f32 v[198:199], v[22:23], v[166:167], v[198:199]
	v_pk_fma_f32 v[200:201], v[32:33], v[184:185], v[56:57]
	v_pk_fma_f32 v[200:201], v[40:41], v[152:153], v[200:201]
	v_pk_fma_f32 v[200:201], v[48:49], v[168:169], v[200:201]
	v_pk_fma_f32 v[202:203], v[34:35], v[186:187], v[58:59]
	v_pk_fma_f32 v[202:203], v[42:43], v[154:155], v[202:203]
	v_pk_fma_f32 v[202:203], v[50:51], v[170:171], v[202:203]
	v_pk_fma_f32 v[204:205], v[36:37], v[188:189], v[60:61]
	v_pk_fma_f32 v[204:205], v[44:45], v[156:157], v[204:205]
	v_pk_fma_f32 v[204:205], v[52:53], v[172:173], v[204:205]
	v_pk_fma_f32 v[206:207], v[38:39], v[190:191], v[62:63]
	v_pk_fma_f32 v[206:207], v[46:47], v[158:159], v[206:207]
	v_pk_fma_f32 v[206:207], v[54:55], v[174:175], v[206:207]
	v_mul_f32_e32 v216, 0x3d372713, v192
	v_mul_f32_e32 v217, 0x3d372713, v193
	v_mul_f32_e32 v218, 0x3d372713, v194
	v_mul_f32_e32 v219, 0x3d372713, v195
	v_mul_f32_e32 v220, 0x3d372713, v196
	v_mul_f32_e32 v221, 0x3d372713, v197
	v_mul_f32_e32 v222, 0x3d372713, v198
	v_mul_f32_e32 v223, 0x3d372713, v199
	v_mul_f32_e32 v216, v192, v216
	v_mul_f32_e32 v217, v193, v217
	v_mul_f32_e32 v218, v194, v218
	v_mul_f32_e32 v219, v195, v219
	v_mul_f32_e32 v220, v196, v220
	v_mul_f32_e32 v221, v197, v221
	v_mul_f32_e32 v222, v198, v222
	v_mul_f32_e32 v223, v199, v223
	v_fma_f32 v216, v192, v216, v192
	v_fma_f32 v217, v193, v217, v193
	v_fma_f32 v218, v194, v218, v194
	v_fma_f32 v219, v195, v219, v195
	v_fma_f32 v220, v196, v220, v196
	v_fma_f32 v221, v197, v221, v197
	v_fma_f32 v222, v198, v222, v198
	v_fma_f32 v223, v199, v223, v199
	v_mul_f32_e32 v216, 0x3f4c422a, v216
	v_mul_f32_e32 v217, 0x3f4c422a, v217
	v_mul_f32_e32 v218, 0x3f4c422a, v218
	v_mul_f32_e32 v219, 0x3f4c422a, v219
	v_mul_f32_e32 v220, 0x3f4c422a, v220
	v_mul_f32_e32 v221, 0x3f4c422a, v221
	v_mul_f32_e32 v222, 0x3f4c422a, v222
	v_mul_f32_e32 v223, 0x3f4c422a, v223
	v_mul_f32_e32 v216, -2.0, v216
	v_mul_f32_e32 v217, -2.0, v217
	v_mul_f32_e32 v218, -2.0, v218
	v_mul_f32_e32 v219, -2.0, v219
	v_mul_f32_e32 v220, -2.0, v220
	v_mul_f32_e32 v221, -2.0, v221
	v_mul_f32_e32 v222, -2.0, v222
	v_mul_f32_e32 v223, -2.0, v223
	v_mul_f32_e32 v216, 0x3fb8aa3b, v216
	v_mul_f32_e32 v217, 0x3fb8aa3b, v217
	v_mul_f32_e32 v218, 0x3fb8aa3b, v218
	v_mul_f32_e32 v219, 0x3fb8aa3b, v219
	v_mul_f32_e32 v220, 0x3fb8aa3b, v220
	v_mul_f32_e32 v221, 0x3fb8aa3b, v221
	v_mul_f32_e32 v222, 0x3fb8aa3b, v222
	v_mul_f32_e32 v223, 0x3fb8aa3b, v223
	v_exp_f32_e32 v216, v216
	v_exp_f32_e32 v217, v217
	v_exp_f32_e32 v218, v218
	v_exp_f32_e32 v219, v219
	v_exp_f32_e32 v220, v220
	v_exp_f32_e32 v221, v221
	v_exp_f32_e32 v222, v222
	v_exp_f32_e32 v223, v223
	v_add_f32_e32 v216, 1.0, v216
	v_add_f32_e32 v217, 1.0, v217
	v_add_f32_e32 v218, 1.0, v218
	v_add_f32_e32 v219, 1.0, v219
	v_add_f32_e32 v220, 1.0, v220
	v_add_f32_e32 v221, 1.0, v221
	v_add_f32_e32 v222, 1.0, v222
	v_add_f32_e32 v223, 1.0, v223
	v_rcp_f32_e32 v216, v216
	v_rcp_f32_e32 v217, v217
	v_rcp_f32_e32 v218, v218
	v_rcp_f32_e32 v219, v219
	v_rcp_f32_e32 v220, v220
	v_rcp_f32_e32 v221, v221
	v_rcp_f32_e32 v222, v222
	v_rcp_f32_e32 v223, v223
	s_nop 0
	v_pk_mul_f32 v[192:193], v[192:193], v[216:217]
	v_pk_mul_f32 v[194:195], v[194:195], v[218:219]
	v_pk_mul_f32 v[196:197], v[196:197], v[220:221]
	v_pk_mul_f32 v[198:199], v[198:199], v[222:223]
	v_pk_mul_f32 v[192:193], v[200:201], v[192:193]
	v_pk_mul_f32 v[194:195], v[202:203], v[194:195]
	v_pk_mul_f32 v[196:197], v[204:205], v[196:197]
	v_pk_mul_f32 v[198:199], v[206:207], v[198:199]
	v_cvt_pk_bf16_f32 v224, v192, v193
	v_cvt_pk_bf16_f32 v225, v194, v195
	v_cvt_pk_bf16_f32 v226, v196, v197
	v_cvt_pk_bf16_f32 v227, v198, v199
	global_store_dwordx4 v232, v[224:227], s[14:15]
	v_add_u32_e32 v232, s38, v232
	s_waitcnt vmcnt(11)
; __device__ void phase7(const Params& p) {
;     ...
;     for (int rr = 0; rr < RB; ++rr) {
;       float cgv[8], cvv[8];
;       i32x4 a = *(const i32x4*)(U + (size_t)(t0 + rr) * (2 * DFF) + j8 * 8);
;       i32x4 bq = *(const i32x4*)(U + (size_t)(t0 + rr) * (2 * DFF) + DFF + j8 * 8);
; #pragma unroll
;       for (int e = 0; e < 4; ++e) {
;         cgv[2 * e] = __uint_as_float(((unsigned)a[e]) << 16);
;         cgv[2 * e + 1] = __uint_as_float(((unsigned)a[e]) & 0xffff0000u);
;         cvv[2 * e] = __uint_as_float(((unsigned)bq[e]) << 16);
;         cvv[2 * e + 1] = __uint_as_float(((unsigned)bq[e]) & 0xffff0000u);
;       }
;       unsigned pk[4];
;       float res[8];
; #pragma unroll
;       for (int e = 0; e < 8; ++e) {
;         float gg = bg[e] + wg[0][e] * pg[0][e] + wg[1][e] * pg[1][e] + wg[2][e] * cgv[e];
;         float vv = bv[e] + wv[0][e] * pvv[0][e] + wv[1][e] * pvv[1][e] + wv[2][e] * cvv[e];
;         res[e] = gelu_tanh(gg) * vv;
;         pg[0][e] = pg[1][e]; pg[1][e] = cgv[e];
;         pvv[0][e] = pvv[1][e]; pvv[1][e] = cvv[e];
;       }
; #pragma unroll
;       for (int e = 0; e < 4; ++e) pk[e] = pack2(res[2 * e], res[2 * e + 1]);
;       *(i32x4*)(act + (size_t)(t0 + rr) * DFF + j8 * 8) = i32x4{(int)pk[0], (int)pk[1], (int)pk[2], (int)pk[3]};
	v_lshlrev_b32_e32 v176, 16, v104
	v_and_b32_e32 v177, 0xffff0000, v104
	v_lshlrev_b32_e32 v178, 16, v105
	v_and_b32_e32 v179, 0xffff0000, v105
	v_lshlrev_b32_e32 v180, 16, v106
	v_and_b32_e32 v181, 0xffff0000, v106
	v_lshlrev_b32_e32 v182, 16, v107
	v_and_b32_e32 v183, 0xffff0000, v107
	v_lshlrev_b32_e32 v184, 16, v108
	v_and_b32_e32 v185, 0xffff0000, v108
	v_lshlrev_b32_e32 v186, 16, v109
	v_and_b32_e32 v187, 0xffff0000, v109
	v_lshlrev_b32_e32 v188, 16, v110
	v_and_b32_e32 v189, 0xffff0000, v110
	v_lshlrev_b32_e32 v190, 16, v111
	v_and_b32_e32 v191, 0xffff0000, v111
	v_pk_fma_f32 v[192:193], v[0:1], v[144:145], v[24:25]
	v_pk_fma_f32 v[192:193], v[8:9], v[160:161], v[192:193]
	v_pk_fma_f32 v[192:193], v[16:17], v[176:177], v[192:193]
	v_pk_fma_f32 v[194:195], v[2:3], v[146:147], v[26:27]
	v_pk_fma_f32 v[194:195], v[10:11], v[162:163], v[194:195]
	v_pk_fma_f32 v[194:195], v[18:19], v[178:179], v[194:195]
	v_pk_fma_f32 v[196:197], v[4:5], v[148:149], v[28:29]
	v_pk_fma_f32 v[196:197], v[12:13], v[164:165], v[196:197]
	v_pk_fma_f32 v[196:197], v[20:21], v[180:181], v[196:197]
	v_pk_fma_f32 v[198:199], v[6:7], v[150:151], v[30:31]
	v_pk_fma_f32 v[198:199], v[14:15], v[166:167], v[198:199]
	v_pk_fma_f32 v[198:199], v[22:23], v[182:183], v[198:199]
	v_pk_fma_f32 v[200:201], v[32:33], v[152:153], v[56:57]
	v_pk_fma_f32 v[200:201], v[40:41], v[168:169], v[200:201]
	v_pk_fma_f32 v[200:201], v[48:49], v[184:185], v[200:201]
	v_pk_fma_f32 v[202:203], v[34:35], v[154:155], v[58:59]
	v_pk_fma_f32 v[202:203], v[42:43], v[170:171], v[202:203]
	v_pk_fma_f32 v[202:203], v[50:51], v[186:187], v[202:203]
	v_pk_fma_f32 v[204:205], v[36:37], v[156:157], v[60:61]
	v_pk_fma_f32 v[204:205], v[44:45], v[172:173], v[204:205]
	v_pk_fma_f32 v[204:205], v[52:53], v[188:189], v[204:205]
	v_pk_fma_f32 v[206:207], v[38:39], v[158:159], v[62:63]
	v_pk_fma_f32 v[206:207], v[46:47], v[174:175], v[206:207]
	v_pk_fma_f32 v[206:207], v[54:55], v[190:191], v[206:207]
	v_mul_f32_e32 v216, 0x3d372713, v192
	v_mul_f32_e32 v217, 0x3d372713, v193
	v_mul_f32_e32 v218, 0x3d372713, v194
	v_mul_f32_e32 v219, 0x3d372713, v195
	v_mul_f32_e32 v220, 0x3d372713, v196
	v_mul_f32_e32 v221, 0x3d372713, v197
	v_mul_f32_e32 v222, 0x3d372713, v198
	v_mul_f32_e32 v223, 0x3d372713, v199
	v_mul_f32_e32 v216, v192, v216
	v_mul_f32_e32 v217, v193, v217
	v_mul_f32_e32 v218, v194, v218
	v_mul_f32_e32 v219, v195, v219
	v_mul_f32_e32 v220, v196, v220
	v_mul_f32_e32 v221, v197, v221
	v_mul_f32_e32 v222, v198, v222
	v_mul_f32_e32 v223, v199, v223
	v_fma_f32 v216, v192, v216, v192
	v_fma_f32 v217, v193, v217, v193
	v_fma_f32 v218, v194, v218, v194
	v_fma_f32 v219, v195, v219, v195
	v_fma_f32 v220, v196, v220, v196
	v_fma_f32 v221, v197, v221, v197
	v_fma_f32 v222, v198, v222, v198
	v_fma_f32 v223, v199, v223, v199
	v_mul_f32_e32 v216, 0x3f4c422a, v216
	v_mul_f32_e32 v217, 0x3f4c422a, v217
	v_mul_f32_e32 v218, 0x3f4c422a, v218
	v_mul_f32_e32 v219, 0x3f4c422a, v219
	v_mul_f32_e32 v220, 0x3f4c422a, v220
	v_mul_f32_e32 v221, 0x3f4c422a, v221
	v_mul_f32_e32 v222, 0x3f4c422a, v222
	v_mul_f32_e32 v223, 0x3f4c422a, v223
	v_mul_f32_e32 v216, -2.0, v216
	v_mul_f32_e32 v217, -2.0, v217
	v_mul_f32_e32 v218, -2.0, v218
	v_mul_f32_e32 v219, -2.0, v219
	v_mul_f32_e32 v220, -2.0, v220
	v_mul_f32_e32 v221, -2.0, v221
	v_mul_f32_e32 v222, -2.0, v222
	v_mul_f32_e32 v223, -2.0, v223
	v_mul_f32_e32 v216, 0x3fb8aa3b, v216
	v_mul_f32_e32 v217, 0x3fb8aa3b, v217
	v_mul_f32_e32 v218, 0x3fb8aa3b, v218
	v_mul_f32_e32 v219, 0x3fb8aa3b, v219
	v_mul_f32_e32 v220, 0x3fb8aa3b, v220
	v_mul_f32_e32 v221, 0x3fb8aa3b, v221
	v_mul_f32_e32 v222, 0x3fb8aa3b, v222
	v_mul_f32_e32 v223, 0x3fb8aa3b, v223
	v_exp_f32_e32 v216, v216
	v_exp_f32_e32 v217, v217
	v_exp_f32_e32 v218, v218
	v_exp_f32_e32 v219, v219
	v_exp_f32_e32 v220, v220
	v_exp_f32_e32 v221, v221
	v_exp_f32_e32 v222, v222
	v_exp_f32_e32 v223, v223
	v_add_f32_e32 v216, 1.0, v216
	v_add_f32_e32 v217, 1.0, v217
	v_add_f32_e32 v218, 1.0, v218
	v_add_f32_e32 v219, 1.0, v219
	v_add_f32_e32 v220, 1.0, v220
	v_add_f32_e32 v221, 1.0, v221
	v_add_f32_e32 v222, 1.0, v222
	v_add_f32_e32 v223, 1.0, v223
	v_rcp_f32_e32 v216, v216
	v_rcp_f32_e32 v217, v217
	v_rcp_f32_e32 v218, v218
	v_rcp_f32_e32 v219, v219
	v_rcp_f32_e32 v220, v220
	v_rcp_f32_e32 v221, v221
	v_rcp_f32_e32 v222, v222
	v_rcp_f32_e32 v223, v223
	s_nop 0
	v_pk_mul_f32 v[192:193], v[192:193], v[216:217]
	v_pk_mul_f32 v[194:195], v[194:195], v[218:219]
	v_pk_mul_f32 v[196:197], v[196:197], v[220:221]
	v_pk_mul_f32 v[198:199], v[198:199], v[222:223]
	v_pk_mul_f32 v[192:193], v[200:201], v[192:193]
	v_pk_mul_f32 v[194:195], v[202:203], v[194:195]
	v_pk_mul_f32 v[196:197], v[204:205], v[196:197]
	v_pk_mul_f32 v[198:199], v[206:207], v[198:199]
	v_cvt_pk_bf16_f32 v224, v192, v193
	v_cvt_pk_bf16_f32 v225, v194, v195
	v_cvt_pk_bf16_f32 v226, v196, v197
	v_cvt_pk_bf16_f32 v227, v198, v199
	global_store_dwordx4 v232, v[224:227], s[14:15]
	v_add_u32_e32 v232, s38, v232
	s_waitcnt vmcnt(10)
; __device__ void phase7(const Params& p) {
;     ...
;     for (int rr = 0; rr < RB; ++rr) {
;       float cgv[8], cvv[8];
;       i32x4 a = *(const i32x4*)(U + (size_t)(t0 + rr) * (2 * DFF) + j8 * 8);
;       i32x4 bq = *(const i32x4*)(U + (size_t)(t0 + rr) * (2 * DFF) + DFF + j8 * 8);
; #pragma unroll
;       for (int e = 0; e < 4; ++e) {
;         cgv[2 * e] = __uint_as_float(((unsigned)a[e]) << 16);
;         cgv[2 * e + 1] = __uint_as_float(((unsigned)a[e]) & 0xffff0000u);
;         cvv[2 * e] = __uint_as_float(((unsigned)bq[e]) << 16);
;         cvv[2 * e + 1] = __uint_as_float(((unsigned)bq[e]) & 0xffff0000u);
;       }
;       unsigned pk[4];
;       float res[8];
; #pragma unroll
;       for (int e = 0; e < 8; ++e) {
;         float gg = bg[e] + wg[0][e] * pg[0][e] + wg[1][e] * pg[1][e] + wg[2][e] * cgv[e];
;         float vv = bv[e] + wv[0][e] * pvv[0][e] + wv[1][e] * pvv[1][e] + wv[2][e] * cvv[e];
;         res[e] = gelu_tanh(gg) * vv;
;         pg[0][e] = pg[1][e]; pg[1][e] = cgv[e];
;         pvv[0][e] = pvv[1][e]; pvv[1][e] = cvv[e];
;       }
; #pragma unroll
;       for (int e = 0; e < 4; ++e) pk[e] = pack2(res[2 * e], res[2 * e + 1]);
;       *(i32x4*)(act + (size_t)(t0 + rr) * DFF + j8 * 8) = i32x4{(int)pk[0], (int)pk[1], (int)pk[2], (int)pk[3]};
	v_lshlrev_b32_e32 v144, 16, v112
	v_and_b32_e32 v145, 0xffff0000, v112
	v_lshlrev_b32_e32 v146, 16, v113
	v_and_b32_e32 v147, 0xffff0000, v113
	v_lshlrev_b32_e32 v148, 16, v114
	v_and_b32_e32 v149, 0xffff0000, v114
	v_lshlrev_b32_e32 v150, 16, v115
	v_and_b32_e32 v151, 0xffff0000, v115
	v_lshlrev_b32_e32 v152, 16, v116
	v_and_b32_e32 v153, 0xffff0000, v116
	v_lshlrev_b32_e32 v154, 16, v117
	v_and_b32_e32 v155, 0xffff0000, v117
	v_lshlrev_b32_e32 v156, 16, v118
	v_and_b32_e32 v157, 0xffff0000, v118
	v_lshlrev_b32_e32 v158, 16, v119
	v_and_b32_e32 v159, 0xffff0000, v119
	v_pk_fma_f32 v[192:193], v[0:1], v[160:161], v[24:25]
	v_pk_fma_f32 v[192:193], v[8:9], v[176:177], v[192:193]
	v_pk_fma_f32 v[192:193], v[16:17], v[144:145], v[192:193]
	v_pk_fma_f32 v[194:195], v[2:3], v[162:163], v[26:27]
	v_pk_fma_f32 v[194:195], v[10:11], v[178:179], v[194:195]
	v_pk_fma_f32 v[194:195], v[18:19], v[146:147], v[194:195]
	v_pk_fma_f32 v[196:197], v[4:5], v[164:165], v[28:29]
	v_pk_fma_f32 v[196:197], v[12:13], v[180:181], v[196:197]
	v_pk_fma_f32 v[196:197], v[20:21], v[148:149], v[196:197]
	v_pk_fma_f32 v[198:199], v[6:7], v[166:167], v[30:31]
	v_pk_fma_f32 v[198:199], v[14:15], v[182:183], v[198:199]
	v_pk_fma_f32 v[198:199], v[22:23], v[150:151], v[198:199]
	v_pk_fma_f32 v[200:201], v[32:33], v[168:169], v[56:57]
	v_pk_fma_f32 v[200:201], v[40:41], v[184:185], v[200:201]
	v_pk_fma_f32 v[200:201], v[48:49], v[152:153], v[200:201]
	v_pk_fma_f32 v[202:203], v[34:35], v[170:171], v[58:59]
	v_pk_fma_f32 v[202:203], v[42:43], v[186:187], v[202:203]
	v_pk_fma_f32 v[202:203], v[50:51], v[154:155], v[202:203]
	v_pk_fma_f32 v[204:205], v[36:37], v[172:173], v[60:61]
	v_pk_fma_f32 v[204:205], v[44:45], v[188:189], v[204:205]
	v_pk_fma_f32 v[204:205], v[52:53], v[156:157], v[204:205]
	v_pk_fma_f32 v[206:207], v[38:39], v[174:175], v[62:63]
	v_pk_fma_f32 v[206:207], v[46:47], v[190:191], v[206:207]
	v_pk_fma_f32 v[206:207], v[54:55], v[158:159], v[206:207]
	v_mul_f32_e32 v216, 0x3d372713, v192
	v_mul_f32_e32 v217, 0x3d372713, v193
	v_mul_f32_e32 v218, 0x3d372713, v194
	v_mul_f32_e32 v219, 0x3d372713, v195
	v_mul_f32_e32 v220, 0x3d372713, v196
	v_mul_f32_e32 v221, 0x3d372713, v197
	v_mul_f32_e32 v222, 0x3d372713, v198
	v_mul_f32_e32 v223, 0x3d372713, v199
	v_mul_f32_e32 v216, v192, v216
	v_mul_f32_e32 v217, v193, v217
	v_mul_f32_e32 v218, v194, v218
	v_mul_f32_e32 v219, v195, v219
	v_mul_f32_e32 v220, v196, v220
	v_mul_f32_e32 v221, v197, v221
	v_mul_f32_e32 v222, v198, v222
	v_mul_f32_e32 v223, v199, v223
	v_fma_f32 v216, v192, v216, v192
	v_fma_f32 v217, v193, v217, v193
	v_fma_f32 v218, v194, v218, v194
	v_fma_f32 v219, v195, v219, v195
	v_fma_f32 v220, v196, v220, v196
	v_fma_f32 v221, v197, v221, v197
	v_fma_f32 v222, v198, v222, v198
	v_fma_f32 v223, v199, v223, v199
	v_mul_f32_e32 v216, 0x3f4c422a, v216
	v_mul_f32_e32 v217, 0x3f4c422a, v217
	v_mul_f32_e32 v218, 0x3f4c422a, v218
	v_mul_f32_e32 v219, 0x3f4c422a, v219
	v_mul_f32_e32 v220, 0x3f4c422a, v220
	v_mul_f32_e32 v221, 0x3f4c422a, v221
	v_mul_f32_e32 v222, 0x3f4c422a, v222
	v_mul_f32_e32 v223, 0x3f4c422a, v223
	v_mul_f32_e32 v216, -2.0, v216
	v_mul_f32_e32 v217, -2.0, v217
	v_mul_f32_e32 v218, -2.0, v218
	v_mul_f32_e32 v219, -2.0, v219
	v_mul_f32_e32 v220, -2.0, v220
	v_mul_f32_e32 v221, -2.0, v221
	v_mul_f32_e32 v222, -2.0, v222
	v_mul_f32_e32 v223, -2.0, v223
	v_mul_f32_e32 v216, 0x3fb8aa3b, v216
	v_mul_f32_e32 v217, 0x3fb8aa3b, v217
	v_mul_f32_e32 v218, 0x3fb8aa3b, v218
	v_mul_f32_e32 v219, 0x3fb8aa3b, v219
	v_mul_f32_e32 v220, 0x3fb8aa3b, v220
	v_mul_f32_e32 v221, 0x3fb8aa3b, v221
	v_mul_f32_e32 v222, 0x3fb8aa3b, v222
	v_mul_f32_e32 v223, 0x3fb8aa3b, v223
	v_exp_f32_e32 v216, v216
	v_exp_f32_e32 v217, v217
	v_exp_f32_e32 v218, v218
	v_exp_f32_e32 v219, v219
	v_exp_f32_e32 v220, v220
	v_exp_f32_e32 v221, v221
	v_exp_f32_e32 v222, v222
	v_exp_f32_e32 v223, v223
	v_add_f32_e32 v216, 1.0, v216
	v_add_f32_e32 v217, 1.0, v217
	v_add_f32_e32 v218, 1.0, v218
	v_add_f32_e32 v219, 1.0, v219
	v_add_f32_e32 v220, 1.0, v220
	v_add_f32_e32 v221, 1.0, v221
	v_add_f32_e32 v222, 1.0, v222
	v_add_f32_e32 v223, 1.0, v223
	v_rcp_f32_e32 v216, v216
	v_rcp_f32_e32 v217, v217
	v_rcp_f32_e32 v218, v218
	v_rcp_f32_e32 v219, v219
	v_rcp_f32_e32 v220, v220
	v_rcp_f32_e32 v221, v221
	v_rcp_f32_e32 v222, v222
	v_rcp_f32_e32 v223, v223
	s_nop 0
	v_pk_mul_f32 v[192:193], v[192:193], v[216:217]
	v_pk_mul_f32 v[194:195], v[194:195], v[218:219]
	v_pk_mul_f32 v[196:197], v[196:197], v[220:221]
	v_pk_mul_f32 v[198:199], v[198:199], v[222:223]
	v_pk_mul_f32 v[192:193], v[200:201], v[192:193]
	v_pk_mul_f32 v[194:195], v[202:203], v[194:195]
	v_pk_mul_f32 v[196:197], v[204:205], v[196:197]
	v_pk_mul_f32 v[198:199], v[206:207], v[198:199]
	v_cvt_pk_bf16_f32 v224, v192, v193
	v_cvt_pk_bf16_f32 v225, v194, v195
	v_cvt_pk_bf16_f32 v226, v196, v197
	v_cvt_pk_bf16_f32 v227, v198, v199
	global_store_dwordx4 v232, v[224:227], s[14:15]
	v_add_u32_e32 v232, s38, v232
	s_waitcnt vmcnt(9)
; __device__ void phase7(const Params& p) {
;     ...
;     for (int rr = 0; rr < RB; ++rr) {
;       float cgv[8], cvv[8];
;       i32x4 a = *(const i32x4*)(U + (size_t)(t0 + rr) * (2 * DFF) + j8 * 8);
;       i32x4 bq = *(const i32x4*)(U + (size_t)(t0 + rr) * (2 * DFF) + DFF + j8 * 8);
; #pragma unroll
;       for (int e = 0; e < 4; ++e) {
;         cgv[2 * e] = __uint_as_float(((unsigned)a[e]) << 16);
;         cgv[2 * e + 1] = __uint_as_float(((unsigned)a[e]) & 0xffff0000u);
;         cvv[2 * e] = __uint_as_float(((unsigned)bq[e]) << 16);
;         cvv[2 * e + 1] = __uint_as_float(((unsigned)bq[e]) & 0xffff0000u);
;       }
;       unsigned pk[4];
;       float res[8];
; #pragma unroll
;       for (int e = 0; e < 8; ++e) {
;         float gg = bg[e] + wg[0][e] * pg[0][e] + wg[1][e] * pg[1][e] + wg[2][e] * cgv[e];
;         float vv = bv[e] + wv[0][e] * pvv[0][e] + wv[1][e] * pvv[1][e] + wv[2][e] * cvv[e];
;         res[e] = gelu_tanh(gg) * vv;
;         pg[0][e] = pg[1][e]; pg[1][e] = cgv[e];
;         pvv[0][e] = pvv[1][e]; pvv[1][e] = cvv[e];
;       }
; #pragma unroll
;       for (int e = 0; e < 4; ++e) pk[e] = pack2(res[2 * e], res[2 * e + 1]);
;       *(i32x4*)(act + (size_t)(t0 + rr) * DFF + j8 * 8) = i32x4{(int)pk[0], (int)pk[1], (int)pk[2], (int)pk[3]};
	v_lshlrev_b32_e32 v160, 16, v120
	v_and_b32_e32 v161, 0xffff0000, v120
	v_lshlrev_b32_e32 v162, 16, v121
	v_and_b32_e32 v163, 0xffff0000, v121
	v_lshlrev_b32_e32 v164, 16, v122
	v_and_b32_e32 v165, 0xffff0000, v122
	v_lshlrev_b32_e32 v166, 16, v123
	v_and_b32_e32 v167, 0xffff0000, v123
	v_lshlrev_b32_e32 v168, 16, v124
	v_and_b32_e32 v169, 0xffff0000, v124
	v_lshlrev_b32_e32 v170, 16, v125
	v_and_b32_e32 v171, 0xffff0000, v125
	v_lshlrev_b32_e32 v172, 16, v126
	v_and_b32_e32 v173, 0xffff0000, v126
	v_lshlrev_b32_e32 v174, 16, v127
	v_and_b32_e32 v175, 0xffff0000, v127
	v_pk_fma_f32 v[192:193], v[0:1], v[176:177], v[24:25]
	v_pk_fma_f32 v[192:193], v[8:9], v[144:145], v[192:193]
	v_pk_fma_f32 v[192:193], v[16:17], v[160:161], v[192:193]
	v_pk_fma_f32 v[194:195], v[2:3], v[178:179], v[26:27]
	v_pk_fma_f32 v[194:195], v[10:11], v[146:147], v[194:195]
	v_pk_fma_f32 v[194:195], v[18:19], v[162:163], v[194:195]
	v_pk_fma_f32 v[196:197], v[4:5], v[180:181], v[28:29]
	v_pk_fma_f32 v[196:197], v[12:13], v[148:149], v[196:197]
	v_pk_fma_f32 v[196:197], v[20:21], v[164:165], v[196:197]
	v_pk_fma_f32 v[198:199], v[6:7], v[182:183], v[30:31]
	v_pk_fma_f32 v[198:199], v[14:15], v[150:151], v[198:199]
	v_pk_fma_f32 v[198:199], v[22:23], v[166:167], v[198:199]
	v_pk_fma_f32 v[200:201], v[32:33], v[184:185], v[56:57]
	v_pk_fma_f32 v[200:201], v[40:41], v[152:153], v[200:201]
	v_pk_fma_f32 v[200:201], v[48:49], v[168:169], v[200:201]
	v_pk_fma_f32 v[202:203], v[34:35], v[186:187], v[58:59]
	v_pk_fma_f32 v[202:203], v[42:43], v[154:155], v[202:203]
	v_pk_fma_f32 v[202:203], v[50:51], v[170:171], v[202:203]
	v_pk_fma_f32 v[204:205], v[36:37], v[188:189], v[60:61]
	v_pk_fma_f32 v[204:205], v[44:45], v[156:157], v[204:205]
	v_pk_fma_f32 v[204:205], v[52:53], v[172:173], v[204:205]
	v_pk_fma_f32 v[206:207], v[38:39], v[190:191], v[62:63]
	v_pk_fma_f32 v[206:207], v[46:47], v[158:159], v[206:207]
	v_pk_fma_f32 v[206:207], v[54:55], v[174:175], v[206:207]
	v_mul_f32_e32 v216, 0x3d372713, v192
	v_mul_f32_e32 v217, 0x3d372713, v193
	v_mul_f32_e32 v218, 0x3d372713, v194
	v_mul_f32_e32 v219, 0x3d372713, v195
	v_mul_f32_e32 v220, 0x3d372713, v196
	v_mul_f32_e32 v221, 0x3d372713, v197
	v_mul_f32_e32 v222, 0x3d372713, v198
	v_mul_f32_e32 v223, 0x3d372713, v199
	v_mul_f32_e32 v216, v192, v216
	v_mul_f32_e32 v217, v193, v217
	v_mul_f32_e32 v218, v194, v218
	v_mul_f32_e32 v219, v195, v219
	v_mul_f32_e32 v220, v196, v220
	v_mul_f32_e32 v221, v197, v221
	v_mul_f32_e32 v222, v198, v222
	v_mul_f32_e32 v223, v199, v223
	v_fma_f32 v216, v192, v216, v192
	v_fma_f32 v217, v193, v217, v193
	v_fma_f32 v218, v194, v218, v194
	v_fma_f32 v219, v195, v219, v195
	v_fma_f32 v220, v196, v220, v196
	v_fma_f32 v221, v197, v221, v197
	v_fma_f32 v222, v198, v222, v198
	v_fma_f32 v223, v199, v223, v199
	v_mul_f32_e32 v216, 0x3f4c422a, v216
	v_mul_f32_e32 v217, 0x3f4c422a, v217
	v_mul_f32_e32 v218, 0x3f4c422a, v218
	v_mul_f32_e32 v219, 0x3f4c422a, v219
	v_mul_f32_e32 v220, 0x3f4c422a, v220
	v_mul_f32_e32 v221, 0x3f4c422a, v221
	v_mul_f32_e32 v222, 0x3f4c422a, v222
	v_mul_f32_e32 v223, 0x3f4c422a, v223
	v_mul_f32_e32 v216, -2.0, v216
	v_mul_f32_e32 v217, -2.0, v217
	v_mul_f32_e32 v218, -2.0, v218
	v_mul_f32_e32 v219, -2.0, v219
	v_mul_f32_e32 v220, -2.0, v220
	v_mul_f32_e32 v221, -2.0, v221
	v_mul_f32_e32 v222, -2.0, v222
	v_mul_f32_e32 v223, -2.0, v223
	v_mul_f32_e32 v216, 0x3fb8aa3b, v216
	v_mul_f32_e32 v217, 0x3fb8aa3b, v217
	v_mul_f32_e32 v218, 0x3fb8aa3b, v218
	v_mul_f32_e32 v219, 0x3fb8aa3b, v219
	v_mul_f32_e32 v220, 0x3fb8aa3b, v220
	v_mul_f32_e32 v221, 0x3fb8aa3b, v221
	v_mul_f32_e32 v222, 0x3fb8aa3b, v222
	v_mul_f32_e32 v223, 0x3fb8aa3b, v223
	v_exp_f32_e32 v216, v216
	v_exp_f32_e32 v217, v217
	v_exp_f32_e32 v218, v218
	v_exp_f32_e32 v219, v219
	v_exp_f32_e32 v220, v220
	v_exp_f32_e32 v221, v221
	v_exp_f32_e32 v222, v222
	v_exp_f32_e32 v223, v223
	v_add_f32_e32 v216, 1.0, v216
	v_add_f32_e32 v217, 1.0, v217
	v_add_f32_e32 v218, 1.0, v218
	v_add_f32_e32 v219, 1.0, v219
	v_add_f32_e32 v220, 1.0, v220
	v_add_f32_e32 v221, 1.0, v221
	v_add_f32_e32 v222, 1.0, v222
	v_add_f32_e32 v223, 1.0, v223
	v_rcp_f32_e32 v216, v216
	v_rcp_f32_e32 v217, v217
	v_rcp_f32_e32 v218, v218
	v_rcp_f32_e32 v219, v219
	v_rcp_f32_e32 v220, v220
	v_rcp_f32_e32 v221, v221
	v_rcp_f32_e32 v222, v222
	v_rcp_f32_e32 v223, v223
	s_nop 0
	v_pk_mul_f32 v[192:193], v[192:193], v[216:217]
	v_pk_mul_f32 v[194:195], v[194:195], v[218:219]
	v_pk_mul_f32 v[196:197], v[196:197], v[220:221]
	v_pk_mul_f32 v[198:199], v[198:199], v[222:223]
	v_pk_mul_f32 v[192:193], v[200:201], v[192:193]
	v_pk_mul_f32 v[194:195], v[202:203], v[194:195]
	v_pk_mul_f32 v[196:197], v[204:205], v[196:197]
	v_pk_mul_f32 v[198:199], v[206:207], v[198:199]
	v_cvt_pk_bf16_f32 v224, v192, v193
	v_cvt_pk_bf16_f32 v225, v194, v195
	v_cvt_pk_bf16_f32 v226, v196, v197
	v_cvt_pk_bf16_f32 v227, v198, v199
	global_store_dwordx4 v232, v[224:227], s[14:15]
	v_add_u32_e32 v232, s38, v232
	s_waitcnt vmcnt(8)
; __device__ void phase7(const Params& p) {
;     ...
;     for (int rr = 0; rr < RB; ++rr) {
;       float cgv[8], cvv[8];
;       i32x4 a = *(const i32x4*)(U + (size_t)(t0 + rr) * (2 * DFF) + j8 * 8);
;       i32x4 bq = *(const i32x4*)(U + (size_t)(t0 + rr) * (2 * DFF) + DFF + j8 * 8);
; #pragma unroll
;       for (int e = 0; e < 4; ++e) {
;         cgv[2 * e] = __uint_as_float(((unsigned)a[e]) << 16);
;         cgv[2 * e + 1] = __uint_as_float(((unsigned)a[e]) & 0xffff0000u);
;         cvv[2 * e] = __uint_as_float(((unsigned)bq[e]) << 16);
;         cvv[2 * e + 1] = __uint_as_float(((unsigned)bq[e]) & 0xffff0000u);
;       }
;       unsigned pk[4];
;       float res[8];
; #pragma unroll
;       for (int e = 0; e < 8; ++e) {
;         float gg = bg[e] + wg[0][e] * pg[0][e] + wg[1][e] * pg[1][e] + wg[2][e] * cgv[e];
;         float vv = bv[e] + wv[0][e] * pvv[0][e] + wv[1][e] * pvv[1][e] + wv[2][e] * cvv[e];
;         res[e] = gelu_tanh(gg) * vv;
;         pg[0][e] = pg[1][e]; pg[1][e] = cgv[e];
;         pvv[0][e] = pvv[1][e]; pvv[1][e] = cvv[e];
;       }
; #pragma unroll
;       for (int e = 0; e < 4; ++e) pk[e] = pack2(res[2 * e], res[2 * e + 1]);
;       *(i32x4*)(act + (size_t)(t0 + rr) * DFF + j8 * 8) = i32x4{(int)pk[0], (int)pk[1], (int)pk[2], (int)pk[3]};
	v_lshlrev_b32_e32 v176, 16, v128
	v_and_b32_e32 v177, 0xffff0000, v128
	v_lshlrev_b32_e32 v178, 16, v129
	v_and_b32_e32 v179, 0xffff0000, v129
	v_lshlrev_b32_e32 v180, 16, v130
	v_and_b32_e32 v181, 0xffff0000, v130
	v_lshlrev_b32_e32 v182, 16, v131
	v_and_b32_e32 v183, 0xffff0000, v131
	v_lshlrev_b32_e32 v184, 16, v132
	v_and_b32_e32 v185, 0xffff0000, v132
	v_lshlrev_b32_e32 v186, 16, v133
	v_and_b32_e32 v187, 0xffff0000, v133
	v_lshlrev_b32_e32 v188, 16, v134
	v_and_b32_e32 v189, 0xffff0000, v134
	v_lshlrev_b32_e32 v190, 16, v135
	v_and_b32_e32 v191, 0xffff0000, v135
	v_pk_fma_f32 v[192:193], v[0:1], v[144:145], v[24:25]
	v_pk_fma_f32 v[192:193], v[8:9], v[160:161], v[192:193]
	v_pk_fma_f32 v[192:193], v[16:17], v[176:177], v[192:193]
	v_pk_fma_f32 v[194:195], v[2:3], v[146:147], v[26:27]
	v_pk_fma_f32 v[194:195], v[10:11], v[162:163], v[194:195]
	v_pk_fma_f32 v[194:195], v[18:19], v[178:179], v[194:195]
	v_pk_fma_f32 v[196:197], v[4:5], v[148:149], v[28:29]
	v_pk_fma_f32 v[196:197], v[12:13], v[164:165], v[196:197]
	v_pk_fma_f32 v[196:197], v[20:21], v[180:181], v[196:197]
	v_pk_fma_f32 v[198:199], v[6:7], v[150:151], v[30:31]
	v_pk_fma_f32 v[198:199], v[14:15], v[166:167], v[198:199]
	v_pk_fma_f32 v[198:199], v[22:23], v[182:183], v[198:199]
	v_pk_fma_f32 v[200:201], v[32:33], v[152:153], v[56:57]
	v_pk_fma_f32 v[200:201], v[40:41], v[168:169], v[200:201]
	v_pk_fma_f32 v[200:201], v[48:49], v[184:185], v[200:201]
	v_pk_fma_f32 v[202:203], v[34:35], v[154:155], v[58:59]
	v_pk_fma_f32 v[202:203], v[42:43], v[170:171], v[202:203]
	v_pk_fma_f32 v[202:203], v[50:51], v[186:187], v[202:203]
	v_pk_fma_f32 v[204:205], v[36:37], v[156:157], v[60:61]
	v_pk_fma_f32 v[204:205], v[44:45], v[172:173], v[204:205]
	v_pk_fma_f32 v[204:205], v[52:53], v[188:189], v[204:205]
	v_pk_fma_f32 v[206:207], v[38:39], v[158:159], v[62:63]
	v_pk_fma_f32 v[206:207], v[46:47], v[174:175], v[206:207]
	v_pk_fma_f32 v[206:207], v[54:55], v[190:191], v[206:207]
	v_mul_f32_e32 v216, 0x3d372713, v192
	v_mul_f32_e32 v217, 0x3d372713, v193
	v_mul_f32_e32 v218, 0x3d372713, v194
	v_mul_f32_e32 v219, 0x3d372713, v195
	v_mul_f32_e32 v220, 0x3d372713, v196
	v_mul_f32_e32 v221, 0x3d372713, v197
	v_mul_f32_e32 v222, 0x3d372713, v198
	v_mul_f32_e32 v223, 0x3d372713, v199
	v_mul_f32_e32 v216, v192, v216
	v_mul_f32_e32 v217, v193, v217
	v_mul_f32_e32 v218, v194, v218
	v_mul_f32_e32 v219, v195, v219
	v_mul_f32_e32 v220, v196, v220
	v_mul_f32_e32 v221, v197, v221
	v_mul_f32_e32 v222, v198, v222
	v_mul_f32_e32 v223, v199, v223
	v_fma_f32 v216, v192, v216, v192
	v_fma_f32 v217, v193, v217, v193
	v_fma_f32 v218, v194, v218, v194
	v_fma_f32 v219, v195, v219, v195
	v_fma_f32 v220, v196, v220, v196
	v_fma_f32 v221, v197, v221, v197
	v_fma_f32 v222, v198, v222, v198
	v_fma_f32 v223, v199, v223, v199
	v_mul_f32_e32 v216, 0x3f4c422a, v216
	v_mul_f32_e32 v217, 0x3f4c422a, v217
	v_mul_f32_e32 v218, 0x3f4c422a, v218
	v_mul_f32_e32 v219, 0x3f4c422a, v219
	v_mul_f32_e32 v220, 0x3f4c422a, v220
	v_mul_f32_e32 v221, 0x3f4c422a, v221
	v_mul_f32_e32 v222, 0x3f4c422a, v222
	v_mul_f32_e32 v223, 0x3f4c422a, v223
	v_mul_f32_e32 v216, -2.0, v216
	v_mul_f32_e32 v217, -2.0, v217
	v_mul_f32_e32 v218, -2.0, v218
	v_mul_f32_e32 v219, -2.0, v219
	v_mul_f32_e32 v220, -2.0, v220
	v_mul_f32_e32 v221, -2.0, v221
	v_mul_f32_e32 v222, -2.0, v222
	v_mul_f32_e32 v223, -2.0, v223
	v_mul_f32_e32 v216, 0x3fb8aa3b, v216
	v_mul_f32_e32 v217, 0x3fb8aa3b, v217
	v_mul_f32_e32 v218, 0x3fb8aa3b, v218
	v_mul_f32_e32 v219, 0x3fb8aa3b, v219
	v_mul_f32_e32 v220, 0x3fb8aa3b, v220
	v_mul_f32_e32 v221, 0x3fb8aa3b, v221
	v_mul_f32_e32 v222, 0x3fb8aa3b, v222
	v_mul_f32_e32 v223, 0x3fb8aa3b, v223
	v_exp_f32_e32 v216, v216
	v_exp_f32_e32 v217, v217
	v_exp_f32_e32 v218, v218
	v_exp_f32_e32 v219, v219
	v_exp_f32_e32 v220, v220
	v_exp_f32_e32 v221, v221
	v_exp_f32_e32 v222, v222
	v_exp_f32_e32 v223, v223
	v_add_f32_e32 v216, 1.0, v216
	v_add_f32_e32 v217, 1.0, v217
	v_add_f32_e32 v218, 1.0, v218
	v_add_f32_e32 v219, 1.0, v219
	v_add_f32_e32 v220, 1.0, v220
	v_add_f32_e32 v221, 1.0, v221
	v_add_f32_e32 v222, 1.0, v222
	v_add_f32_e32 v223, 1.0, v223
	v_rcp_f32_e32 v216, v216
	v_rcp_f32_e32 v217, v217
	v_rcp_f32_e32 v218, v218
	v_rcp_f32_e32 v219, v219
	v_rcp_f32_e32 v220, v220
	v_rcp_f32_e32 v221, v221
	v_rcp_f32_e32 v222, v222
	v_rcp_f32_e32 v223, v223
	s_nop 0
	v_pk_mul_f32 v[192:193], v[192:193], v[216:217]
	v_pk_mul_f32 v[194:195], v[194:195], v[218:219]
	v_pk_mul_f32 v[196:197], v[196:197], v[220:221]
	v_pk_mul_f32 v[198:199], v[198:199], v[222:223]
	v_pk_mul_f32 v[192:193], v[200:201], v[192:193]
	v_pk_mul_f32 v[194:195], v[202:203], v[194:195]
	v_pk_mul_f32 v[196:197], v[204:205], v[196:197]
	v_pk_mul_f32 v[198:199], v[206:207], v[198:199]
	v_cvt_pk_bf16_f32 v224, v192, v193
	v_cvt_pk_bf16_f32 v225, v194, v195
	v_cvt_pk_bf16_f32 v226, v196, v197
	v_cvt_pk_bf16_f32 v227, v198, v199
	global_store_dwordx4 v232, v[224:227], s[14:15]
	v_add_u32_e32 v232, s38, v232
	s_waitcnt vmcnt(7)
; __device__ void phase7(const Params& p) {
;     ...
;   for (int it = blockIdx.x * NT + tid; it < total; it += gridDim.x * NT) {
;     ...
;     for (int rr = 0; rr < RB; ++rr) {
;       float cgv[8], cvv[8];
;       i32x4 a = *(const i32x4*)(U + (size_t)(t0 + rr) * (2 * DFF) + j8 * 8);
;       i32x4 bq = *(const i32x4*)(U + (size_t)(t0 + rr) * (2 * DFF) + DFF + j8 * 8);
; #pragma unroll
;       for (int e = 0; e < 4; ++e) {
;         cgv[2 * e] = __uint_as_float(((unsigned)a[e]) << 16);
;         cgv[2 * e + 1] = __uint_as_float(((unsigned)a[e]) & 0xffff0000u);
;         cvv[2 * e] = __uint_as_float(((unsigned)bq[e]) << 16);
;         cvv[2 * e + 1] = __uint_as_float(((unsigned)bq[e]) & 0xffff0000u);
;       }
;       unsigned pk[4];
;       float res[8];
; #pragma unroll
;       for (int e = 0; e < 8; ++e) {
;         float gg = bg[e] + wg[0][e] * pg[0][e] + wg[1][e] * pg[1][e] + wg[2][e] * cgv[e];
;         float vv = bv[e] + wv[0][e] * pvv[0][e] + wv[1][e] * pvv[1][e] + wv[2][e] * cvv[e];
;         res[e] = gelu_tanh(gg) * vv;
;         pg[0][e] = pg[1][e]; pg[1][e] = cgv[e];
;         pvv[0][e] = pvv[1][e]; pvv[1][e] = cvv[e];
;       }
; #pragma unroll
;       for (int e = 0; e < 4; ++e) pk[e] = pack2(res[2 * e], res[2 * e + 1]);
;       *(i32x4*)(act + (size_t)(t0 + rr) * DFF + j8 * 8) = i32x4{(int)pk[0], (int)pk[1], (int)pk[2], (int)pk[3]};
	v_lshlrev_b32_e32 v144, 16, v136
	v_and_b32_e32 v145, 0xffff0000, v136
	v_lshlrev_b32_e32 v146, 16, v137
	v_and_b32_e32 v147, 0xffff0000, v137
	v_lshlrev_b32_e32 v148, 16, v138
	v_and_b32_e32 v149, 0xffff0000, v138
	v_lshlrev_b32_e32 v150, 16, v139
	v_and_b32_e32 v151, 0xffff0000, v139
	v_lshlrev_b32_e32 v152, 16, v140
	v_and_b32_e32 v153, 0xffff0000, v140
	v_lshlrev_b32_e32 v154, 16, v141
	v_and_b32_e32 v155, 0xffff0000, v141
	v_lshlrev_b32_e32 v156, 16, v142
	v_and_b32_e32 v157, 0xffff0000, v142
	v_lshlrev_b32_e32 v158, 16, v143
	v_and_b32_e32 v159, 0xffff0000, v143
	v_pk_fma_f32 v[192:193], v[0:1], v[160:161], v[24:25]
	v_pk_fma_f32 v[192:193], v[8:9], v[176:177], v[192:193]
	v_pk_fma_f32 v[192:193], v[16:17], v[144:145], v[192:193]
	v_pk_fma_f32 v[194:195], v[2:3], v[162:163], v[26:27]
	v_pk_fma_f32 v[194:195], v[10:11], v[178:179], v[194:195]
	v_pk_fma_f32 v[194:195], v[18:19], v[146:147], v[194:195]
	v_pk_fma_f32 v[196:197], v[4:5], v[164:165], v[28:29]
	v_pk_fma_f32 v[196:197], v[12:13], v[180:181], v[196:197]
	v_pk_fma_f32 v[196:197], v[20:21], v[148:149], v[196:197]
	v_pk_fma_f32 v[198:199], v[6:7], v[166:167], v[30:31]
	v_pk_fma_f32 v[198:199], v[14:15], v[182:183], v[198:199]
	v_pk_fma_f32 v[198:199], v[22:23], v[150:151], v[198:199]
	v_pk_fma_f32 v[200:201], v[32:33], v[168:169], v[56:57]
	v_pk_fma_f32 v[200:201], v[40:41], v[184:185], v[200:201]
	v_pk_fma_f32 v[200:201], v[48:49], v[152:153], v[200:201]
	v_pk_fma_f32 v[202:203], v[34:35], v[170:171], v[58:59]
	v_pk_fma_f32 v[202:203], v[42:43], v[186:187], v[202:203]
	v_pk_fma_f32 v[202:203], v[50:51], v[154:155], v[202:203]
	v_pk_fma_f32 v[204:205], v[36:37], v[172:173], v[60:61]
	v_pk_fma_f32 v[204:205], v[44:45], v[188:189], v[204:205]
	v_pk_fma_f32 v[204:205], v[52:53], v[156:157], v[204:205]
	v_pk_fma_f32 v[206:207], v[38:39], v[174:175], v[62:63]
	v_pk_fma_f32 v[206:207], v[46:47], v[190:191], v[206:207]
	v_pk_fma_f32 v[206:207], v[54:55], v[158:159], v[206:207]
	v_mul_f32_e32 v216, 0x3d372713, v192
	v_mul_f32_e32 v217, 0x3d372713, v193
	v_mul_f32_e32 v218, 0x3d372713, v194
	v_mul_f32_e32 v219, 0x3d372713, v195
	v_mul_f32_e32 v220, 0x3d372713, v196
	v_mul_f32_e32 v221, 0x3d372713, v197
	v_mul_f32_e32 v222, 0x3d372713, v198
	v_mul_f32_e32 v223, 0x3d372713, v199
	v_mul_f32_e32 v216, v192, v216
	v_mul_f32_e32 v217, v193, v217
	v_mul_f32_e32 v218, v194, v218
	v_mul_f32_e32 v219, v195, v219
	v_mul_f32_e32 v220, v196, v220
	v_mul_f32_e32 v221, v197, v221
	v_mul_f32_e32 v222, v198, v222
	v_mul_f32_e32 v223, v199, v223
	v_fma_f32 v216, v192, v216, v192
	v_fma_f32 v217, v193, v217, v193
	v_fma_f32 v218, v194, v218, v194
	v_fma_f32 v219, v195, v219, v195
	v_fma_f32 v220, v196, v220, v196
	v_fma_f32 v221, v197, v221, v197
	v_fma_f32 v222, v198, v222, v198
	v_fma_f32 v223, v199, v223, v199
	v_mul_f32_e32 v216, 0x3f4c422a, v216
	v_mul_f32_e32 v217, 0x3f4c422a, v217
	v_mul_f32_e32 v218, 0x3f4c422a, v218
	v_mul_f32_e32 v219, 0x3f4c422a, v219
	v_mul_f32_e32 v220, 0x3f4c422a, v220
	v_mul_f32_e32 v221, 0x3f4c422a, v221
	v_mul_f32_e32 v222, 0x3f4c422a, v222
	v_mul_f32_e32 v223, 0x3f4c422a, v223
	v_mul_f32_e32 v216, -2.0, v216
	v_mul_f32_e32 v217, -2.0, v217
	v_mul_f32_e32 v218, -2.0, v218
	v_mul_f32_e32 v219, -2.0, v219
	v_mul_f32_e32 v220, -2.0, v220
	v_mul_f32_e32 v221, -2.0, v221
	v_mul_f32_e32 v222, -2.0, v222
	v_mul_f32_e32 v223, -2.0, v223
	v_mul_f32_e32 v216, 0x3fb8aa3b, v216
	v_mul_f32_e32 v217, 0x3fb8aa3b, v217
	v_mul_f32_e32 v218, 0x3fb8aa3b, v218
	v_mul_f32_e32 v219, 0x3fb8aa3b, v219
	v_mul_f32_e32 v220, 0x3fb8aa3b, v220
	v_mul_f32_e32 v221, 0x3fb8aa3b, v221
	v_mul_f32_e32 v222, 0x3fb8aa3b, v222
	v_mul_f32_e32 v223, 0x3fb8aa3b, v223
	v_exp_f32_e32 v216, v216
	v_exp_f32_e32 v217, v217
	v_exp_f32_e32 v218, v218
	v_exp_f32_e32 v219, v219
	v_exp_f32_e32 v220, v220
	v_exp_f32_e32 v221, v221
	v_exp_f32_e32 v222, v222
	v_exp_f32_e32 v223, v223
	v_add_f32_e32 v216, 1.0, v216
	v_add_f32_e32 v217, 1.0, v217
	v_add_f32_e32 v218, 1.0, v218
	v_add_f32_e32 v219, 1.0, v219
	v_add_f32_e32 v220, 1.0, v220
	v_add_f32_e32 v221, 1.0, v221
	v_add_f32_e32 v222, 1.0, v222
	v_add_f32_e32 v223, 1.0, v223
	v_rcp_f32_e32 v216, v216
	v_rcp_f32_e32 v217, v217
	v_rcp_f32_e32 v218, v218
	v_rcp_f32_e32 v219, v219
	v_rcp_f32_e32 v220, v220
	v_rcp_f32_e32 v221, v221
	v_rcp_f32_e32 v222, v222
	v_rcp_f32_e32 v223, v223
	s_nop 0
	v_pk_mul_f32 v[192:193], v[192:193], v[216:217]
	v_pk_mul_f32 v[194:195], v[194:195], v[218:219]
	v_pk_mul_f32 v[196:197], v[196:197], v[220:221]
	v_pk_mul_f32 v[198:199], v[198:199], v[222:223]
	v_pk_mul_f32 v[192:193], v[200:201], v[192:193]
	v_pk_mul_f32 v[194:195], v[202:203], v[194:195]
	v_pk_mul_f32 v[196:197], v[204:205], v[196:197]
	v_pk_mul_f32 v[198:199], v[206:207], v[198:199]
	v_cvt_pk_bf16_f32 v224, v192, v193
	v_cvt_pk_bf16_f32 v225, v194, v195
	v_cvt_pk_bf16_f32 v226, v196, v197
	v_cvt_pk_bf16_f32 v227, v198, v199
	global_store_dwordx4 v232, v[224:227], s[14:15]
	v_add_u32_e32 v235, s3, v235
	v_cmp_gt_i32_e32 vcc, s5, v235
	s_and_b64 exec, exec, vcc
	s_cbranch_execnz .Lp7_loop
